# P7 epilogue prefetch plus all s_setprio removed from the GEMM K-loops (both wave halves at equal priority)
# speedup vs baseline: 1.0112x; 1.0018x over previous
; #define PG8_STAGE(bufoff, gbase, voff) do { _Pragma("unroll") for (int _i = 0; _i < 2; ++_i) \
;         __builtin_amdgcn_global_load_lds((const unsigned*)((const char*)(gbase) + (voff)[_i]), (LAS unsigned*)(lds + (bufoff) + ldsw + _i * 8192), 16, 0, 0); } while (0)
; #define PG8_LDA(dst, b, h) do { _Pragma("unroll") for (int m = 0; m < 4; ++m) _Pragma("unroll") for (int k = 0; k < 2; ++k) dst[m][k] = *(const LAS bf16x8*)(lds + PG8_SA(b, h) + aoff + m * 2048 + k * 1024); } while (0)
; #define PG8_LDB(dst, b, h) do { _Pragma("unroll") for (int n = 0; n < 2; ++n) _Pragma("unroll") for (int k = 0; k < 2; ++k) dst[n][k] = *(const LAS bf16x8*)(lds + PG8_SB(b, h) + boff + n * 2048 + k * 1024); } while (0)
; #define PG8_MMA(ai, bj, At, Bt) do { __builtin_amdgcn_s_setprio(1); _Pragma("unroll") for (int m = 0; m < 4; ++m) _Pragma("unroll") for (int n = 0; n < 2; ++n) _Pragma("unroll") for (int k = 0; k < 2; ++k) \
;         acc[ai][bj][m][n] = __builtin_amdgcn_mfma_f32_16x16x32_bf16(Bt[n][k], At[m][k], acc[ai][bj][m][n], 0, 0, 0); __builtin_amdgcn_s_setprio(0); } while (0)
; #define PG8_WAIT_V(n) asm volatile("s_waitcnt vmcnt(" #n ")" ::: "memory")
; #define PG8_WAIT_L(n) asm volatile("s_waitcnt lgkmcnt(" #n ")" ::: "memory")
; #define PG8_BAR __builtin_amdgcn_s_barrier()
; #define PG8_SCHED __builtin_amdgcn_sched_barrier(0)
; template <class Epi, bool ALIGN_EPI>
; __device__ __forceinline__ void gemm_phase(LAS unsigned char* lds, const Gemm g, const StaticOrder& S, const Epi& E) {
;     ...
;             const bool last = (t == nt - 2);
;             const char* a1 = cA + (size_t)(t + 1) * kstep;
;             const char* a2 = last ? nA : cA + (size_t)(t + 2) * kstep; const char* b2 = last ? nB : cB + (size_t)(t + 2) * kstep;
;             const char* a3 = a2 + kstep; const char* b3 = b2 + kstep;
;             PG8_LDB(B0, 0, 0); PG8_LDB(B1, 0, 1); PG8_SCHED; PG8_LDA(At, 0, 0); PG8_STAGE(PG8_SA(1, 1), a1 + hstepA, voffA);
;             PG8_WAIT_V(8); PG8_WAIT_L(0); PG8_BAR; PG8_MMA(0, 0, At, B0); PG8_MMA(0, 1, At, B1); PG8_BAR; PG8_SCHED;
;             PG8_LDA(At, 0, 1); PG8_STAGE(PG8_SB(0, 0), b2, voffB); PG8_STAGE(PG8_SB(0, 1), b2 + hstepB, voffB); PG8_STAGE(PG8_SA(0, 0), a2, voffA);
;             PG8_WAIT_V(8); PG8_WAIT_L(0); PG8_BAR; PG8_MMA(1, 0, At, B0); PG8_MMA(1, 1, At, B1); PG8_BAR; PG8_SCHED;
.LBB0_102:
	s_add_u32 s6, s2, 0xfffc0080
	s_addc_u32 s7, s3, -1
	s_add_i32 s49, 0, 0x10000
	s_cmp_eq_u32 s37, 12
	s_cselect_b32 s9, s4, s7
	s_cselect_b32 s8, s10, s6
	v_add_u32_e32 v152, s49, v148
	s_cselect_b32 s7, s11, s36
	s_cselect_b32 s6, s13, s27
	s_add_i32 s52, 0, 0x14000
	ds_read_b128 v[140:143], v152
	ds_read_b128 v[144:147], v152 offset:1024
	ds_read_b128 v[156:159], v152 offset:2048
	ds_read_b128 v[160:163], v152 offset:3072
	v_add_u32_e32 v152, s52, v148
	ds_read_b128 v[170:173], v152
	ds_read_b128 v[180:183], v152 offset:1024
	ds_read_b128 v[184:187], v152 offset:2048
	ds_read_b128 v[188:191], v152 offset:3072
	v_lshl_add_u64 v[152:153], s[2:3], 0, v[136:137]
	s_add_i32 m0, s41, 0xc000
	ds_read_b128 v[192:195], v150
	ds_read_b128 v[196:199], v150 offset:1024
	ds_read_b128 v[200:203], v150 offset:2048
	ds_read_b128 v[204:207], v150 offset:3072
	ds_read_b128 v[208:211], v150 offset:4096
	ds_read_b128 v[212:215], v150 offset:5120
	ds_read_b128 v[216:219], v150 offset:6144
	ds_read_b128 v[220:223], v150 offset:7168
	global_load_lds_dwordx4 v[152:153], off
	v_lshl_add_u64 v[152:153], s[2:3], 0, v[138:139]
	s_add_i32 m0, s41, 0xe000
	s_nop 0
	global_load_lds_dwordx4 v[152:153], off
	s_waitcnt vmcnt(8)
	s_waitcnt lgkmcnt(0)
	s_barrier
	s_waitcnt lgkmcnt(0)
	v_mfma_f32_16x16x32_bf16 v[122:125], v[140:143], v[192:195], v[122:125]
	v_mfma_f32_16x16x32_bf16 v[126:129], v[156:159], v[192:195], v[126:129]
	v_mfma_f32_16x16x32_bf16 v[110:113], v[140:143], v[200:203], v[110:113]
	v_mfma_f32_16x16x32_bf16 v[106:109], v[156:159], v[200:203], v[106:109]
	v_mfma_f32_16x16x32_bf16 v[94:97], v[140:143], v[208:211], v[94:97]
	v_mfma_f32_16x16x32_bf16 v[90:93], v[156:159], v[208:211], v[90:93]
	v_mfma_f32_16x16x32_bf16 v[78:81], v[140:143], v[216:219], v[78:81]
	v_mfma_f32_16x16x32_bf16 v[74:77], v[156:159], v[216:219], v[74:77]
	v_mfma_f32_16x16x32_bf16 v[122:125], v[144:147], v[196:199], v[122:125]
	v_mfma_f32_16x16x32_bf16 v[126:129], v[160:163], v[196:199], v[126:129]
	v_mfma_f32_16x16x32_bf16 v[110:113], v[144:147], v[204:207], v[110:113]
	v_mfma_f32_16x16x32_bf16 v[106:109], v[160:163], v[204:207], v[106:109]
	v_mfma_f32_16x16x32_bf16 v[94:97], v[144:147], v[212:215], v[94:97]
	v_mfma_f32_16x16x32_bf16 v[90:93], v[160:163], v[212:215], v[90:93]
	v_mfma_f32_16x16x32_bf16 v[78:81], v[144:147], v[220:223], v[78:81]
	v_mfma_f32_16x16x32_bf16 v[74:77], v[160:163], v[220:223], v[74:77]
	v_mfma_f32_16x16x32_bf16 v[118:121], v[170:173], v[192:195], v[118:121]
	v_mfma_f32_16x16x32_bf16 v[114:117], v[184:187], v[192:195], v[114:117]
	v_mfma_f32_16x16x32_bf16 v[102:105], v[170:173], v[200:203], v[102:105]
	v_mfma_f32_16x16x32_bf16 v[98:101], v[184:187], v[200:203], v[98:101]
	v_mfma_f32_16x16x32_bf16 v[86:89], v[170:173], v[208:211], v[86:89]
	v_mfma_f32_16x16x32_bf16 v[82:85], v[184:187], v[208:211], v[82:85]
	v_mfma_f32_16x16x32_bf16 v[70:73], v[170:173], v[216:219], v[70:73]
	v_mfma_f32_16x16x32_bf16 v[66:69], v[184:187], v[216:219], v[66:69]
	v_mfma_f32_16x16x32_bf16 v[118:121], v[180:183], v[196:199], v[118:121]
	v_mfma_f32_16x16x32_bf16 v[114:117], v[188:191], v[196:199], v[114:117]
	v_mfma_f32_16x16x32_bf16 v[102:105], v[180:183], v[204:207], v[102:105]
	v_mfma_f32_16x16x32_bf16 v[98:101], v[188:191], v[204:207], v[98:101]
	v_mfma_f32_16x16x32_bf16 v[86:89], v[180:183], v[212:215], v[86:89]
	v_mfma_f32_16x16x32_bf16 v[82:85], v[188:191], v[212:215], v[82:85]
	v_mfma_f32_16x16x32_bf16 v[70:73], v[180:183], v[220:223], v[70:73]
	v_mfma_f32_16x16x32_bf16 v[66:69], v[188:191], v[220:223], v[66:69]
	s_barrier
	s_add_i32 s49, s49, s40
	v_lshl_add_u64 v[152:153], s[6:7], 0, v[0:1]
	s_mov_b32 m0, s49
	ds_read_b128 v[192:195], v150 offset:16384
	ds_read_b128 v[196:199], v150 offset:17408
	ds_read_b128 v[200:203], v150 offset:18432
	ds_read_b128 v[204:207], v150 offset:19456
	ds_read_b128 v[208:211], v150 offset:20480
	ds_read_b128 v[212:215], v150 offset:21504
	ds_read_b128 v[216:219], v150 offset:22528
	ds_read_b128 v[220:223], v150 offset:23552
	global_load_lds_dwordx4 v[152:153], off
	s_add_i32 m0, s49, 0x2000
	s_add_u32 s50, s6, 0x40000
	v_lshl_add_u64 v[164:165], s[6:7], 0, v[134:135]
	s_addc_u32 s51, s7, 0
	s_add_i32 s49, s52, s40
	global_load_lds_dwordx4 v[164:165], off
	v_lshl_add_u64 v[168:169], s[50:51], 0, v[0:1]
	s_mov_b32 m0, s49
	v_lshl_add_u64 v[174:175], s[8:9], 0, v[132:133]
	global_load_lds_dwordx4 v[168:169], off
	v_lshl_add_u64 v[168:169], s[50:51], 0, v[134:135]
	s_add_i32 m0, s49, 0x2000
	s_nop 0
	global_load_lds_dwordx4 v[168:169], off
	v_lshl_add_u64 v[168:169], s[8:9], 0, v[130:131]
	s_mov_b32 m0, s41
	s_nop 0
	global_load_lds_dwordx4 v[168:169], off
	s_mov_b32 m0, s42
	s_nop 0
	global_load_lds_dwordx4 v[174:175], off
	s_waitcnt vmcnt(8)
	s_waitcnt lgkmcnt(0)
	s_barrier
; #define PG8_STAGE(bufoff, gbase, voff) do { _Pragma("unroll") for (int _i = 0; _i < 2; ++_i) \
;         __builtin_amdgcn_global_load_lds((const unsigned*)((const char*)(gbase) + (voff)[_i]), (LAS unsigned*)(lds + (bufoff) + ldsw + _i * 8192), 16, 0, 0); } while (0)
; #define PG8_LDA(dst, b, h) do { _Pragma("unroll") for (int m = 0; m < 4; ++m) _Pragma("unroll") for (int k = 0; k < 2; ++k) dst[m][k] = *(const LAS bf16x8*)(lds + PG8_SA(b, h) + aoff + m * 2048 + k * 1024); } while (0)
; #define PG8_LDB(dst, b, h) do { _Pragma("unroll") for (int n = 0; n < 2; ++n) _Pragma("unroll") for (int k = 0; k < 2; ++k) dst[n][k] = *(const LAS bf16x8*)(lds + PG8_SB(b, h) + boff + n * 2048 + k * 1024); } while (0)
; #define PG8_MMA(ai, bj, At, Bt) do { __builtin_amdgcn_s_setprio(1); _Pragma("unroll") for (int m = 0; m < 4; ++m) _Pragma("unroll") for (int n = 0; n < 2; ++n) _Pragma("unroll") for (int k = 0; k < 2; ++k) \
;         acc[ai][bj][m][n] = __builtin_amdgcn_mfma_f32_16x16x32_bf16(Bt[n][k], At[m][k], acc[ai][bj][m][n], 0, 0, 0); __builtin_amdgcn_s_setprio(0); } while (0)
; #define PG8_WAIT_V(n) asm volatile("s_waitcnt vmcnt(" #n ")" ::: "memory")
; #define PG8_WAIT_L(n) asm volatile("s_waitcnt lgkmcnt(" #n ")" ::: "memory")
; #define PG8_BAR __builtin_amdgcn_s_barrier()
; #define PG8_SCHED __builtin_amdgcn_sched_barrier(0)
; template <class Epi, bool ALIGN_EPI>
; __device__ __forceinline__ void gemm_phase(LAS unsigned char* lds, const Gemm g, const StaticOrder& S, const Epi& E) {
;     ...
;             PG8_WAIT_V(8); PG8_WAIT_L(0); PG8_BAR; PG8_MMA(1, 0, At, B0); PG8_MMA(1, 1, At, B1); PG8_BAR; PG8_SCHED;
;             PG8_LDB(B0, 1, 0); PG8_LDB(B1, 1, 1); PG8_SCHED; PG8_LDA(At, 1, 0); PG8_STAGE(PG8_SA(0, 1), a2 + hstepA, voffA);
;             PG8_WAIT_V(8); PG8_WAIT_L(0); PG8_BAR; PG8_MMA(0, 0, At, B0); PG8_MMA(0, 1, At, B1); PG8_BAR; PG8_SCHED;
	s_waitcnt lgkmcnt(0)
	v_mfma_f32_16x16x32_bf16 v[62:65], v[140:143], v[192:195], v[62:65]
	v_mfma_f32_16x16x32_bf16 v[58:61], v[156:159], v[192:195], v[58:61]
	v_mfma_f32_16x16x32_bf16 v[46:49], v[140:143], v[200:203], v[46:49]
	v_mfma_f32_16x16x32_bf16 v[42:45], v[156:159], v[200:203], v[42:45]
	v_mfma_f32_16x16x32_bf16 v[30:33], v[140:143], v[208:211], v[30:33]
	v_mfma_f32_16x16x32_bf16 v[26:29], v[156:159], v[208:211], v[26:29]
	v_mfma_f32_16x16x32_bf16 v[14:17], v[140:143], v[216:219], v[14:17]
	v_mfma_f32_16x16x32_bf16 v[10:13], v[156:159], v[216:219], v[10:13]
	v_mfma_f32_16x16x32_bf16 v[62:65], v[144:147], v[196:199], v[62:65]
	v_mfma_f32_16x16x32_bf16 v[58:61], v[160:163], v[196:199], v[58:61]
	v_mfma_f32_16x16x32_bf16 v[46:49], v[144:147], v[204:207], v[46:49]
	v_mfma_f32_16x16x32_bf16 v[42:45], v[160:163], v[204:207], v[42:45]
	v_mfma_f32_16x16x32_bf16 v[30:33], v[144:147], v[212:215], v[30:33]
	v_mfma_f32_16x16x32_bf16 v[26:29], v[160:163], v[212:215], v[26:29]
	v_mfma_f32_16x16x32_bf16 v[14:17], v[144:147], v[220:223], v[14:17]
	v_mfma_f32_16x16x32_bf16 v[10:13], v[160:163], v[220:223], v[10:13]
	v_mfma_f32_16x16x32_bf16 v[54:57], v[170:173], v[192:195], v[54:57]
	v_mfma_f32_16x16x32_bf16 v[50:53], v[184:187], v[192:195], v[50:53]
	v_mfma_f32_16x16x32_bf16 v[38:41], v[170:173], v[200:203], v[38:41]
	v_mfma_f32_16x16x32_bf16 v[34:37], v[184:187], v[200:203], v[34:37]
	v_mfma_f32_16x16x32_bf16 v[22:25], v[170:173], v[208:211], v[22:25]
	v_mfma_f32_16x16x32_bf16 v[18:21], v[184:187], v[208:211], v[18:21]
	v_mfma_f32_16x16x32_bf16 v[6:9], v[170:173], v[216:219], v[6:9]
	v_mfma_f32_16x16x32_bf16 v[2:5], v[184:187], v[216:219], v[2:5]
	v_mfma_f32_16x16x32_bf16 v[54:57], v[180:183], v[196:199], v[54:57]
	v_mfma_f32_16x16x32_bf16 v[50:53], v[188:191], v[196:199], v[50:53]
	v_mfma_f32_16x16x32_bf16 v[38:41], v[180:183], v[204:207], v[38:41]
	v_mfma_f32_16x16x32_bf16 v[34:37], v[188:191], v[204:207], v[34:37]
	v_mfma_f32_16x16x32_bf16 v[22:25], v[180:183], v[212:215], v[22:25]
	v_mfma_f32_16x16x32_bf16 v[18:21], v[188:191], v[212:215], v[18:21]
	v_mfma_f32_16x16x32_bf16 v[6:9], v[180:183], v[220:223], v[6:9]
	v_mfma_f32_16x16x32_bf16 v[2:5], v[188:191], v[220:223], v[2:5]
	s_barrier
	s_add_i32 s49, 0, 0x18000
	s_add_i32 s50, 0, 0x1c000
	v_add_u32_e32 v160, s49, v148
	v_add_u32_e32 v188, s50, v148
	ds_read_b128 v[140:143], v160
	ds_read_b128 v[144:147], v160 offset:1024
	ds_read_b128 v[156:159], v160 offset:2048
	ds_read_b128 v[160:163], v160 offset:3072
	ds_read_b128 v[170:173], v188
	ds_read_b128 v[180:183], v188 offset:1024
	ds_read_b128 v[184:187], v188 offset:2048
	ds_read_b128 v[188:191], v188 offset:3072
	s_add_u32 s8, s8, 0x40000
	s_addc_u32 s9, s9, 0
	s_mov_b32 m0, s43
	v_lshl_add_u64 v[224:225], s[8:9], 0, v[130:131]
	ds_read_b128 v[192:195], v150 offset:32768
	ds_read_b128 v[196:199], v150 offset:33792
	ds_read_b128 v[200:203], v150 offset:34816
	ds_read_b128 v[204:207], v150 offset:35840
	ds_read_b128 v[208:211], v150 offset:36864
	ds_read_b128 v[212:215], v150 offset:37888
	ds_read_b128 v[216:219], v150 offset:38912
	ds_read_b128 v[220:223], v150 offset:39936
	global_load_lds_dwordx4 v[224:225], off
	v_lshl_add_u64 v[224:225], s[8:9], 0, v[132:133]
	s_mov_b32 m0, s44
	s_nop 0
	global_load_lds_dwordx4 v[224:225], off
	s_waitcnt vmcnt(8)
	s_waitcnt lgkmcnt(0)
	s_barrier
	s_waitcnt lgkmcnt(0)
	v_mfma_f32_16x16x32_bf16 v[122:125], v[140:143], v[192:195], v[122:125]
	v_mfma_f32_16x16x32_bf16 v[126:129], v[156:159], v[192:195], v[126:129]
	v_mfma_f32_16x16x32_bf16 v[110:113], v[140:143], v[200:203], v[110:113]
	v_mfma_f32_16x16x32_bf16 v[106:109], v[156:159], v[200:203], v[106:109]
	v_mfma_f32_16x16x32_bf16 v[94:97], v[140:143], v[208:211], v[94:97]
	v_mfma_f32_16x16x32_bf16 v[90:93], v[156:159], v[208:211], v[90:93]
	v_mfma_f32_16x16x32_bf16 v[78:81], v[140:143], v[216:219], v[78:81]
	v_mfma_f32_16x16x32_bf16 v[74:77], v[156:159], v[216:219], v[74:77]
	v_mfma_f32_16x16x32_bf16 v[122:125], v[144:147], v[196:199], v[122:125]
	v_mfma_f32_16x16x32_bf16 v[126:129], v[160:163], v[196:199], v[126:129]
	v_mfma_f32_16x16x32_bf16 v[110:113], v[144:147], v[204:207], v[110:113]
	v_mfma_f32_16x16x32_bf16 v[106:109], v[160:163], v[204:207], v[106:109]
	v_mfma_f32_16x16x32_bf16 v[94:97], v[144:147], v[212:215], v[94:97]
	v_mfma_f32_16x16x32_bf16 v[90:93], v[160:163], v[212:215], v[90:93]
	v_mfma_f32_16x16x32_bf16 v[78:81], v[144:147], v[220:223], v[78:81]
	v_mfma_f32_16x16x32_bf16 v[74:77], v[160:163], v[220:223], v[74:77]
	v_mfma_f32_16x16x32_bf16 v[118:121], v[170:173], v[192:195], v[118:121]
	v_mfma_f32_16x16x32_bf16 v[114:117], v[184:187], v[192:195], v[114:117]
	v_mfma_f32_16x16x32_bf16 v[102:105], v[170:173], v[200:203], v[102:105]
	v_mfma_f32_16x16x32_bf16 v[98:101], v[184:187], v[200:203], v[98:101]
	v_mfma_f32_16x16x32_bf16 v[86:89], v[170:173], v[208:211], v[86:89]
	v_mfma_f32_16x16x32_bf16 v[82:85], v[184:187], v[208:211], v[82:85]
	v_mfma_f32_16x16x32_bf16 v[70:73], v[170:173], v[216:219], v[70:73]
	v_mfma_f32_16x16x32_bf16 v[66:69], v[184:187], v[216:219], v[66:69]
	v_mfma_f32_16x16x32_bf16 v[118:121], v[180:183], v[196:199], v[118:121]
	v_mfma_f32_16x16x32_bf16 v[114:117], v[188:191], v[196:199], v[114:117]
	v_mfma_f32_16x16x32_bf16 v[102:105], v[180:183], v[204:207], v[102:105]
	v_mfma_f32_16x16x32_bf16 v[98:101], v[188:191], v[204:207], v[98:101]
	v_mfma_f32_16x16x32_bf16 v[86:89], v[180:183], v[212:215], v[86:89]
	v_mfma_f32_16x16x32_bf16 v[82:85], v[188:191], v[212:215], v[82:85]
	v_mfma_f32_16x16x32_bf16 v[70:73], v[180:183], v[220:223], v[70:73]
	v_mfma_f32_16x16x32_bf16 v[66:69], v[188:191], v[220:223], v[66:69]
	s_barrier
; #define PG8_STAGE(bufoff, gbase, voff) do { _Pragma("unroll") for (int _i = 0; _i < 2; ++_i) \
;         __builtin_amdgcn_global_load_lds((const unsigned*)((const char*)(gbase) + (voff)[_i]), (LAS unsigned*)(lds + (bufoff) + ldsw + _i * 8192), 16, 0, 0); } while (0)
; #define PG8_LDA(dst, b, h) do { _Pragma("unroll") for (int m = 0; m < 4; ++m) _Pragma("unroll") for (int k = 0; k < 2; ++k) dst[m][k] = *(const LAS bf16x8*)(lds + PG8_SA(b, h) + aoff + m * 2048 + k * 1024); } while (0)
; #define PG8_MMA(ai, bj, At, Bt) do { __builtin_amdgcn_s_setprio(1); _Pragma("unroll") for (int m = 0; m < 4; ++m) _Pragma("unroll") for (int n = 0; n < 2; ++n) _Pragma("unroll") for (int k = 0; k < 2; ++k) \
;         acc[ai][bj][m][n] = __builtin_amdgcn_mfma_f32_16x16x32_bf16(Bt[n][k], At[m][k], acc[ai][bj][m][n], 0, 0, 0); __builtin_amdgcn_s_setprio(0); } while (0)
; #define PG8_WAIT_V(n) asm volatile("s_waitcnt vmcnt(" #n ")" ::: "memory")
; #define PG8_WAIT_L(n) asm volatile("s_waitcnt lgkmcnt(" #n ")" ::: "memory")
; #define PG8_BAR __builtin_amdgcn_s_barrier()
; #define PG8_SCHED __builtin_amdgcn_sched_barrier(0)
; template <class Epi, bool ALIGN_EPI>
; __device__ __forceinline__ void gemm_phase(LAS unsigned char* lds, const Gemm g, const StaticOrder& S, const Epi& E) {
;     ...
;             PG8_LDA(At, 1, 1); PG8_STAGE(PG8_SB(1, 0), b3, voffB); PG8_STAGE(PG8_SB(1, 1), b3 + hstepB, voffB); PG8_STAGE(PG8_SA(1, 0), a3, voffA);
;             PG8_WAIT_V(8); PG8_WAIT_L(0); PG8_BAR; PG8_MMA(1, 0, At, B0); PG8_MMA(1, 1, At, B1); PG8_BAR; PG8_SCHED;
;         }
;         if constexpr (ALIGN_EPI) { if (wr == 0) PG8_BAR; }
	s_add_i32 s8, s49, s40
	v_lshl_add_u64 v[152:153], v[152:153], 0, s[94:95]
	s_mov_b32 m0, s8
	ds_read_b128 v[192:195], v150 offset:49152
	ds_read_b128 v[196:199], v150 offset:50176
	ds_read_b128 v[200:203], v150 offset:51200
	ds_read_b128 v[204:207], v150 offset:52224
	ds_read_b128 v[208:211], v150 offset:53248
	ds_read_b128 v[212:215], v150 offset:54272
	ds_read_b128 v[216:219], v150 offset:55296
	ds_read_b128 v[220:223], v150 offset:56320
	global_load_lds_dwordx4 v[152:153], off
	s_add_i32 m0, s8, 0x2000
	s_add_u32 s6, s6, 0x40080
	v_lshl_add_u64 v[152:153], v[164:165], 0, s[94:95]
	s_addc_u32 s7, s7, 0
	s_add_i32 s8, s50, s40
	global_load_lds_dwordx4 v[152:153], off
	v_lshl_add_u64 v[152:153], s[6:7], 0, v[0:1]
	s_mov_b32 m0, s8
	s_nop 0
	global_load_lds_dwordx4 v[152:153], off
	v_lshl_add_u64 v[152:153], s[6:7], 0, v[134:135]
	s_add_i32 m0, s8, 0x2000
	s_nop 0
	global_load_lds_dwordx4 v[152:153], off
	v_lshl_add_u64 v[152:153], v[168:169], 0, s[94:95]
	s_mov_b32 m0, s46
	s_nop 0
	global_load_lds_dwordx4 v[152:153], off
	v_lshl_add_u64 v[152:153], v[174:175], 0, s[94:95]
	s_mov_b32 m0, s47
	s_nop 0
	global_load_lds_dwordx4 v[152:153], off
	s_waitcnt vmcnt(8)
	s_waitcnt lgkmcnt(0)
	s_barrier
	s_waitcnt lgkmcnt(0)
	v_mfma_f32_16x16x32_bf16 v[62:65], v[140:143], v[192:195], v[62:65]
	v_mfma_f32_16x16x32_bf16 v[58:61], v[156:159], v[192:195], v[58:61]
	v_mfma_f32_16x16x32_bf16 v[46:49], v[140:143], v[200:203], v[46:49]
	v_mfma_f32_16x16x32_bf16 v[42:45], v[156:159], v[200:203], v[42:45]
	v_mfma_f32_16x16x32_bf16 v[30:33], v[140:143], v[208:211], v[30:33]
	v_mfma_f32_16x16x32_bf16 v[26:29], v[156:159], v[208:211], v[26:29]
	v_mfma_f32_16x16x32_bf16 v[14:17], v[140:143], v[216:219], v[14:17]
	v_mfma_f32_16x16x32_bf16 v[10:13], v[156:159], v[216:219], v[10:13]
	v_mfma_f32_16x16x32_bf16 v[62:65], v[144:147], v[196:199], v[62:65]
	v_mfma_f32_16x16x32_bf16 v[58:61], v[160:163], v[196:199], v[58:61]
	v_mfma_f32_16x16x32_bf16 v[46:49], v[144:147], v[204:207], v[46:49]
	v_mfma_f32_16x16x32_bf16 v[42:45], v[160:163], v[204:207], v[42:45]
	v_mfma_f32_16x16x32_bf16 v[30:33], v[144:147], v[212:215], v[30:33]
	v_mfma_f32_16x16x32_bf16 v[26:29], v[160:163], v[212:215], v[26:29]
	v_mfma_f32_16x16x32_bf16 v[14:17], v[144:147], v[220:223], v[14:17]
	v_mfma_f32_16x16x32_bf16 v[10:13], v[160:163], v[220:223], v[10:13]
	v_mfma_f32_16x16x32_bf16 v[54:57], v[170:173], v[192:195], v[54:57]
	v_mfma_f32_16x16x32_bf16 v[50:53], v[184:187], v[192:195], v[50:53]
	v_mfma_f32_16x16x32_bf16 v[38:41], v[170:173], v[200:203], v[38:41]
	v_mfma_f32_16x16x32_bf16 v[34:37], v[184:187], v[200:203], v[34:37]
	v_mfma_f32_16x16x32_bf16 v[22:25], v[170:173], v[208:211], v[22:25]
	v_mfma_f32_16x16x32_bf16 v[18:21], v[184:187], v[208:211], v[18:21]
	v_mfma_f32_16x16x32_bf16 v[6:9], v[170:173], v[216:219], v[6:9]
	v_mfma_f32_16x16x32_bf16 v[2:5], v[184:187], v[216:219], v[2:5]
	v_mfma_f32_16x16x32_bf16 v[54:57], v[180:183], v[196:199], v[54:57]
	v_mfma_f32_16x16x32_bf16 v[50:53], v[188:191], v[196:199], v[50:53]
	v_mfma_f32_16x16x32_bf16 v[38:41], v[180:183], v[204:207], v[38:41]
	v_mfma_f32_16x16x32_bf16 v[34:37], v[188:191], v[204:207], v[34:37]
	v_mfma_f32_16x16x32_bf16 v[22:25], v[180:183], v[212:215], v[22:25]
	v_mfma_f32_16x16x32_bf16 v[18:21], v[188:191], v[212:215], v[18:21]
	v_mfma_f32_16x16x32_bf16 v[6:9], v[180:183], v[220:223], v[6:9]
	v_mfma_f32_16x16x32_bf16 v[2:5], v[188:191], v[220:223], v[2:5]
	s_barrier
	s_add_i32 s37, s37, 2
	s_add_u32 s2, s2, 0x100
	s_addc_u32 s3, s3, 0
	s_add_u32 s27, s27, 0x100
	s_addc_u32 s36, s36, 0
	s_cmp_gt_u32 s37, 13
	s_cbranch_scc0 .LBB0_102
	s_and_b64 vcc, exec, s[20:21]
	s_cbranch_vccz .LBB0_105
	s_barrier

; #define PG8_STAGE(bufoff, gbase, voff) do { _Pragma("unroll") for (int _i = 0; _i < 2; ++_i) \
;         __builtin_amdgcn_global_load_lds((const unsigned*)((const char*)(gbase) + (voff)[_i]), (LAS unsigned*)(lds + (bufoff) + ldsw + _i * 8192), 16, 0, 0); } while (0)
; #define PG8_LDA(dst, b, h) do { _Pragma("unroll") for (int m = 0; m < 4; ++m) _Pragma("unroll") for (int k = 0; k < 2; ++k) dst[m][k] = *(const LAS bf16x8*)(lds + PG8_SA(b, h) + aoff + m * 2048 + k * 1024); } while (0)
; #define PG8_LDB(dst, b, h) do { _Pragma("unroll") for (int n = 0; n < 2; ++n) _Pragma("unroll") for (int k = 0; k < 2; ++k) dst[n][k] = *(const LAS bf16x8*)(lds + PG8_SB(b, h) + boff + n * 2048 + k * 1024); } while (0)
; #define PG8_MMA(ai, bj, At, Bt) do { __builtin_amdgcn_s_setprio(1); _Pragma("unroll") for (int m = 0; m < 4; ++m) _Pragma("unroll") for (int n = 0; n < 2; ++n) _Pragma("unroll") for (int k = 0; k < 2; ++k) \
;         acc[ai][bj][m][n] = __builtin_amdgcn_mfma_f32_16x16x32_bf16(Bt[n][k], At[m][k], acc[ai][bj][m][n], 0, 0, 0); __builtin_amdgcn_s_setprio(0); } while (0)
; #define PG8_WAIT_V(n) asm volatile("s_waitcnt vmcnt(" #n ")" ::: "memory")
; #define PG8_WAIT_L(n) asm volatile("s_waitcnt lgkmcnt(" #n ")" ::: "memory")
; #define PG8_BAR __builtin_amdgcn_s_barrier()
; #define PG8_SCHED __builtin_amdgcn_sched_barrier(0)
; template <class Epi, bool ALIGN_EPI>
; __device__ __forceinline__ void gemm_phase(LAS unsigned char* lds, const Gemm g, const StaticOrder& S, const Epi& E) {
;     ...
;             const bool last = (t == nt - 2);
;             const char* a1 = cA + (size_t)(t + 1) * kstep;
;             const char* a2 = last ? nA : cA + (size_t)(t + 2) * kstep; const char* b2 = last ? nB : cB + (size_t)(t + 2) * kstep;
;             const char* a3 = a2 + kstep; const char* b3 = b2 + kstep;
;             PG8_LDB(B0, 0, 0); PG8_LDB(B1, 0, 1); PG8_SCHED; PG8_LDA(At, 0, 0); PG8_STAGE(PG8_SA(1, 1), a1 + hstepA, voffA);
;             PG8_WAIT_V(8); PG8_WAIT_L(0); PG8_BAR; PG8_MMA(0, 0, At, B0); PG8_MMA(0, 1, At, B1); PG8_BAR; PG8_SCHED;
;             PG8_LDA(At, 0, 1); PG8_STAGE(PG8_SB(0, 0), b2, voffB); PG8_STAGE(PG8_SB(0, 1), b2 + hstepB, voffB); PG8_STAGE(PG8_SA(0, 0), a2, voffA);
;             PG8_WAIT_V(8); PG8_WAIT_L(0); PG8_BAR; PG8_MMA(1, 0, At, B0); PG8_MMA(1, 1, At, B1); PG8_BAR; PG8_SCHED;
.LBB0_216:
	s_add_u32 s12, s10, 0x100
	s_addc_u32 s13, s11, 0
	s_add_i32 s44, 0, 0x10000
	s_cmp_eq_u32 s43, 40
	s_cselect_b32 s25, s19, s13
	s_cselect_b32 s24, s18, s12
	v_add_u32_e32 v144, s44, v146
	s_cselect_b32 s23, s21, s42
	s_cselect_b32 s22, s20, s41
	s_add_i32 s45, 0, 0x14000
	ds_read_b128 v[140:143], v144
	ds_read_b128 v[148:151], v144 offset:1024
	ds_read_b128 v[156:159], v144 offset:2048
	ds_read_b128 v[180:183], v144 offset:3072
	v_add_u32_e32 v144, s45, v146
	ds_read_b128 v[184:187], v144
	ds_read_b128 v[188:191], v144 offset:1024
	ds_read_b128 v[192:195], v144 offset:2048
	ds_read_b128 v[196:199], v144 offset:3072
	v_lshl_add_u64 v[144:145], s[10:11], 0, v[136:137]
	s_add_i32 m0, s29, 0xc000
	ds_read_b128 v[200:203], v147
	ds_read_b128 v[204:207], v147 offset:1024
	ds_read_b128 v[208:211], v147 offset:2048
	ds_read_b128 v[212:215], v147 offset:3072
	ds_read_b128 v[216:219], v147 offset:4096
	ds_read_b128 v[220:223], v147 offset:5120
	ds_read_b128 v[224:227], v147 offset:6144
	ds_read_b128 v[228:231], v147 offset:7168
	global_load_lds_dwordx4 v[144:145], off
	v_lshl_add_u64 v[144:145], s[10:11], 0, v[138:139]
	s_add_i32 m0, s29, 0xe000
	s_nop 0
	global_load_lds_dwordx4 v[144:145], off
	s_waitcnt vmcnt(8)
	s_waitcnt lgkmcnt(0)
	s_barrier
	s_waitcnt lgkmcnt(0)
	v_mfma_f32_16x16x32_bf16 v[126:129], v[140:143], v[200:203], v[126:129]
	v_mfma_f32_16x16x32_bf16 v[122:125], v[156:159], v[200:203], v[122:125]
	v_mfma_f32_16x16x32_bf16 v[110:113], v[140:143], v[208:211], v[110:113]
	v_mfma_f32_16x16x32_bf16 v[106:109], v[156:159], v[208:211], v[106:109]
	v_mfma_f32_16x16x32_bf16 v[94:97], v[140:143], v[216:219], v[94:97]
	v_mfma_f32_16x16x32_bf16 v[90:93], v[156:159], v[216:219], v[90:93]
	v_mfma_f32_16x16x32_bf16 v[78:81], v[140:143], v[224:227], v[78:81]
	v_mfma_f32_16x16x32_bf16 v[74:77], v[156:159], v[224:227], v[74:77]
	v_mfma_f32_16x16x32_bf16 v[126:129], v[148:151], v[204:207], v[126:129]
	v_mfma_f32_16x16x32_bf16 v[122:125], v[180:183], v[204:207], v[122:125]
	v_mfma_f32_16x16x32_bf16 v[110:113], v[148:151], v[212:215], v[110:113]
	v_mfma_f32_16x16x32_bf16 v[106:109], v[180:183], v[212:215], v[106:109]
	v_mfma_f32_16x16x32_bf16 v[94:97], v[148:151], v[220:223], v[94:97]
	v_mfma_f32_16x16x32_bf16 v[90:93], v[180:183], v[220:223], v[90:93]
	v_mfma_f32_16x16x32_bf16 v[78:81], v[148:151], v[228:231], v[78:81]
	v_mfma_f32_16x16x32_bf16 v[74:77], v[180:183], v[228:231], v[74:77]
	v_mfma_f32_16x16x32_bf16 v[118:121], v[184:187], v[200:203], v[118:121]
	v_mfma_f32_16x16x32_bf16 v[114:117], v[192:195], v[200:203], v[114:117]
	v_mfma_f32_16x16x32_bf16 v[102:105], v[184:187], v[208:211], v[102:105]
	v_mfma_f32_16x16x32_bf16 v[98:101], v[192:195], v[208:211], v[98:101]
	v_mfma_f32_16x16x32_bf16 v[86:89], v[184:187], v[216:219], v[86:89]
	v_mfma_f32_16x16x32_bf16 v[82:85], v[192:195], v[216:219], v[82:85]
	v_mfma_f32_16x16x32_bf16 v[70:73], v[184:187], v[224:227], v[70:73]
	v_mfma_f32_16x16x32_bf16 v[66:69], v[192:195], v[224:227], v[66:69]
	v_mfma_f32_16x16x32_bf16 v[118:121], v[188:191], v[204:207], v[118:121]
	v_mfma_f32_16x16x32_bf16 v[114:117], v[196:199], v[204:207], v[114:117]
	v_mfma_f32_16x16x32_bf16 v[102:105], v[188:191], v[212:215], v[102:105]
	v_mfma_f32_16x16x32_bf16 v[98:101], v[196:199], v[212:215], v[98:101]
	v_mfma_f32_16x16x32_bf16 v[86:89], v[188:191], v[220:223], v[86:89]
	v_mfma_f32_16x16x32_bf16 v[82:85], v[196:199], v[220:223], v[82:85]
	v_mfma_f32_16x16x32_bf16 v[70:73], v[188:191], v[228:231], v[70:73]
	v_mfma_f32_16x16x32_bf16 v[66:69], v[196:199], v[228:231], v[66:69]
	s_barrier
	s_add_i32 s10, s44, s28
	v_lshl_add_u64 v[144:145], s[22:23], 0, v[0:1]
	s_mov_b32 m0, s10
	ds_read_b128 v[200:203], v147 offset:16384
	ds_read_b128 v[204:207], v147 offset:17408
	ds_read_b128 v[208:211], v147 offset:18432
	ds_read_b128 v[212:215], v147 offset:19456
	ds_read_b128 v[216:219], v147 offset:20480
	ds_read_b128 v[220:223], v147 offset:21504
	ds_read_b128 v[224:227], v147 offset:22528
	ds_read_b128 v[228:231], v147 offset:23552
	global_load_lds_dwordx4 v[144:145], off
	s_add_i32 m0, s10, 0x2000
	s_add_u32 s10, s22, 0xb0000
	v_lshl_add_u64 v[152:153], s[22:23], 0, v[134:135]
	s_addc_u32 s11, s23, 0
	s_add_i32 s44, s45, s28
	global_load_lds_dwordx4 v[152:153], off
	v_lshl_add_u64 v[160:161], s[10:11], 0, v[0:1]
	s_mov_b32 m0, s44
	v_lshl_add_u64 v[162:163], s[24:25], 0, v[132:133]
	global_load_lds_dwordx4 v[160:161], off
	v_lshl_add_u64 v[160:161], s[10:11], 0, v[134:135]
	s_add_i32 m0, s44, 0x2000
	s_nop 0
	global_load_lds_dwordx4 v[160:161], off
	v_lshl_add_u64 v[160:161], s[24:25], 0, v[130:131]
	s_mov_b32 m0, s29
	s_nop 0
	global_load_lds_dwordx4 v[160:161], off
	s_mov_b32 m0, s30
	s_nop 0
	global_load_lds_dwordx4 v[162:163], off
	s_waitcnt vmcnt(8)
	s_waitcnt lgkmcnt(0)
	s_barrier
; #define PG8_STAGE(bufoff, gbase, voff) do { _Pragma("unroll") for (int _i = 0; _i < 2; ++_i) \
;         __builtin_amdgcn_global_load_lds((const unsigned*)((const char*)(gbase) + (voff)[_i]), (LAS unsigned*)(lds + (bufoff) + ldsw + _i * 8192), 16, 0, 0); } while (0)
; #define PG8_LDA(dst, b, h) do { _Pragma("unroll") for (int m = 0; m < 4; ++m) _Pragma("unroll") for (int k = 0; k < 2; ++k) dst[m][k] = *(const LAS bf16x8*)(lds + PG8_SA(b, h) + aoff + m * 2048 + k * 1024); } while (0)
; #define PG8_LDB(dst, b, h) do { _Pragma("unroll") for (int n = 0; n < 2; ++n) _Pragma("unroll") for (int k = 0; k < 2; ++k) dst[n][k] = *(const LAS bf16x8*)(lds + PG8_SB(b, h) + boff + n * 2048 + k * 1024); } while (0)
; #define PG8_MMA(ai, bj, At, Bt) do { __builtin_amdgcn_s_setprio(1); _Pragma("unroll") for (int m = 0; m < 4; ++m) _Pragma("unroll") for (int n = 0; n < 2; ++n) _Pragma("unroll") for (int k = 0; k < 2; ++k) \
;         acc[ai][bj][m][n] = __builtin_amdgcn_mfma_f32_16x16x32_bf16(Bt[n][k], At[m][k], acc[ai][bj][m][n], 0, 0, 0); __builtin_amdgcn_s_setprio(0); } while (0)
; #define PG8_WAIT_V(n) asm volatile("s_waitcnt vmcnt(" #n ")" ::: "memory")
; #define PG8_WAIT_L(n) asm volatile("s_waitcnt lgkmcnt(" #n ")" ::: "memory")
; #define PG8_BAR __builtin_amdgcn_s_barrier()
; #define PG8_SCHED __builtin_amdgcn_sched_barrier(0)
; template <class Epi, bool ALIGN_EPI>
; __device__ __forceinline__ void gemm_phase(LAS unsigned char* lds, const Gemm g, const StaticOrder& S, const Epi& E) {
;     ...
;             PG8_WAIT_V(8); PG8_WAIT_L(0); PG8_BAR; PG8_MMA(1, 0, At, B0); PG8_MMA(1, 1, At, B1); PG8_BAR; PG8_SCHED;
;             PG8_LDB(B0, 1, 0); PG8_LDB(B1, 1, 1); PG8_SCHED; PG8_LDA(At, 1, 0); PG8_STAGE(PG8_SA(0, 1), a2 + hstepA, voffA);
;             PG8_WAIT_V(8); PG8_WAIT_L(0); PG8_BAR; PG8_MMA(0, 0, At, B0); PG8_MMA(0, 1, At, B1); PG8_BAR; PG8_SCHED;
	s_waitcnt lgkmcnt(0)
	v_mfma_f32_16x16x32_bf16 v[62:65], v[140:143], v[200:203], v[62:65]
	v_mfma_f32_16x16x32_bf16 v[58:61], v[156:159], v[200:203], v[58:61]
	v_mfma_f32_16x16x32_bf16 v[46:49], v[140:143], v[208:211], v[46:49]
	v_mfma_f32_16x16x32_bf16 v[42:45], v[156:159], v[208:211], v[42:45]
	v_mfma_f32_16x16x32_bf16 v[30:33], v[140:143], v[216:219], v[30:33]
	v_mfma_f32_16x16x32_bf16 v[26:29], v[156:159], v[216:219], v[26:29]
	v_mfma_f32_16x16x32_bf16 v[14:17], v[140:143], v[224:227], v[14:17]
	v_mfma_f32_16x16x32_bf16 v[10:13], v[156:159], v[224:227], v[10:13]
	v_mfma_f32_16x16x32_bf16 v[62:65], v[148:151], v[204:207], v[62:65]
	v_mfma_f32_16x16x32_bf16 v[58:61], v[180:183], v[204:207], v[58:61]
	v_mfma_f32_16x16x32_bf16 v[46:49], v[148:151], v[212:215], v[46:49]
	v_mfma_f32_16x16x32_bf16 v[42:45], v[180:183], v[212:215], v[42:45]
	v_mfma_f32_16x16x32_bf16 v[30:33], v[148:151], v[220:223], v[30:33]
	v_mfma_f32_16x16x32_bf16 v[26:29], v[180:183], v[220:223], v[26:29]
	v_mfma_f32_16x16x32_bf16 v[14:17], v[148:151], v[228:231], v[14:17]
	v_mfma_f32_16x16x32_bf16 v[10:13], v[180:183], v[228:231], v[10:13]
	v_mfma_f32_16x16x32_bf16 v[54:57], v[184:187], v[200:203], v[54:57]
	v_mfma_f32_16x16x32_bf16 v[50:53], v[192:195], v[200:203], v[50:53]
	v_mfma_f32_16x16x32_bf16 v[38:41], v[184:187], v[208:211], v[38:41]
	v_mfma_f32_16x16x32_bf16 v[34:37], v[192:195], v[208:211], v[34:37]
	v_mfma_f32_16x16x32_bf16 v[22:25], v[184:187], v[216:219], v[22:25]
	v_mfma_f32_16x16x32_bf16 v[18:21], v[192:195], v[216:219], v[18:21]
	v_mfma_f32_16x16x32_bf16 v[6:9], v[184:187], v[224:227], v[6:9]
	v_mfma_f32_16x16x32_bf16 v[2:5], v[192:195], v[224:227], v[2:5]
	v_mfma_f32_16x16x32_bf16 v[54:57], v[188:191], v[204:207], v[54:57]
	v_mfma_f32_16x16x32_bf16 v[50:53], v[196:199], v[204:207], v[50:53]
	v_mfma_f32_16x16x32_bf16 v[38:41], v[188:191], v[212:215], v[38:41]
	v_mfma_f32_16x16x32_bf16 v[34:37], v[196:199], v[212:215], v[34:37]
	v_mfma_f32_16x16x32_bf16 v[22:25], v[188:191], v[220:223], v[22:25]
	v_mfma_f32_16x16x32_bf16 v[18:21], v[196:199], v[220:223], v[18:21]
	v_mfma_f32_16x16x32_bf16 v[6:9], v[188:191], v[228:231], v[6:9]
	v_mfma_f32_16x16x32_bf16 v[2:5], v[196:199], v[228:231], v[2:5]
	s_barrier
	s_add_i32 s44, 0, 0x18000
	v_add_u32_e32 v164, s44, v146
	s_add_i32 s45, 0, 0x1c000
	ds_read_b128 v[140:143], v164
	ds_read_b128 v[148:151], v164 offset:1024
	ds_read_b128 v[156:159], v164 offset:2048
	ds_read_b128 v[180:183], v164 offset:3072
	v_add_u32_e32 v164, s45, v146
	ds_read_b128 v[184:187], v164
	ds_read_b128 v[188:191], v164 offset:1024
	ds_read_b128 v[192:195], v164 offset:2048
	ds_read_b128 v[196:199], v164 offset:3072
	s_add_u32 s10, s24, 0xb0000
	s_addc_u32 s11, s25, 0
	s_mov_b32 m0, s31
	v_lshl_add_u64 v[170:171], s[10:11], 0, v[130:131]
	ds_read_b128 v[200:203], v147 offset:32768
	ds_read_b128 v[204:207], v147 offset:33792
	ds_read_b128 v[208:211], v147 offset:34816
	ds_read_b128 v[212:215], v147 offset:35840
	ds_read_b128 v[216:219], v147 offset:36864
	ds_read_b128 v[220:223], v147 offset:37888
	ds_read_b128 v[224:227], v147 offset:38912
	ds_read_b128 v[228:231], v147 offset:39936
	global_load_lds_dwordx4 v[170:171], off
	v_lshl_add_u64 v[170:171], s[10:11], 0, v[132:133]
	s_mov_b32 m0, s34
	s_nop 0
	global_load_lds_dwordx4 v[170:171], off
	s_waitcnt vmcnt(8)
	s_waitcnt lgkmcnt(0)
	s_barrier
	s_waitcnt lgkmcnt(0)
	v_mfma_f32_16x16x32_bf16 v[126:129], v[140:143], v[200:203], v[126:129]
	v_mfma_f32_16x16x32_bf16 v[122:125], v[156:159], v[200:203], v[122:125]
	v_mfma_f32_16x16x32_bf16 v[110:113], v[140:143], v[208:211], v[110:113]
	v_mfma_f32_16x16x32_bf16 v[106:109], v[156:159], v[208:211], v[106:109]
	v_mfma_f32_16x16x32_bf16 v[94:97], v[140:143], v[216:219], v[94:97]
	v_mfma_f32_16x16x32_bf16 v[90:93], v[156:159], v[216:219], v[90:93]
	v_mfma_f32_16x16x32_bf16 v[78:81], v[140:143], v[224:227], v[78:81]
	v_mfma_f32_16x16x32_bf16 v[74:77], v[156:159], v[224:227], v[74:77]
	v_mfma_f32_16x16x32_bf16 v[126:129], v[148:151], v[204:207], v[126:129]
	v_mfma_f32_16x16x32_bf16 v[122:125], v[180:183], v[204:207], v[122:125]
	v_mfma_f32_16x16x32_bf16 v[110:113], v[148:151], v[212:215], v[110:113]
	v_mfma_f32_16x16x32_bf16 v[106:109], v[180:183], v[212:215], v[106:109]
	v_mfma_f32_16x16x32_bf16 v[94:97], v[148:151], v[220:223], v[94:97]
	v_mfma_f32_16x16x32_bf16 v[90:93], v[180:183], v[220:223], v[90:93]
	v_mfma_f32_16x16x32_bf16 v[78:81], v[148:151], v[228:231], v[78:81]
	v_mfma_f32_16x16x32_bf16 v[74:77], v[180:183], v[228:231], v[74:77]
	v_mfma_f32_16x16x32_bf16 v[118:121], v[184:187], v[200:203], v[118:121]
	v_mfma_f32_16x16x32_bf16 v[114:117], v[192:195], v[200:203], v[114:117]
	v_mfma_f32_16x16x32_bf16 v[102:105], v[184:187], v[208:211], v[102:105]
	v_mfma_f32_16x16x32_bf16 v[98:101], v[192:195], v[208:211], v[98:101]
	v_mfma_f32_16x16x32_bf16 v[86:89], v[184:187], v[216:219], v[86:89]
	v_mfma_f32_16x16x32_bf16 v[82:85], v[192:195], v[216:219], v[82:85]
	v_mfma_f32_16x16x32_bf16 v[70:73], v[184:187], v[224:227], v[70:73]
	v_mfma_f32_16x16x32_bf16 v[66:69], v[192:195], v[224:227], v[66:69]
	v_mfma_f32_16x16x32_bf16 v[118:121], v[188:191], v[204:207], v[118:121]
	v_mfma_f32_16x16x32_bf16 v[114:117], v[196:199], v[204:207], v[114:117]
	v_mfma_f32_16x16x32_bf16 v[102:105], v[188:191], v[212:215], v[102:105]
	v_mfma_f32_16x16x32_bf16 v[98:101], v[196:199], v[212:215], v[98:101]
	v_mfma_f32_16x16x32_bf16 v[86:89], v[188:191], v[220:223], v[86:89]
	v_mfma_f32_16x16x32_bf16 v[82:85], v[196:199], v[220:223], v[82:85]
	v_mfma_f32_16x16x32_bf16 v[70:73], v[188:191], v[228:231], v[70:73]
	v_mfma_f32_16x16x32_bf16 v[66:69], v[196:199], v[228:231], v[66:69]
	s_barrier
; #define PG8_STAGE(bufoff, gbase, voff) do { _Pragma("unroll") for (int _i = 0; _i < 2; ++_i) \
;         __builtin_amdgcn_global_load_lds((const unsigned*)((const char*)(gbase) + (voff)[_i]), (LAS unsigned*)(lds + (bufoff) + ldsw + _i * 8192), 16, 0, 0); } while (0)
; #define PG8_LDA(dst, b, h) do { _Pragma("unroll") for (int m = 0; m < 4; ++m) _Pragma("unroll") for (int k = 0; k < 2; ++k) dst[m][k] = *(const LAS bf16x8*)(lds + PG8_SA(b, h) + aoff + m * 2048 + k * 1024); } while (0)
; #define PG8_MMA(ai, bj, At, Bt) do { __builtin_amdgcn_s_setprio(1); _Pragma("unroll") for (int m = 0; m < 4; ++m) _Pragma("unroll") for (int n = 0; n < 2; ++n) _Pragma("unroll") for (int k = 0; k < 2; ++k) \
;         acc[ai][bj][m][n] = __builtin_amdgcn_mfma_f32_16x16x32_bf16(Bt[n][k], At[m][k], acc[ai][bj][m][n], 0, 0, 0); __builtin_amdgcn_s_setprio(0); } while (0)
; #define PG8_WAIT_V(n) asm volatile("s_waitcnt vmcnt(" #n ")" ::: "memory")
; #define PG8_WAIT_L(n) asm volatile("s_waitcnt lgkmcnt(" #n ")" ::: "memory")
; #define PG8_BAR __builtin_amdgcn_s_barrier()
; #define PG8_SCHED __builtin_amdgcn_sched_barrier(0)
; template <class Epi, bool ALIGN_EPI>
; __device__ __forceinline__ void gemm_phase(LAS unsigned char* lds, const Gemm g, const StaticOrder& S, const Epi& E) {
;     ...
;             PG8_LDA(At, 1, 1); PG8_STAGE(PG8_SB(1, 0), b3, voffB); PG8_STAGE(PG8_SB(1, 1), b3 + hstepB, voffB); PG8_STAGE(PG8_SA(1, 0), a3, voffA);
;             PG8_WAIT_V(8); PG8_WAIT_L(0); PG8_BAR; PG8_MMA(1, 0, At, B0); PG8_MMA(1, 1, At, B1); PG8_BAR; PG8_SCHED;
;         }
;         if constexpr (ALIGN_EPI) { if (wr == 0) PG8_BAR; }
	s_add_i32 s10, s44, s28
	v_lshl_add_u64 v[144:145], v[144:145], 0, s[94:95]
	s_mov_b32 m0, s10
	ds_read_b128 v[200:203], v147 offset:49152
	ds_read_b128 v[204:207], v147 offset:50176
	ds_read_b128 v[208:211], v147 offset:51200
	ds_read_b128 v[212:215], v147 offset:52224
	ds_read_b128 v[216:219], v147 offset:53248
	ds_read_b128 v[220:223], v147 offset:54272
	ds_read_b128 v[224:227], v147 offset:55296
	ds_read_b128 v[228:231], v147 offset:56320
	global_load_lds_dwordx4 v[144:145], off
	s_add_i32 m0, s10, 0x2000
	s_add_u32 s10, s22, 0xb0080
	v_lshl_add_u64 v[144:145], v[152:153], 0, s[94:95]
	s_addc_u32 s11, s23, 0
	s_add_i32 s22, s45, s28
	global_load_lds_dwordx4 v[144:145], off
	v_lshl_add_u64 v[144:145], s[10:11], 0, v[0:1]
	s_mov_b32 m0, s22
	s_nop 0
	global_load_lds_dwordx4 v[144:145], off
	v_lshl_add_u64 v[144:145], s[10:11], 0, v[134:135]
	s_add_i32 m0, s22, 0x2000
	s_nop 0
	global_load_lds_dwordx4 v[144:145], off
	v_lshl_add_u64 v[144:145], v[160:161], 0, s[94:95]
	s_mov_b32 m0, s35
	s_nop 0
	global_load_lds_dwordx4 v[144:145], off
	v_lshl_add_u64 v[144:145], v[162:163], 0, s[94:95]
	s_mov_b32 m0, s36
	s_nop 0
	global_load_lds_dwordx4 v[144:145], off
	s_waitcnt vmcnt(8)
	s_waitcnt lgkmcnt(0)
	s_barrier
	s_waitcnt lgkmcnt(0)
	v_mfma_f32_16x16x32_bf16 v[62:65], v[140:143], v[200:203], v[62:65]
	v_mfma_f32_16x16x32_bf16 v[58:61], v[156:159], v[200:203], v[58:61]
	v_mfma_f32_16x16x32_bf16 v[46:49], v[140:143], v[208:211], v[46:49]
	v_mfma_f32_16x16x32_bf16 v[42:45], v[156:159], v[208:211], v[42:45]
	v_mfma_f32_16x16x32_bf16 v[30:33], v[140:143], v[216:219], v[30:33]
	v_mfma_f32_16x16x32_bf16 v[26:29], v[156:159], v[216:219], v[26:29]
	v_mfma_f32_16x16x32_bf16 v[14:17], v[140:143], v[224:227], v[14:17]
	v_mfma_f32_16x16x32_bf16 v[10:13], v[156:159], v[224:227], v[10:13]
	v_mfma_f32_16x16x32_bf16 v[62:65], v[148:151], v[204:207], v[62:65]
	v_mfma_f32_16x16x32_bf16 v[58:61], v[180:183], v[204:207], v[58:61]
	v_mfma_f32_16x16x32_bf16 v[46:49], v[148:151], v[212:215], v[46:49]
	v_mfma_f32_16x16x32_bf16 v[42:45], v[180:183], v[212:215], v[42:45]
	v_mfma_f32_16x16x32_bf16 v[30:33], v[148:151], v[220:223], v[30:33]
	v_mfma_f32_16x16x32_bf16 v[26:29], v[180:183], v[220:223], v[26:29]
	v_mfma_f32_16x16x32_bf16 v[14:17], v[148:151], v[228:231], v[14:17]
	v_mfma_f32_16x16x32_bf16 v[10:13], v[180:183], v[228:231], v[10:13]
	v_mfma_f32_16x16x32_bf16 v[54:57], v[184:187], v[200:203], v[54:57]
	v_mfma_f32_16x16x32_bf16 v[50:53], v[192:195], v[200:203], v[50:53]
	v_mfma_f32_16x16x32_bf16 v[38:41], v[184:187], v[208:211], v[38:41]
	v_mfma_f32_16x16x32_bf16 v[34:37], v[192:195], v[208:211], v[34:37]
	v_mfma_f32_16x16x32_bf16 v[22:25], v[184:187], v[216:219], v[22:25]
	v_mfma_f32_16x16x32_bf16 v[18:21], v[192:195], v[216:219], v[18:21]
	v_mfma_f32_16x16x32_bf16 v[6:9], v[184:187], v[224:227], v[6:9]
	v_mfma_f32_16x16x32_bf16 v[2:5], v[192:195], v[224:227], v[2:5]
	v_mfma_f32_16x16x32_bf16 v[54:57], v[188:191], v[204:207], v[54:57]
	v_mfma_f32_16x16x32_bf16 v[50:53], v[196:199], v[204:207], v[50:53]
	v_mfma_f32_16x16x32_bf16 v[38:41], v[188:191], v[212:215], v[38:41]
	v_mfma_f32_16x16x32_bf16 v[34:37], v[196:199], v[212:215], v[34:37]
	v_mfma_f32_16x16x32_bf16 v[22:25], v[188:191], v[220:223], v[22:25]
	v_mfma_f32_16x16x32_bf16 v[18:21], v[196:199], v[220:223], v[18:21]
	v_mfma_f32_16x16x32_bf16 v[6:9], v[188:191], v[228:231], v[6:9]
	v_mfma_f32_16x16x32_bf16 v[2:5], v[196:199], v[228:231], v[2:5]
	s_barrier
	s_add_i32 s43, s43, 2
	s_add_u32 s41, s41, 0x100
	s_addc_u32 s42, s42, 0
	s_cmp_gt_u32 s43, 41
	s_mov_b64 s[10:11], s[12:13]
	s_cbranch_scc0 .LBB0_216
	s_and_b64 vcc, exec, s[2:3]
	s_cbranch_vccz .LBB0_219
	s_barrier

; #define PG8_STAGE(bufoff, gbase, voff) do { _Pragma("unroll") for (int _i = 0; _i < 2; ++_i) \
;         __builtin_amdgcn_global_load_lds((const unsigned*)((const char*)(gbase) + (voff)[_i]), (LAS unsigned*)(lds + (bufoff) + ldsw + _i * 8192), 16, 0, 0); } while (0)
; #define PG8_LDA(dst, b, h) do { _Pragma("unroll") for (int m = 0; m < 4; ++m) _Pragma("unroll") for (int k = 0; k < 2; ++k) dst[m][k] = *(const LAS bf16x8*)(lds + PG8_SA(b, h) + aoff + m * 2048 + k * 1024); } while (0)
; #define PG8_LDB(dst, b, h) do { _Pragma("unroll") for (int n = 0; n < 2; ++n) _Pragma("unroll") for (int k = 0; k < 2; ++k) dst[n][k] = *(const LAS bf16x8*)(lds + PG8_SB(b, h) + boff + n * 2048 + k * 1024); } while (0)
; #define PG8_MMA(ai, bj, At, Bt) do { __builtin_amdgcn_s_setprio(1); _Pragma("unroll") for (int m = 0; m < 4; ++m) _Pragma("unroll") for (int n = 0; n < 2; ++n) _Pragma("unroll") for (int k = 0; k < 2; ++k) \
;         acc[ai][bj][m][n] = __builtin_amdgcn_mfma_f32_16x16x32_bf16(Bt[n][k], At[m][k], acc[ai][bj][m][n], 0, 0, 0); __builtin_amdgcn_s_setprio(0); } while (0)
; #define PG8_BAR __builtin_amdgcn_s_barrier()
; template <class Epi, bool ALIGN_EPI>
; __device__ __forceinline__ void gemm_phase(LAS unsigned char* lds, const Gemm g, const StaticOrder& S, const Epi& E) {
;     ...
;         const bool has_next = S.next(ui + 1, nxt);
;         const char* nA = has_next ? (const char*)g.A + (size_t)nxt.pm * tstepA : cA; const char* nB = has_next ? (const char*)g.Bt + (size_t)nxt.pn * tstepB : cB;
;         for (int t = 0; t < nt; t += 2) {
;             const bool last = (t == nt - 2);
;             const char* a1 = cA + (size_t)(t + 1) * kstep;
;             const char* a2 = last ? nA : cA + (size_t)(t + 2) * kstep; const char* b2 = last ? nB : cB + (size_t)(t + 2) * kstep;
;             const char* a3 = a2 + kstep; const char* b3 = b2 + kstep;
;             PG8_LDB(B0, 0, 0); PG8_LDB(B1, 0, 1); PG8_SCHED; PG8_LDA(At, 0, 0); PG8_STAGE(PG8_SA(1, 1), a1 + hstepA, voffA);
;             PG8_WAIT_V(8); PG8_WAIT_L(0); PG8_BAR; PG8_MMA(0, 0, At, B0); PG8_MMA(0, 1, At, B1); PG8_BAR; PG8_SCHED;
;             PG8_LDA(At, 0, 1); PG8_STAGE(PG8_SB(0, 0), b2, voffB); PG8_STAGE(PG8_SB(0, 1), b2 + hstepB, voffB); PG8_STAGE(PG8_SA(0, 0), a2, voffA);
;             PG8_WAIT_V(8); PG8_WAIT_L(0); PG8_BAR; PG8_MMA(1, 0, At, B0); PG8_MMA(1, 1, At, B1); PG8_BAR; PG8_SCHED;
.LBB0_287:
	s_ashr_i32 s9, s8, 31
	s_lshl_b64 s[16:17], s[8:9], 17
	s_add_u32 s16, s4, s16
	s_addc_u32 s17, s28, s17
	s_and_b64 s[18:19], s[12:13], exec
	s_cselect_b32 s27, s17, s21
	s_cselect_b32 s26, s16, s20
	s_ashr_i32 s11, s10, 31
	s_lshl_b64 s[18:19], s[10:11], 17
	s_add_u32 s18, s29, s18
	s_addc_u32 s19, s30, s19
	s_and_b64 s[24:25], s[12:13], exec
	s_cselect_b32 s25, s19, s23
	s_cselect_b32 s24, s18, s22
	s_add_i32 s11, 0, 0x10000
	s_add_i32 s41, 0, 0x14000
	v_add_u32_e32 v164, s11, v136
	v_add_u32_e32 v165, s41, v136
	ds_read_b128 v[2:5], v164
	ds_read_b128 v[6:9], v164 offset:1024
	ds_read_b128 v[10:13], v164 offset:2048
	ds_read_b128 v[14:17], v164 offset:3072
	ds_read_b128 v[18:21], v165
	ds_read_b128 v[22:25], v165 offset:1024
	ds_read_b128 v[26:29], v165 offset:2048
	ds_read_b128 v[30:33], v165 offset:3072
	s_add_u32 s42, s20, 0x10080
	s_addc_u32 s43, s21, 0
	s_add_i32 s45, s34, 0xc000
	v_lshl_add_u64 v[66:67], s[42:43], 0, v[130:131]
	s_mov_b32 m0, s45
	s_add_i32 s9, s34, 0xe000
	ds_read_b128 v[34:37], v137
	ds_read_b128 v[38:41], v137 offset:1024
	ds_read_b128 v[42:45], v137 offset:2048
	ds_read_b128 v[46:49], v137 offset:3072
	ds_read_b128 v[50:53], v137 offset:4096
	ds_read_b128 v[54:57], v137 offset:5120
	ds_read_b128 v[58:61], v137 offset:6144
	ds_read_b128 v[62:65], v137 offset:7168
	global_load_lds_dwordx4 v[66:67], off
	v_lshl_add_u64 v[66:67], s[42:43], 0, v[132:133]
	s_mov_b32 m0, s9
	s_nop 0
	global_load_lds_dwordx4 v[66:67], off
	s_waitcnt vmcnt(8)
	s_waitcnt lgkmcnt(0)
	s_barrier
	s_waitcnt lgkmcnt(0)
	v_mfma_f32_16x16x32_bf16 v[66:69], v[2:5], v[34:37], 0
	v_mfma_f32_16x16x32_bf16 v[70:73], v[10:13], v[34:37], 0
	v_mfma_f32_16x16x32_bf16 v[74:77], v[2:5], v[42:45], 0
	v_mfma_f32_16x16x32_bf16 v[78:81], v[10:13], v[42:45], 0
	v_mfma_f32_16x16x32_bf16 v[82:85], v[2:5], v[50:53], 0
	v_mfma_f32_16x16x32_bf16 v[86:89], v[10:13], v[50:53], 0
	v_mfma_f32_16x16x32_bf16 v[90:93], v[2:5], v[58:61], 0
	v_mfma_f32_16x16x32_bf16 v[94:97], v[10:13], v[58:61], 0
	v_mfma_f32_16x16x32_bf16 v[66:69], v[6:9], v[38:41], v[66:69]
	v_mfma_f32_16x16x32_bf16 v[70:73], v[14:17], v[38:41], v[70:73]
	v_mfma_f32_16x16x32_bf16 v[74:77], v[6:9], v[46:49], v[74:77]
	v_mfma_f32_16x16x32_bf16 v[78:81], v[14:17], v[46:49], v[78:81]
	v_mfma_f32_16x16x32_bf16 v[82:85], v[6:9], v[54:57], v[82:85]
	v_mfma_f32_16x16x32_bf16 v[86:89], v[14:17], v[54:57], v[86:89]
	v_mfma_f32_16x16x32_bf16 v[90:93], v[6:9], v[62:65], v[90:93]
	v_mfma_f32_16x16x32_bf16 v[94:97], v[14:17], v[62:65], v[94:97]
	v_mfma_f32_16x16x32_bf16 v[98:101], v[18:21], v[34:37], 0
	v_mfma_f32_16x16x32_bf16 v[34:37], v[26:29], v[34:37], 0
	v_mfma_f32_16x16x32_bf16 v[98:101], v[22:25], v[38:41], v[98:101]
	v_mfma_f32_16x16x32_bf16 v[34:37], v[30:33], v[38:41], v[34:37]
	v_mfma_f32_16x16x32_bf16 v[38:41], v[18:21], v[42:45], 0
	v_mfma_f32_16x16x32_bf16 v[42:45], v[26:29], v[42:45], 0
	v_mfma_f32_16x16x32_bf16 v[38:41], v[22:25], v[46:49], v[38:41]
	v_mfma_f32_16x16x32_bf16 v[42:45], v[30:33], v[46:49], v[42:45]
	v_mfma_f32_16x16x32_bf16 v[46:49], v[18:21], v[50:53], 0
	v_mfma_f32_16x16x32_bf16 v[50:53], v[26:29], v[50:53], 0
	v_mfma_f32_16x16x32_bf16 v[46:49], v[22:25], v[54:57], v[46:49]
	v_mfma_f32_16x16x32_bf16 v[50:53], v[30:33], v[54:57], v[50:53]
	v_mfma_f32_16x16x32_bf16 v[54:57], v[18:21], v[58:61], 0
	v_mfma_f32_16x16x32_bf16 v[58:61], v[26:29], v[58:61], 0
	v_mfma_f32_16x16x32_bf16 v[54:57], v[22:25], v[62:65], v[54:57]
	v_mfma_f32_16x16x32_bf16 v[58:61], v[30:33], v[62:65], v[58:61]
	s_barrier
	s_add_i32 s43, s11, s31
	v_lshl_add_u64 v[160:161], s[22:23], 0, v[0:1]
	s_mov_b64 s[48:49], 0x100
	s_add_i32 s11, s43, 0x2000
	v_lshl_add_u64 v[138:139], v[160:161], 0, s[48:49]
	s_mov_b32 m0, s43
	v_lshl_add_u64 v[162:163], s[22:23], 0, v[134:135]
	s_add_u32 s46, s22, 0x10100
	ds_read_b128 v[62:65], v137 offset:16384
	ds_read_b128 v[102:105], v137 offset:17408
	ds_read_b128 v[106:109], v137 offset:18432
	ds_read_b128 v[110:113], v137 offset:19456
	ds_read_b128 v[114:117], v137 offset:20480
	ds_read_b128 v[118:121], v137 offset:21504
	ds_read_b128 v[122:125], v137 offset:22528
	ds_read_b128 v[126:129], v137 offset:23552
	global_load_lds_dwordx4 v[138:139], off
	v_lshl_add_u64 v[138:139], v[162:163], 0, s[48:49]
	s_mov_b32 m0, s11
	s_addc_u32 s47, s23, 0
	s_add_i32 s41, s41, s31
	global_load_lds_dwordx4 v[138:139], off
	v_lshl_add_u64 v[138:139], s[46:47], 0, v[0:1]
	s_mov_b32 m0, s41
	s_add_i32 s42, s41, 0x2000
	global_load_lds_dwordx4 v[138:139], off
	v_lshl_add_u64 v[138:139], s[46:47], 0, v[134:135]
	s_mov_b32 m0, s42
	v_lshl_add_u64 v[170:171], s[20:21], 0, v[130:131]
	global_load_lds_dwordx4 v[138:139], off
	v_lshl_add_u64 v[138:139], v[170:171], 0, s[48:49]
	s_mov_b32 m0, s34
	v_lshl_add_u64 v[172:173], s[20:21], 0, v[132:133]
	global_load_lds_dwordx4 v[138:139], off
	v_lshl_add_u64 v[138:139], v[172:173], 0, s[48:49]
	s_mov_b32 m0, s35
	s_nop 0
	global_load_lds_dwordx4 v[138:139], off
	s_waitcnt vmcnt(8)
	s_waitcnt lgkmcnt(0)
	s_barrier
; #define PG8_STAGE(bufoff, gbase, voff) do { _Pragma("unroll") for (int _i = 0; _i < 2; ++_i) \
;         __builtin_amdgcn_global_load_lds((const unsigned*)((const char*)(gbase) + (voff)[_i]), (LAS unsigned*)(lds + (bufoff) + ldsw + _i * 8192), 16, 0, 0); } while (0)
; #define PG8_LDA(dst, b, h) do { _Pragma("unroll") for (int m = 0; m < 4; ++m) _Pragma("unroll") for (int k = 0; k < 2; ++k) dst[m][k] = *(const LAS bf16x8*)(lds + PG8_SA(b, h) + aoff + m * 2048 + k * 1024); } while (0)
; #define PG8_LDB(dst, b, h) do { _Pragma("unroll") for (int n = 0; n < 2; ++n) _Pragma("unroll") for (int k = 0; k < 2; ++k) dst[n][k] = *(const LAS bf16x8*)(lds + PG8_SB(b, h) + boff + n * 2048 + k * 1024); } while (0)
; #define PG8_MMA(ai, bj, At, Bt) do { __builtin_amdgcn_s_setprio(1); _Pragma("unroll") for (int m = 0; m < 4; ++m) _Pragma("unroll") for (int n = 0; n < 2; ++n) _Pragma("unroll") for (int k = 0; k < 2; ++k) \
;         acc[ai][bj][m][n] = __builtin_amdgcn_mfma_f32_16x16x32_bf16(Bt[n][k], At[m][k], acc[ai][bj][m][n], 0, 0, 0); __builtin_amdgcn_s_setprio(0); } while (0)
; #define PG8_WAIT_V(n) asm volatile("s_waitcnt vmcnt(" #n ")" ::: "memory")
; #define PG8_WAIT_L(n) asm volatile("s_waitcnt lgkmcnt(" #n ")" ::: "memory")
; #define PG8_BAR __builtin_amdgcn_s_barrier()
; #define PG8_SCHED __builtin_amdgcn_sched_barrier(0)
; template <class Epi, bool ALIGN_EPI>
; __device__ __forceinline__ void gemm_phase(LAS unsigned char* lds, const Gemm g, const StaticOrder& S, const Epi& E) {
;     ...
;             PG8_WAIT_V(8); PG8_WAIT_L(0); PG8_BAR; PG8_MMA(1, 0, At, B0); PG8_MMA(1, 1, At, B1); PG8_BAR; PG8_SCHED;
;             PG8_LDB(B0, 1, 0); PG8_LDB(B1, 1, 1); PG8_SCHED; PG8_LDA(At, 1, 0); PG8_STAGE(PG8_SA(0, 1), a2 + hstepA, voffA);
;             PG8_WAIT_V(8); PG8_WAIT_L(0); PG8_BAR; PG8_MMA(0, 0, At, B0); PG8_MMA(0, 1, At, B1); PG8_BAR; PG8_SCHED;
	s_waitcnt lgkmcnt(0)
	v_mfma_f32_16x16x32_bf16 v[138:141], v[2:5], v[62:65], 0
	v_mfma_f32_16x16x32_bf16 v[146:149], v[2:5], v[106:109], 0
	v_mfma_f32_16x16x32_bf16 v[156:159], v[2:5], v[114:117], 0
	v_mfma_f32_16x16x32_bf16 v[2:5], v[2:5], v[122:125], 0
	v_mfma_f32_16x16x32_bf16 v[138:141], v[6:9], v[102:105], v[138:141]
	v_mfma_f32_16x16x32_bf16 v[146:149], v[6:9], v[110:113], v[146:149]
	v_mfma_f32_16x16x32_bf16 v[156:159], v[6:9], v[118:121], v[156:159]
	v_mfma_f32_16x16x32_bf16 v[2:5], v[6:9], v[126:129], v[2:5]
	v_mfma_f32_16x16x32_bf16 v[6:9], v[10:13], v[122:125], 0
	v_mfma_f32_16x16x32_bf16 v[142:145], v[10:13], v[62:65], 0
	v_mfma_f32_16x16x32_bf16 v[150:153], v[10:13], v[106:109], 0
	v_mfma_f32_16x16x32_bf16 v[180:183], v[10:13], v[114:117], 0
	v_mfma_f32_16x16x32_bf16 v[6:9], v[14:17], v[126:129], v[6:9]
	v_mfma_f32_16x16x32_bf16 v[142:145], v[14:17], v[102:105], v[142:145]
	v_mfma_f32_16x16x32_bf16 v[150:153], v[14:17], v[110:113], v[150:153]
	v_mfma_f32_16x16x32_bf16 v[180:183], v[14:17], v[118:121], v[180:183]
	v_mfma_f32_16x16x32_bf16 v[10:13], v[18:21], v[62:65], 0
	v_mfma_f32_16x16x32_bf16 v[14:17], v[26:29], v[62:65], 0
	v_mfma_f32_16x16x32_bf16 v[10:13], v[22:25], v[102:105], v[10:13]
	v_mfma_f32_16x16x32_bf16 v[14:17], v[30:33], v[102:105], v[14:17]
	v_mfma_f32_16x16x32_bf16 v[62:65], v[18:21], v[106:109], 0
	v_mfma_f32_16x16x32_bf16 v[102:105], v[26:29], v[106:109], 0
	v_mfma_f32_16x16x32_bf16 v[106:109], v[18:21], v[114:117], 0
	v_mfma_f32_16x16x32_bf16 v[18:21], v[18:21], v[122:125], 0
	v_mfma_f32_16x16x32_bf16 v[62:65], v[22:25], v[110:113], v[62:65]
	v_mfma_f32_16x16x32_bf16 v[102:105], v[30:33], v[110:113], v[102:105]
	v_mfma_f32_16x16x32_bf16 v[106:109], v[22:25], v[118:121], v[106:109]
	v_mfma_f32_16x16x32_bf16 v[110:113], v[26:29], v[114:117], 0
	v_mfma_f32_16x16x32_bf16 v[18:21], v[22:25], v[126:129], v[18:21]
	v_mfma_f32_16x16x32_bf16 v[22:25], v[26:29], v[122:125], 0
	v_mfma_f32_16x16x32_bf16 v[110:113], v[30:33], v[118:121], v[110:113]
	v_mfma_f32_16x16x32_bf16 v[22:25], v[30:33], v[126:129], v[22:25]
	s_barrier
	s_add_i32 s44, 0, 0x18000
	s_add_i32 s50, 0, 0x1c000
	v_add_u32_e32 v228, s44, v136
	v_add_u32_e32 v236, s50, v136
	ds_read_b128 v[26:29], v228
	ds_read_b128 v[30:33], v228 offset:1024
	ds_read_b128 v[114:117], v228 offset:2048
	ds_read_b128 v[118:121], v228 offset:3072
	ds_read_b128 v[122:125], v236
	ds_read_b128 v[126:129], v236 offset:1024
	ds_read_b128 v[184:187], v236 offset:2048
	ds_read_b128 v[188:191], v236 offset:3072
	s_add_u32 s46, s20, 0x10100
	s_addc_u32 s47, s21, 0
	s_mov_b32 m0, s36
	v_lshl_add_u64 v[224:225], s[46:47], 0, v[130:131]
	ds_read_b128 v[192:195], v137 offset:32768
	ds_read_b128 v[196:199], v137 offset:33792
	ds_read_b128 v[200:203], v137 offset:34816
	ds_read_b128 v[204:207], v137 offset:35840
	ds_read_b128 v[208:211], v137 offset:36864
	ds_read_b128 v[212:215], v137 offset:37888
	ds_read_b128 v[216:219], v137 offset:38912
	ds_read_b128 v[220:223], v137 offset:39936
	global_load_lds_dwordx4 v[224:225], off
	v_lshl_add_u64 v[224:225], s[46:47], 0, v[132:133]
	s_mov_b32 m0, s37
	s_nop 0
	global_load_lds_dwordx4 v[224:225], off
	s_waitcnt vmcnt(8)
	s_waitcnt lgkmcnt(0)
	s_barrier
	s_waitcnt lgkmcnt(0)
	v_mfma_f32_16x16x32_bf16 v[66:69], v[26:29], v[192:195], v[66:69]
	v_mfma_f32_16x16x32_bf16 v[70:73], v[114:117], v[192:195], v[70:73]
	v_mfma_f32_16x16x32_bf16 v[74:77], v[26:29], v[200:203], v[74:77]
	v_mfma_f32_16x16x32_bf16 v[78:81], v[114:117], v[200:203], v[78:81]
	v_mfma_f32_16x16x32_bf16 v[82:85], v[26:29], v[208:211], v[82:85]
	v_mfma_f32_16x16x32_bf16 v[86:89], v[114:117], v[208:211], v[86:89]
	v_mfma_f32_16x16x32_bf16 v[90:93], v[26:29], v[216:219], v[90:93]
	v_mfma_f32_16x16x32_bf16 v[94:97], v[114:117], v[216:219], v[94:97]
	v_mfma_f32_16x16x32_bf16 v[66:69], v[30:33], v[196:199], v[66:69]
	v_mfma_f32_16x16x32_bf16 v[70:73], v[118:121], v[196:199], v[70:73]
	v_mfma_f32_16x16x32_bf16 v[74:77], v[30:33], v[204:207], v[74:77]
	v_mfma_f32_16x16x32_bf16 v[78:81], v[118:121], v[204:207], v[78:81]
	v_mfma_f32_16x16x32_bf16 v[82:85], v[30:33], v[212:215], v[82:85]
	v_mfma_f32_16x16x32_bf16 v[86:89], v[118:121], v[212:215], v[86:89]
	v_mfma_f32_16x16x32_bf16 v[90:93], v[30:33], v[220:223], v[90:93]
	v_mfma_f32_16x16x32_bf16 v[94:97], v[118:121], v[220:223], v[94:97]
	v_mfma_f32_16x16x32_bf16 v[98:101], v[122:125], v[192:195], v[98:101]
	v_mfma_f32_16x16x32_bf16 v[34:37], v[184:187], v[192:195], v[34:37]
	v_mfma_f32_16x16x32_bf16 v[38:41], v[122:125], v[200:203], v[38:41]
	v_mfma_f32_16x16x32_bf16 v[42:45], v[184:187], v[200:203], v[42:45]
	v_mfma_f32_16x16x32_bf16 v[46:49], v[122:125], v[208:211], v[46:49]
	v_mfma_f32_16x16x32_bf16 v[50:53], v[184:187], v[208:211], v[50:53]
	v_mfma_f32_16x16x32_bf16 v[54:57], v[122:125], v[216:219], v[54:57]
	v_mfma_f32_16x16x32_bf16 v[58:61], v[184:187], v[216:219], v[58:61]
	v_mfma_f32_16x16x32_bf16 v[98:101], v[126:129], v[196:199], v[98:101]
	v_mfma_f32_16x16x32_bf16 v[34:37], v[188:191], v[196:199], v[34:37]
	v_mfma_f32_16x16x32_bf16 v[38:41], v[126:129], v[204:207], v[38:41]
	v_mfma_f32_16x16x32_bf16 v[42:45], v[188:191], v[204:207], v[42:45]
	v_mfma_f32_16x16x32_bf16 v[46:49], v[126:129], v[212:215], v[46:49]
	v_mfma_f32_16x16x32_bf16 v[50:53], v[188:191], v[212:215], v[50:53]
	v_mfma_f32_16x16x32_bf16 v[54:57], v[126:129], v[220:223], v[54:57]
	v_mfma_f32_16x16x32_bf16 v[58:61], v[188:191], v[220:223], v[58:61]
	s_barrier
; #define PG8_STAGE(bufoff, gbase, voff) do { _Pragma("unroll") for (int _i = 0; _i < 2; ++_i) \
;         __builtin_amdgcn_global_load_lds((const unsigned*)((const char*)(gbase) + (voff)[_i]), (LAS unsigned*)(lds + (bufoff) + ldsw + _i * 8192), 16, 0, 0); } while (0)
; #define PG8_LDA(dst, b, h) do { _Pragma("unroll") for (int m = 0; m < 4; ++m) _Pragma("unroll") for (int k = 0; k < 2; ++k) dst[m][k] = *(const LAS bf16x8*)(lds + PG8_SA(b, h) + aoff + m * 2048 + k * 1024); } while (0)
; #define PG8_LDB(dst, b, h) do { _Pragma("unroll") for (int n = 0; n < 2; ++n) _Pragma("unroll") for (int k = 0; k < 2; ++k) dst[n][k] = *(const LAS bf16x8*)(lds + PG8_SB(b, h) + boff + n * 2048 + k * 1024); } while (0)
; #define PG8_MMA(ai, bj, At, Bt) do { __builtin_amdgcn_s_setprio(1); _Pragma("unroll") for (int m = 0; m < 4; ++m) _Pragma("unroll") for (int n = 0; n < 2; ++n) _Pragma("unroll") for (int k = 0; k < 2; ++k) \
;         acc[ai][bj][m][n] = __builtin_amdgcn_mfma_f32_16x16x32_bf16(Bt[n][k], At[m][k], acc[ai][bj][m][n], 0, 0, 0); __builtin_amdgcn_s_setprio(0); } while (0)
; #define PG8_WAIT_V(n) asm volatile("s_waitcnt vmcnt(" #n ")" ::: "memory")
; #define PG8_BAR __builtin_amdgcn_s_barrier()
; template <class Epi, bool ALIGN_EPI>
; __device__ __forceinline__ void gemm_phase(LAS unsigned char* lds, const Gemm g, const StaticOrder& S, const Epi& E) {
;     ...
;             PG8_LDB(B0, 0, 0); PG8_LDB(B1, 0, 1); PG8_SCHED; PG8_LDA(At, 0, 0); PG8_STAGE(PG8_SA(1, 1), a1 + hstepA, voffA);
;             PG8_WAIT_V(8); PG8_WAIT_L(0); PG8_BAR; PG8_MMA(0, 0, At, B0); PG8_MMA(0, 1, At, B1); PG8_BAR; PG8_SCHED;
;             PG8_LDA(At, 0, 1); PG8_STAGE(PG8_SB(0, 0), b2, voffB); PG8_STAGE(PG8_SB(0, 1), b2 + hstepB, voffB); PG8_STAGE(PG8_SA(0, 0), a2, voffA);
;             PG8_WAIT_V(8); PG8_WAIT_L(0); PG8_BAR; PG8_MMA(1, 0, At, B0); PG8_MMA(1, 1, At, B1); PG8_BAR; PG8_SCHED;
;             PG8_LDB(B0, 1, 0); PG8_LDB(B1, 1, 1); PG8_SCHED; PG8_LDA(At, 1, 0); PG8_STAGE(PG8_SA(0, 1), a2 + hstepA, voffA);
;             PG8_WAIT_V(8); PG8_WAIT_L(0); PG8_BAR; PG8_MMA(0, 0, At, B0); PG8_MMA(0, 1, At, B1); PG8_BAR; PG8_SCHED;
;             PG8_LDA(At, 1, 1); PG8_STAGE(PG8_SB(1, 0), b3, voffB); PG8_STAGE(PG8_SB(1, 1), b3 + hstepB, voffB); PG8_STAGE(PG8_SA(1, 0), a3, voffA);
;             PG8_WAIT_V(8); PG8_WAIT_L(0); PG8_BAR; PG8_MMA(1, 0, At, B0); PG8_MMA(1, 1, At, B1); PG8_BAR; PG8_SCHED;
	s_add_i32 s46, s44, s31
	s_mov_b64 s[52:53], 0x180
	s_add_i32 s44, s46, 0x2000
	v_lshl_add_u64 v[160:161], v[160:161], 0, s[52:53]
	s_mov_b32 m0, s46
	s_add_u32 s48, s22, 0x10180
	ds_read_b128 v[192:195], v137 offset:49152
	ds_read_b128 v[196:199], v137 offset:50176
	ds_read_b128 v[200:203], v137 offset:51200
	ds_read_b128 v[204:207], v137 offset:52224
	ds_read_b128 v[208:211], v137 offset:53248
	ds_read_b128 v[212:215], v137 offset:54272
	ds_read_b128 v[216:219], v137 offset:55296
	ds_read_b128 v[220:223], v137 offset:56320
	global_load_lds_dwordx4 v[160:161], off
	v_lshl_add_u64 v[160:161], v[162:163], 0, s[52:53]
	s_mov_b32 m0, s44
	s_addc_u32 s49, s23, 0
	s_add_i32 s22, s50, s31
	global_load_lds_dwordx4 v[160:161], off
	v_lshl_add_u64 v[160:161], s[48:49], 0, v[0:1]
	s_mov_b32 m0, s22
	s_add_i32 s23, s22, 0x2000
	global_load_lds_dwordx4 v[160:161], off
	v_lshl_add_u64 v[160:161], s[48:49], 0, v[134:135]
	s_mov_b32 m0, s23
	s_nop 0
	global_load_lds_dwordx4 v[160:161], off
	v_lshl_add_u64 v[160:161], v[170:171], 0, s[52:53]
	s_mov_b32 m0, s38
	s_nop 0
	global_load_lds_dwordx4 v[160:161], off
	v_lshl_add_u64 v[160:161], v[172:173], 0, s[52:53]
	s_mov_b32 m0, s39
	s_nop 0
	global_load_lds_dwordx4 v[160:161], off
	s_waitcnt vmcnt(8)
	s_waitcnt lgkmcnt(0)
	s_barrier
	s_waitcnt lgkmcnt(0)
	v_mfma_f32_16x16x32_bf16 v[2:5], v[26:29], v[216:219], v[2:5]
	v_mfma_f32_16x16x32_bf16 v[6:9], v[114:117], v[216:219], v[6:9]
	v_mfma_f32_16x16x32_bf16 v[138:141], v[26:29], v[192:195], v[138:141]
	v_mfma_f32_16x16x32_bf16 v[142:145], v[114:117], v[192:195], v[142:145]
	v_mfma_f32_16x16x32_bf16 v[146:149], v[26:29], v[200:203], v[146:149]
	v_mfma_f32_16x16x32_bf16 v[150:153], v[114:117], v[200:203], v[150:153]
	v_mfma_f32_16x16x32_bf16 v[156:159], v[26:29], v[208:211], v[156:159]
	v_mfma_f32_16x16x32_bf16 v[180:183], v[114:117], v[208:211], v[180:183]
	v_mfma_f32_16x16x32_bf16 v[2:5], v[30:33], v[220:223], v[2:5]
	v_mfma_f32_16x16x32_bf16 v[6:9], v[118:121], v[220:223], v[6:9]
	v_mfma_f32_16x16x32_bf16 v[138:141], v[30:33], v[196:199], v[138:141]
	v_mfma_f32_16x16x32_bf16 v[142:145], v[118:121], v[196:199], v[142:145]
	v_mfma_f32_16x16x32_bf16 v[146:149], v[30:33], v[204:207], v[146:149]
	v_mfma_f32_16x16x32_bf16 v[150:153], v[118:121], v[204:207], v[150:153]
	v_mfma_f32_16x16x32_bf16 v[156:159], v[30:33], v[212:215], v[156:159]
	v_mfma_f32_16x16x32_bf16 v[180:183], v[118:121], v[212:215], v[180:183]
	v_mfma_f32_16x16x32_bf16 v[10:13], v[122:125], v[192:195], v[10:13]
	v_mfma_f32_16x16x32_bf16 v[14:17], v[184:187], v[192:195], v[14:17]
	v_mfma_f32_16x16x32_bf16 v[26:29], v[122:125], v[200:203], v[62:65]
	v_mfma_f32_16x16x32_bf16 v[30:33], v[184:187], v[200:203], v[102:105]
	v_mfma_f32_16x16x32_bf16 v[62:65], v[122:125], v[208:211], v[106:109]
	v_mfma_f32_16x16x32_bf16 v[102:105], v[184:187], v[208:211], v[110:113]
	v_mfma_f32_16x16x32_bf16 v[18:21], v[122:125], v[216:219], v[18:21]
	v_mfma_f32_16x16x32_bf16 v[22:25], v[184:187], v[216:219], v[22:25]
	v_mfma_f32_16x16x32_bf16 v[10:13], v[126:129], v[196:199], v[10:13]
	v_mfma_f32_16x16x32_bf16 v[14:17], v[188:191], v[196:199], v[14:17]
	v_mfma_f32_16x16x32_bf16 v[26:29], v[126:129], v[204:207], v[26:29]
	v_mfma_f32_16x16x32_bf16 v[30:33], v[188:191], v[204:207], v[30:33]
	v_mfma_f32_16x16x32_bf16 v[62:65], v[126:129], v[212:215], v[62:65]
	v_mfma_f32_16x16x32_bf16 v[102:105], v[188:191], v[212:215], v[102:105]
	v_mfma_f32_16x16x32_bf16 v[18:21], v[126:129], v[220:223], v[18:21]
	v_mfma_f32_16x16x32_bf16 v[22:25], v[188:191], v[220:223], v[22:25]
	s_barrier
	ds_read_b128 v[106:109], v164
	ds_read_b128 v[110:113], v164 offset:1024
	ds_read_b128 v[114:117], v164 offset:2048
	ds_read_b128 v[118:121], v164 offset:3072
	ds_read_b128 v[122:125], v165
	ds_read_b128 v[126:129], v165 offset:1024
	ds_read_b128 v[184:187], v165 offset:2048
	ds_read_b128 v[188:191], v165 offset:3072
	s_add_u32 s20, s20, 0x10180
	s_addc_u32 s21, s21, 0
	s_mov_b32 m0, s45
	v_lshl_add_u64 v[160:161], s[20:21], 0, v[130:131]
	ds_read_b128 v[192:195], v137
	ds_read_b128 v[196:199], v137 offset:1024
	ds_read_b128 v[200:203], v137 offset:2048
	ds_read_b128 v[204:207], v137 offset:3072
	ds_read_b128 v[208:211], v137 offset:4096
	ds_read_b128 v[212:215], v137 offset:5120
	ds_read_b128 v[216:219], v137 offset:6144
	ds_read_b128 v[220:223], v137 offset:7168
	global_load_lds_dwordx4 v[160:161], off
	v_lshl_add_u64 v[160:161], s[20:21], 0, v[132:133]
	s_mov_b32 m0, s9
	s_nop 0
	global_load_lds_dwordx4 v[160:161], off
	s_waitcnt vmcnt(8)
	s_waitcnt lgkmcnt(0)
	s_barrier
; #define PG8_STAGE(bufoff, gbase, voff) do { _Pragma("unroll") for (int _i = 0; _i < 2; ++_i) \
;         __builtin_amdgcn_global_load_lds((const unsigned*)((const char*)(gbase) + (voff)[_i]), (LAS unsigned*)(lds + (bufoff) + ldsw + _i * 8192), 16, 0, 0); } while (0)
; #define PG8_LDA(dst, b, h) do { _Pragma("unroll") for (int m = 0; m < 4; ++m) _Pragma("unroll") for (int k = 0; k < 2; ++k) dst[m][k] = *(const LAS bf16x8*)(lds + PG8_SA(b, h) + aoff + m * 2048 + k * 1024); } while (0)
; #define PG8_MMA(ai, bj, At, Bt) do { __builtin_amdgcn_s_setprio(1); _Pragma("unroll") for (int m = 0; m < 4; ++m) _Pragma("unroll") for (int n = 0; n < 2; ++n) _Pragma("unroll") for (int k = 0; k < 2; ++k) \
;         acc[ai][bj][m][n] = __builtin_amdgcn_mfma_f32_16x16x32_bf16(Bt[n][k], At[m][k], acc[ai][bj][m][n], 0, 0, 0); __builtin_amdgcn_s_setprio(0); } while (0)
; #define PG8_WAIT_V(n) asm volatile("s_waitcnt vmcnt(" #n ")" ::: "memory")
; #define PG8_WAIT_L(n) asm volatile("s_waitcnt lgkmcnt(" #n ")" ::: "memory")
; #define PG8_BAR __builtin_amdgcn_s_barrier()
; #define PG8_SCHED __builtin_amdgcn_sched_barrier(0)
; template <class Epi, bool ALIGN_EPI>
; __device__ __forceinline__ void gemm_phase(LAS unsigned char* lds, const Gemm g, const StaticOrder& S, const Epi& E) {
;     ...
;             PG8_WAIT_V(8); PG8_WAIT_L(0); PG8_BAR; PG8_MMA(0, 0, At, B0); PG8_MMA(0, 1, At, B1); PG8_BAR; PG8_SCHED;
;             PG8_LDA(At, 0, 1); PG8_STAGE(PG8_SB(0, 0), b2, voffB); PG8_STAGE(PG8_SB(0, 1), b2 + hstepB, voffB); PG8_STAGE(PG8_SA(0, 0), a2, voffA);
;             PG8_WAIT_V(8); PG8_WAIT_L(0); PG8_BAR; PG8_MMA(1, 0, At, B0); PG8_MMA(1, 1, At, B1); PG8_BAR; PG8_SCHED;
	s_waitcnt lgkmcnt(0)
	v_mfma_f32_16x16x32_bf16 v[66:69], v[106:109], v[192:195], v[66:69]
	v_mfma_f32_16x16x32_bf16 v[70:73], v[114:117], v[192:195], v[70:73]
	v_mfma_f32_16x16x32_bf16 v[74:77], v[106:109], v[200:203], v[74:77]
	v_mfma_f32_16x16x32_bf16 v[78:81], v[114:117], v[200:203], v[78:81]
	v_mfma_f32_16x16x32_bf16 v[82:85], v[106:109], v[208:211], v[82:85]
	v_mfma_f32_16x16x32_bf16 v[86:89], v[114:117], v[208:211], v[86:89]
	v_mfma_f32_16x16x32_bf16 v[90:93], v[106:109], v[216:219], v[90:93]
	v_mfma_f32_16x16x32_bf16 v[94:97], v[114:117], v[216:219], v[94:97]
	v_mfma_f32_16x16x32_bf16 v[66:69], v[110:113], v[196:199], v[66:69]
	v_mfma_f32_16x16x32_bf16 v[70:73], v[118:121], v[196:199], v[70:73]
	v_mfma_f32_16x16x32_bf16 v[74:77], v[110:113], v[204:207], v[74:77]
	v_mfma_f32_16x16x32_bf16 v[78:81], v[118:121], v[204:207], v[78:81]
	v_mfma_f32_16x16x32_bf16 v[82:85], v[110:113], v[212:215], v[82:85]
	v_mfma_f32_16x16x32_bf16 v[86:89], v[118:121], v[212:215], v[86:89]
	v_mfma_f32_16x16x32_bf16 v[90:93], v[110:113], v[220:223], v[90:93]
	v_mfma_f32_16x16x32_bf16 v[94:97], v[118:121], v[220:223], v[94:97]
	v_mfma_f32_16x16x32_bf16 v[34:37], v[184:187], v[192:195], v[34:37]
	v_mfma_f32_16x16x32_bf16 v[98:101], v[122:125], v[192:195], v[98:101]
	v_mfma_f32_16x16x32_bf16 v[192:195], v[188:191], v[196:199], v[34:37]
	v_mfma_f32_16x16x32_bf16 v[34:37], v[122:125], v[200:203], v[38:41]
	v_mfma_f32_16x16x32_bf16 v[224:227], v[126:129], v[196:199], v[98:101]
	v_mfma_f32_16x16x32_bf16 v[196:199], v[126:129], v[204:207], v[34:37]
	v_mfma_f32_16x16x32_bf16 v[34:37], v[184:187], v[200:203], v[42:45]
	v_mfma_f32_16x16x32_bf16 v[42:45], v[188:191], v[204:207], v[34:37]
	v_mfma_f32_16x16x32_bf16 v[34:37], v[122:125], v[208:211], v[46:49]
	v_mfma_f32_16x16x32_bf16 v[46:49], v[126:129], v[212:215], v[34:37]
	v_mfma_f32_16x16x32_bf16 v[34:37], v[184:187], v[208:211], v[50:53]
	v_mfma_f32_16x16x32_bf16 v[50:53], v[188:191], v[212:215], v[34:37]
	v_mfma_f32_16x16x32_bf16 v[34:37], v[122:125], v[216:219], v[54:57]
	v_mfma_f32_16x16x32_bf16 v[54:57], v[126:129], v[220:223], v[34:37]
	v_mfma_f32_16x16x32_bf16 v[34:37], v[184:187], v[216:219], v[58:61]
	v_mfma_f32_16x16x32_bf16 v[58:61], v[188:191], v[220:223], v[34:37]
	s_barrier
	s_mov_b32 m0, s43
	v_lshl_add_u64 v[164:165], s[24:25], 0, v[0:1]
	s_add_u32 s20, s24, 0x10000
	s_nop 1
	ds_read_b128 v[34:37], v137 offset:16384
	ds_read_b128 v[38:41], v137 offset:17408
	ds_read_b128 v[98:101], v137 offset:18432
	ds_read_b128 v[200:203], v137 offset:19456
	ds_read_b128 v[204:207], v137 offset:20480
	ds_read_b128 v[208:211], v137 offset:21504
	ds_read_b128 v[212:215], v137 offset:22528
	ds_read_b128 v[216:219], v137 offset:23552
	global_load_lds_dwordx4 v[164:165], off
	v_lshl_add_u64 v[252:253], s[24:25], 0, v[134:135]
	s_mov_b32 m0, s11
	s_addc_u32 s21, s25, 0
	global_load_lds_dwordx4 v[252:253], off
	v_lshl_add_u64 v[160:161], s[20:21], 0, v[0:1]
	s_mov_b32 m0, s41
	v_lshl_add_u64 v[174:175], s[26:27], 0, v[130:131]
	global_load_lds_dwordx4 v[160:161], off
	v_lshl_add_u64 v[160:161], s[20:21], 0, v[134:135]
	s_mov_b32 m0, s42
	v_lshl_add_u64 v[168:169], s[26:27], 0, v[132:133]
	global_load_lds_dwordx4 v[160:161], off
	s_mov_b32 m0, s34
	s_nop 0
	global_load_lds_dwordx4 v[174:175], off
	s_mov_b32 m0, s35
	s_nop 0
	global_load_lds_dwordx4 v[168:169], off
	s_waitcnt vmcnt(8)
	s_waitcnt lgkmcnt(0)
	s_barrier
	s_waitcnt lgkmcnt(0)
	v_mfma_f32_16x16x32_bf16 v[2:5], v[106:109], v[212:215], v[2:5]
	v_mfma_f32_16x16x32_bf16 v[6:9], v[114:117], v[212:215], v[6:9]
	v_mfma_f32_16x16x32_bf16 v[138:141], v[106:109], v[34:37], v[138:141]
	v_mfma_f32_16x16x32_bf16 v[142:145], v[114:117], v[34:37], v[142:145]
	v_mfma_f32_16x16x32_bf16 v[146:149], v[106:109], v[98:101], v[146:149]
	v_mfma_f32_16x16x32_bf16 v[150:153], v[114:117], v[98:101], v[150:153]
	v_mfma_f32_16x16x32_bf16 v[156:159], v[106:109], v[204:207], v[156:159]
	v_mfma_f32_16x16x32_bf16 v[180:183], v[114:117], v[204:207], v[180:183]
	v_mfma_f32_16x16x32_bf16 v[2:5], v[110:113], v[216:219], v[2:5]
	v_mfma_f32_16x16x32_bf16 v[6:9], v[118:121], v[216:219], v[6:9]
	v_mfma_f32_16x16x32_bf16 v[138:141], v[110:113], v[38:41], v[138:141]
	v_mfma_f32_16x16x32_bf16 v[142:145], v[118:121], v[38:41], v[142:145]
	v_mfma_f32_16x16x32_bf16 v[146:149], v[110:113], v[200:203], v[146:149]
	v_mfma_f32_16x16x32_bf16 v[150:153], v[118:121], v[200:203], v[150:153]
	v_mfma_f32_16x16x32_bf16 v[156:159], v[110:113], v[208:211], v[156:159]
	v_mfma_f32_16x16x32_bf16 v[180:183], v[118:121], v[208:211], v[180:183]
	v_mfma_f32_16x16x32_bf16 v[10:13], v[122:125], v[34:37], v[10:13]
	v_mfma_f32_16x16x32_bf16 v[14:17], v[184:187], v[34:37], v[14:17]
	v_mfma_f32_16x16x32_bf16 v[26:29], v[122:125], v[98:101], v[26:29]
	v_mfma_f32_16x16x32_bf16 v[30:33], v[184:187], v[98:101], v[30:33]
	v_mfma_f32_16x16x32_bf16 v[34:37], v[122:125], v[204:207], v[62:65]
	v_mfma_f32_16x16x32_bf16 v[26:29], v[126:129], v[200:203], v[26:29]
	v_mfma_f32_16x16x32_bf16 v[30:33], v[188:191], v[200:203], v[30:33]
	v_mfma_f32_16x16x32_bf16 v[200:203], v[126:129], v[208:211], v[34:37]
	v_mfma_f32_16x16x32_bf16 v[34:37], v[184:187], v[204:207], v[102:105]
	v_mfma_f32_16x16x32_bf16 v[18:21], v[122:125], v[212:215], v[18:21]
	v_mfma_f32_16x16x32_bf16 v[10:13], v[126:129], v[38:41], v[10:13]
	v_mfma_f32_16x16x32_bf16 v[14:17], v[188:191], v[38:41], v[14:17]
	v_mfma_f32_16x16x32_bf16 v[204:207], v[188:191], v[208:211], v[34:37]
	v_mfma_f32_16x16x32_bf16 v[208:211], v[126:129], v[216:219], v[18:21]
	v_mfma_f32_16x16x32_bf16 v[18:21], v[184:187], v[212:215], v[22:25]
	v_mfma_f32_16x16x32_bf16 v[184:187], v[188:191], v[216:219], v[18:21]
	s_barrier
; #define PG8_STAGE(bufoff, gbase, voff) do { _Pragma("unroll") for (int _i = 0; _i < 2; ++_i) \
;         __builtin_amdgcn_global_load_lds((const unsigned*)((const char*)(gbase) + (voff)[_i]), (LAS unsigned*)(lds + (bufoff) + ldsw + _i * 8192), 16, 0, 0); } while (0)
; #define PG8_LDA(dst, b, h) do { _Pragma("unroll") for (int m = 0; m < 4; ++m) _Pragma("unroll") for (int k = 0; k < 2; ++k) dst[m][k] = *(const LAS bf16x8*)(lds + PG8_SA(b, h) + aoff + m * 2048 + k * 1024); } while (0)
; #define PG8_LDB(dst, b, h) do { _Pragma("unroll") for (int n = 0; n < 2; ++n) _Pragma("unroll") for (int k = 0; k < 2; ++k) dst[n][k] = *(const LAS bf16x8*)(lds + PG8_SB(b, h) + boff + n * 2048 + k * 1024); } while (0)
; #define PG8_MMA(ai, bj, At, Bt) do { __builtin_amdgcn_s_setprio(1); _Pragma("unroll") for (int m = 0; m < 4; ++m) _Pragma("unroll") for (int n = 0; n < 2; ++n) _Pragma("unroll") for (int k = 0; k < 2; ++k) \
;         acc[ai][bj][m][n] = __builtin_amdgcn_mfma_f32_16x16x32_bf16(Bt[n][k], At[m][k], acc[ai][bj][m][n], 0, 0, 0); __builtin_amdgcn_s_setprio(0); } while (0)
; #define PG8_WAIT_V(n) asm volatile("s_waitcnt vmcnt(" #n ")" ::: "memory")
; #define PG8_WAIT_L(n) asm volatile("s_waitcnt lgkmcnt(" #n ")" ::: "memory")
; #define PG8_BAR __builtin_amdgcn_s_barrier()
; #define PG8_SCHED __builtin_amdgcn_sched_barrier(0)
; template <class Epi, bool ALIGN_EPI>
; __device__ __forceinline__ void gemm_phase(LAS unsigned char* lds, const Gemm g, const StaticOrder& S, const Epi& E) {
;     ...
;             PG8_LDB(B0, 1, 0); PG8_LDB(B1, 1, 1); PG8_SCHED; PG8_LDA(At, 1, 0); PG8_STAGE(PG8_SA(0, 1), a2 + hstepA, voffA);
;             PG8_WAIT_V(8); PG8_WAIT_L(0); PG8_BAR; PG8_MMA(0, 0, At, B0); PG8_MMA(0, 1, At, B1); PG8_BAR; PG8_SCHED;
;             PG8_LDA(At, 1, 1); PG8_STAGE(PG8_SB(1, 0), b3, voffB); PG8_STAGE(PG8_SB(1, 1), b3 + hstepB, voffB); PG8_STAGE(PG8_SA(1, 0), a3, voffA);
;             PG8_WAIT_V(8); PG8_WAIT_L(0); PG8_BAR; PG8_MMA(1, 0, At, B0); PG8_MMA(1, 1, At, B1); PG8_BAR; PG8_SCHED;
;         }
;         if constexpr (ALIGN_EPI) { if (wr == 0) PG8_BAR; }
	ds_read_b128 v[62:65], v228
	ds_read_b128 v[188:191], v228 offset:1024
	ds_read_b128 v[212:215], v228 offset:2048
	ds_read_b128 v[216:219], v228 offset:3072
	ds_read_b128 v[220:223], v236
	ds_read_b128 v[228:231], v236 offset:1024
	ds_read_b128 v[232:235], v236 offset:2048
	ds_read_b128 v[236:239], v236 offset:3072
	s_add_u32 s20, s26, 0x10000
	s_addc_u32 s21, s27, 0
	s_mov_b32 m0, s36
	v_lshl_add_u64 v[34:35], s[20:21], 0, v[130:131]
	ds_read_b128 v[18:21], v137 offset:32768
	ds_read_b128 v[22:25], v137 offset:33792
	ds_read_b128 v[110:113], v137 offset:34816
	ds_read_b128 v[240:243], v137 offset:35840
	ds_read_b128 v[244:247], v137 offset:36864
	ds_read_b128 v[248:251], v137 offset:37888
	ds_read_b128 v[160:163], v137 offset:38912
	ds_read_b128 v[170:173], v137 offset:39936
	global_load_lds_dwordx4 v[34:35], off
	v_lshl_add_u64 v[34:35], s[20:21], 0, v[132:133]
	s_mov_b32 m0, s37
	s_nop 0
	global_load_lds_dwordx4 v[34:35], off
	s_waitcnt vmcnt(8)
	s_waitcnt lgkmcnt(0)
	s_barrier
	s_waitcnt lgkmcnt(0)
	v_mfma_f32_16x16x32_bf16 v[34:37], v[62:65], v[18:21], v[66:69]
	v_mfma_f32_16x16x32_bf16 v[114:117], v[188:191], v[22:25], v[34:37]
	v_mfma_f32_16x16x32_bf16 v[34:37], v[212:215], v[18:21], v[70:73]
	v_mfma_f32_16x16x32_bf16 v[118:121], v[216:219], v[22:25], v[34:37]
	v_mfma_f32_16x16x32_bf16 v[34:37], v[62:65], v[110:113], v[74:77]
	v_mfma_f32_16x16x32_bf16 v[98:101], v[188:191], v[240:243], v[34:37]
	v_mfma_f32_16x16x32_bf16 v[34:37], v[212:215], v[110:113], v[78:81]
	v_mfma_f32_16x16x32_bf16 v[102:105], v[216:219], v[240:243], v[34:37]
	v_mfma_f32_16x16x32_bf16 v[34:37], v[62:65], v[244:247], v[82:85]
	v_mfma_f32_16x16x32_bf16 v[66:69], v[188:191], v[248:251], v[34:37]
	v_mfma_f32_16x16x32_bf16 v[34:37], v[212:215], v[244:247], v[86:89]
	v_mfma_f32_16x16x32_bf16 v[70:73], v[216:219], v[248:251], v[34:37]
	v_mfma_f32_16x16x32_bf16 v[34:37], v[62:65], v[160:163], v[90:93]
	v_mfma_f32_16x16x32_bf16 v[38:41], v[212:215], v[160:163], v[94:97]
	v_mfma_f32_16x16x32_bf16 v[34:37], v[188:191], v[170:173], v[34:37]
	v_mfma_f32_16x16x32_bf16 v[38:41], v[216:219], v[170:173], v[38:41]
	v_mfma_f32_16x16x32_bf16 v[74:77], v[220:223], v[18:21], v[224:227]
	v_mfma_f32_16x16x32_bf16 v[18:21], v[232:235], v[18:21], v[192:195]
	v_mfma_f32_16x16x32_bf16 v[126:129], v[236:239], v[22:25], v[18:21]
	v_mfma_f32_16x16x32_bf16 v[18:21], v[220:223], v[110:113], v[196:199]
	v_mfma_f32_16x16x32_bf16 v[106:109], v[228:231], v[240:243], v[18:21]
	v_mfma_f32_16x16x32_bf16 v[18:21], v[232:235], v[110:113], v[42:45]
	v_mfma_f32_16x16x32_bf16 v[110:113], v[236:239], v[240:243], v[18:21]
	v_mfma_f32_16x16x32_bf16 v[18:21], v[220:223], v[244:247], v[46:49]
	v_mfma_f32_16x16x32_bf16 v[122:125], v[228:231], v[22:25], v[74:77]
	v_mfma_f32_16x16x32_bf16 v[74:77], v[228:231], v[248:251], v[18:21]
	v_mfma_f32_16x16x32_bf16 v[18:21], v[232:235], v[244:247], v[50:53]
	v_mfma_f32_16x16x32_bf16 v[78:81], v[236:239], v[248:251], v[18:21]
	v_mfma_f32_16x16x32_bf16 v[18:21], v[220:223], v[160:163], v[54:57]
	v_mfma_f32_16x16x32_bf16 v[42:45], v[228:231], v[170:173], v[18:21]
	v_mfma_f32_16x16x32_bf16 v[18:21], v[232:235], v[160:163], v[58:61]
	v_mfma_f32_16x16x32_bf16 v[46:49], v[236:239], v[170:173], v[18:21]
	s_barrier
	s_mov_b32 m0, s46
	s_nop 3
	v_lshl_add_u64 v[18:19], v[164:165], 0, s[94:95]
	s_add_u32 s20, s24, 0x10080
	ds_read_b128 v[58:61], v137 offset:49152
	ds_read_b128 v[94:97], v137 offset:50176
	ds_read_b128 v[160:163], v137 offset:51200
	ds_read_b128 v[170:173], v137 offset:52224
	ds_read_b128 v[192:195], v137 offset:53248
	ds_read_b128 v[196:199], v137 offset:54272
	ds_read_b128 v[224:227], v137 offset:55296
	ds_read_b128 v[240:243], v137 offset:56320
	global_load_lds_dwordx4 v[18:19], off
	v_lshl_add_u64 v[18:19], v[252:253], 0, s[94:95]
	s_mov_b32 m0, s44
	s_addc_u32 s21, s25, 0
	global_load_lds_dwordx4 v[18:19], off
	v_lshl_add_u64 v[18:19], s[20:21], 0, v[0:1]
	s_mov_b32 m0, s22
	s_nop 0
	global_load_lds_dwordx4 v[18:19], off
	v_lshl_add_u64 v[18:19], s[20:21], 0, v[134:135]
	s_mov_b32 m0, s23
	s_nop 0
	global_load_lds_dwordx4 v[18:19], off
	v_lshl_add_u64 v[18:19], v[174:175], 0, s[94:95]
	s_mov_b32 m0, s38
	s_nop 0
	global_load_lds_dwordx4 v[18:19], off
	v_lshl_add_u64 v[18:19], v[168:169], 0, s[94:95]
	s_mov_b32 m0, s39
	s_nop 0
	global_load_lds_dwordx4 v[18:19], off
	s_waitcnt vmcnt(8)
	s_waitcnt lgkmcnt(0)
	s_barrier
	s_waitcnt lgkmcnt(0)
	v_mfma_f32_16x16x32_bf16 v[18:21], v[62:65], v[58:61], v[138:141]
	v_mfma_f32_16x16x32_bf16 v[82:85], v[188:191], v[94:97], v[18:21]
	v_mfma_f32_16x16x32_bf16 v[18:21], v[212:215], v[58:61], v[142:145]
	v_mfma_f32_16x16x32_bf16 v[86:89], v[216:219], v[94:97], v[18:21]
	v_mfma_f32_16x16x32_bf16 v[18:21], v[62:65], v[160:163], v[146:149]
	v_mfma_f32_16x16x32_bf16 v[50:53], v[188:191], v[170:173], v[18:21]
	v_mfma_f32_16x16x32_bf16 v[18:21], v[212:215], v[160:163], v[150:153]
	v_mfma_f32_16x16x32_bf16 v[54:57], v[216:219], v[170:173], v[18:21]
	v_mfma_f32_16x16x32_bf16 v[18:21], v[62:65], v[192:195], v[156:159]
	v_mfma_f32_16x16x32_bf16 v[22:25], v[212:215], v[192:195], v[180:183]
	v_mfma_f32_16x16x32_bf16 v[2:5], v[62:65], v[224:227], v[2:5]
	v_mfma_f32_16x16x32_bf16 v[6:9], v[212:215], v[224:227], v[6:9]
	v_mfma_f32_16x16x32_bf16 v[18:21], v[188:191], v[196:199], v[18:21]
	v_mfma_f32_16x16x32_bf16 v[22:25], v[216:219], v[196:199], v[22:25]
	v_mfma_f32_16x16x32_bf16 v[2:5], v[188:191], v[240:243], v[2:5]
	v_mfma_f32_16x16x32_bf16 v[6:9], v[216:219], v[240:243], v[6:9]
	v_mfma_f32_16x16x32_bf16 v[10:13], v[220:223], v[58:61], v[10:13]
	v_mfma_f32_16x16x32_bf16 v[90:93], v[228:231], v[94:97], v[10:13]
	v_mfma_f32_16x16x32_bf16 v[10:13], v[232:235], v[58:61], v[14:17]
	v_mfma_f32_16x16x32_bf16 v[94:97], v[236:239], v[94:97], v[10:13]
	v_mfma_f32_16x16x32_bf16 v[10:13], v[220:223], v[160:163], v[26:29]
	v_mfma_f32_16x16x32_bf16 v[58:61], v[228:231], v[170:173], v[10:13]
	v_mfma_f32_16x16x32_bf16 v[10:13], v[232:235], v[160:163], v[30:33]
	v_mfma_f32_16x16x32_bf16 v[62:65], v[236:239], v[170:173], v[10:13]
	v_mfma_f32_16x16x32_bf16 v[10:13], v[220:223], v[192:195], v[200:203]
	v_mfma_f32_16x16x32_bf16 v[26:29], v[228:231], v[196:199], v[10:13]
	v_mfma_f32_16x16x32_bf16 v[10:13], v[232:235], v[192:195], v[204:207]
	v_mfma_f32_16x16x32_bf16 v[30:33], v[236:239], v[196:199], v[10:13]
	v_mfma_f32_16x16x32_bf16 v[10:13], v[220:223], v[224:227], v[208:211]
	v_mfma_f32_16x16x32_bf16 v[14:17], v[232:235], v[224:227], v[184:187]
	v_mfma_f32_16x16x32_bf16 v[10:13], v[228:231], v[240:243], v[10:13]
	v_mfma_f32_16x16x32_bf16 v[14:17], v[236:239], v[240:243], v[14:17]
	s_barrier
	s_andn2_b64 vcc, exec, s[2:3]
	s_cbranch_vccnz .LBB0_289
	s_barrier

; #define PG8_STAGE(bufoff, gbase, voff) do { _Pragma("unroll") for (int _i = 0; _i < 2; ++_i) \
;         __builtin_amdgcn_global_load_lds((const unsigned*)((const char*)(gbase) + (voff)[_i]), (LAS unsigned*)(lds + (bufoff) + ldsw + _i * 8192), 16, 0, 0); } while (0)
; #define PG8_LDA(dst, b, h) do { _Pragma("unroll") for (int m = 0; m < 4; ++m) _Pragma("unroll") for (int k = 0; k < 2; ++k) dst[m][k] = *(const LAS bf16x8*)(lds + PG8_SA(b, h) + aoff + m * 2048 + k * 1024); } while (0)
; #define PG8_LDB(dst, b, h) do { _Pragma("unroll") for (int n = 0; n < 2; ++n) _Pragma("unroll") for (int k = 0; k < 2; ++k) dst[n][k] = *(const LAS bf16x8*)(lds + PG8_SB(b, h) + boff + n * 2048 + k * 1024); } while (0)
; #define PG8_MMA(ai, bj, At, Bt) do { __builtin_amdgcn_s_setprio(1); _Pragma("unroll") for (int m = 0; m < 4; ++m) _Pragma("unroll") for (int n = 0; n < 2; ++n) _Pragma("unroll") for (int k = 0; k < 2; ++k) \
;         acc[ai][bj][m][n] = __builtin_amdgcn_mfma_f32_16x16x32_bf16(Bt[n][k], At[m][k], acc[ai][bj][m][n], 0, 0, 0); __builtin_amdgcn_s_setprio(0); } while (0)
; #define PG8_WAIT_V(n) asm volatile("s_waitcnt vmcnt(" #n ")" ::: "memory")
; #define PG8_WAIT_L(n) asm volatile("s_waitcnt lgkmcnt(" #n ")" ::: "memory")
; #define PG8_BAR __builtin_amdgcn_s_barrier()
; #define PG8_SCHED __builtin_amdgcn_sched_barrier(0)
; template <class Epi, bool ALIGN_EPI>
; __device__ __forceinline__ void gemm_phase(LAS unsigned char* lds, const Gemm g, const StaticOrder& S, const Epi& E) {
;     ...
;             const bool last = (t == nt - 2);
;             const char* a1 = cA + (size_t)(t + 1) * kstep;
;             const char* a2 = last ? nA : cA + (size_t)(t + 2) * kstep; const char* b2 = last ? nB : cB + (size_t)(t + 2) * kstep;
;             const char* a3 = a2 + kstep; const char* b3 = b2 + kstep;
;             PG8_LDB(B0, 0, 0); PG8_LDB(B1, 0, 1); PG8_SCHED; PG8_LDA(At, 0, 0); PG8_STAGE(PG8_SA(1, 1), a1 + hstepA, voffA);
;             PG8_WAIT_V(8); PG8_WAIT_L(0); PG8_BAR; PG8_MMA(0, 0, At, B0); PG8_MMA(0, 1, At, B1); PG8_BAR; PG8_SCHED;
;             PG8_LDA(At, 0, 1); PG8_STAGE(PG8_SB(0, 0), b2, voffB); PG8_STAGE(PG8_SB(0, 1), b2 + hstepB, voffB); PG8_STAGE(PG8_SA(0, 0), a2, voffA);
;             PG8_WAIT_V(8); PG8_WAIT_L(0); PG8_BAR; PG8_MMA(1, 0, At, B0); PG8_MMA(1, 1, At, B1); PG8_BAR; PG8_SCHED;
.LBB0_304:
	s_add_u32 s18, s6, 0xfffc0080
	s_addc_u32 s19, s7, -1
	s_add_i32 s41, 0, 0x10000
	s_cmp_eq_u32 s40, 12
	s_cselect_b32 s21, s1, s19
	s_cselect_b32 s20, s36, s18
	v_add_u32_e32 v152, s41, v144
	s_cselect_b32 s19, s11, s39
	s_cselect_b32 s18, s37, s38
	s_add_i32 s44, 0, 0x14000
	ds_read_b128 v[140:143], v152
	ds_read_b128 v[148:151], v152 offset:1024
	ds_read_b128 v[156:159], v152 offset:2048
	ds_read_b128 v[180:183], v152 offset:3072
	v_add_u32_e32 v152, s44, v144
	ds_read_b128 v[184:187], v152
	ds_read_b128 v[188:191], v152 offset:1024
	ds_read_b128 v[192:195], v152 offset:2048
	ds_read_b128 v[196:199], v152 offset:3072
	v_lshl_add_u64 v[152:153], s[6:7], 0, v[136:137]
	s_add_i32 m0, s25, 0xc000
	ds_read_b128 v[200:203], v146
	ds_read_b128 v[204:207], v146 offset:1024
	ds_read_b128 v[208:211], v146 offset:2048
	ds_read_b128 v[212:215], v146 offset:3072
	ds_read_b128 v[216:219], v146 offset:4096
	ds_read_b128 v[220:223], v146 offset:5120
	ds_read_b128 v[224:227], v146 offset:6144
	ds_read_b128 v[228:231], v146 offset:7168
	global_load_lds_dwordx4 v[152:153], off
	v_lshl_add_u64 v[152:153], s[6:7], 0, v[138:139]
	s_add_i32 m0, s25, 0xe000
	s_nop 0
	global_load_lds_dwordx4 v[152:153], off
	s_waitcnt vmcnt(8)
	s_waitcnt lgkmcnt(0)
	s_barrier
	s_waitcnt lgkmcnt(0)
	v_mfma_f32_16x16x32_bf16 v[126:129], v[140:143], v[200:203], v[126:129]
	v_mfma_f32_16x16x32_bf16 v[118:121], v[156:159], v[200:203], v[118:121]
	v_mfma_f32_16x16x32_bf16 v[110:113], v[140:143], v[208:211], v[110:113]
	v_mfma_f32_16x16x32_bf16 v[102:105], v[156:159], v[208:211], v[102:105]
	v_mfma_f32_16x16x32_bf16 v[94:97], v[140:143], v[216:219], v[94:97]
	v_mfma_f32_16x16x32_bf16 v[86:89], v[156:159], v[216:219], v[86:89]
	v_mfma_f32_16x16x32_bf16 v[78:81], v[140:143], v[224:227], v[78:81]
	v_mfma_f32_16x16x32_bf16 v[70:73], v[156:159], v[224:227], v[70:73]
	v_mfma_f32_16x16x32_bf16 v[126:129], v[148:151], v[204:207], v[126:129]
	v_mfma_f32_16x16x32_bf16 v[118:121], v[180:183], v[204:207], v[118:121]
	v_mfma_f32_16x16x32_bf16 v[110:113], v[148:151], v[212:215], v[110:113]
	v_mfma_f32_16x16x32_bf16 v[102:105], v[180:183], v[212:215], v[102:105]
	v_mfma_f32_16x16x32_bf16 v[94:97], v[148:151], v[220:223], v[94:97]
	v_mfma_f32_16x16x32_bf16 v[86:89], v[180:183], v[220:223], v[86:89]
	v_mfma_f32_16x16x32_bf16 v[78:81], v[148:151], v[228:231], v[78:81]
	v_mfma_f32_16x16x32_bf16 v[70:73], v[180:183], v[228:231], v[70:73]
	v_mfma_f32_16x16x32_bf16 v[122:125], v[184:187], v[200:203], v[122:125]
	v_mfma_f32_16x16x32_bf16 v[114:117], v[192:195], v[200:203], v[114:117]
	v_mfma_f32_16x16x32_bf16 v[106:109], v[184:187], v[208:211], v[106:109]
	v_mfma_f32_16x16x32_bf16 v[98:101], v[192:195], v[208:211], v[98:101]
	v_mfma_f32_16x16x32_bf16 v[90:93], v[184:187], v[216:219], v[90:93]
	v_mfma_f32_16x16x32_bf16 v[82:85], v[192:195], v[216:219], v[82:85]
	v_mfma_f32_16x16x32_bf16 v[74:77], v[184:187], v[224:227], v[74:77]
	v_mfma_f32_16x16x32_bf16 v[66:69], v[192:195], v[224:227], v[66:69]
	v_mfma_f32_16x16x32_bf16 v[122:125], v[188:191], v[204:207], v[122:125]
	v_mfma_f32_16x16x32_bf16 v[114:117], v[196:199], v[204:207], v[114:117]
	v_mfma_f32_16x16x32_bf16 v[106:109], v[188:191], v[212:215], v[106:109]
	v_mfma_f32_16x16x32_bf16 v[98:101], v[196:199], v[212:215], v[98:101]
	v_mfma_f32_16x16x32_bf16 v[90:93], v[188:191], v[220:223], v[90:93]
	v_mfma_f32_16x16x32_bf16 v[82:85], v[196:199], v[220:223], v[82:85]
	v_mfma_f32_16x16x32_bf16 v[74:77], v[188:191], v[228:231], v[74:77]
	v_mfma_f32_16x16x32_bf16 v[66:69], v[196:199], v[228:231], v[66:69]
	s_barrier
	s_add_i32 s41, s41, s24
	v_lshl_add_u64 v[152:153], s[18:19], 0, v[0:1]
	s_mov_b32 m0, s41
	ds_read_b128 v[200:203], v146 offset:16384
	ds_read_b128 v[204:207], v146 offset:17408
	ds_read_b128 v[208:211], v146 offset:18432
	ds_read_b128 v[212:215], v146 offset:19456
	ds_read_b128 v[216:219], v146 offset:20480
	ds_read_b128 v[220:223], v146 offset:21504
	ds_read_b128 v[224:227], v146 offset:22528
	ds_read_b128 v[228:231], v146 offset:23552
	global_load_lds_dwordx4 v[152:153], off
	s_add_i32 m0, s41, 0x2000
	s_add_u32 s42, s18, 0x40000
	v_lshl_add_u64 v[160:161], s[18:19], 0, v[130:131]
	s_addc_u32 s43, s19, 0
	s_add_i32 s41, s44, s24
	global_load_lds_dwordx4 v[160:161], off
	v_lshl_add_u64 v[162:163], s[42:43], 0, v[0:1]
	s_mov_b32 m0, s41
	v_lshl_add_u64 v[170:171], s[20:21], 0, v[132:133]
	global_load_lds_dwordx4 v[162:163], off
	v_lshl_add_u64 v[162:163], s[42:43], 0, v[130:131]
	s_add_i32 m0, s41, 0x2000
	s_nop 0
	global_load_lds_dwordx4 v[162:163], off
	v_lshl_add_u64 v[162:163], s[20:21], 0, v[134:135]
	s_mov_b32 m0, s25
	s_nop 0
	global_load_lds_dwordx4 v[162:163], off
	s_mov_b32 m0, s26
	s_nop 0
	global_load_lds_dwordx4 v[170:171], off
	s_waitcnt vmcnt(8)
	s_waitcnt lgkmcnt(0)
	s_barrier
; #define PG8_STAGE(bufoff, gbase, voff) do { _Pragma("unroll") for (int _i = 0; _i < 2; ++_i) \
;         __builtin_amdgcn_global_load_lds((const unsigned*)((const char*)(gbase) + (voff)[_i]), (LAS unsigned*)(lds + (bufoff) + ldsw + _i * 8192), 16, 0, 0); } while (0)
; #define PG8_LDA(dst, b, h) do { _Pragma("unroll") for (int m = 0; m < 4; ++m) _Pragma("unroll") for (int k = 0; k < 2; ++k) dst[m][k] = *(const LAS bf16x8*)(lds + PG8_SA(b, h) + aoff + m * 2048 + k * 1024); } while (0)
; #define PG8_LDB(dst, b, h) do { _Pragma("unroll") for (int n = 0; n < 2; ++n) _Pragma("unroll") for (int k = 0; k < 2; ++k) dst[n][k] = *(const LAS bf16x8*)(lds + PG8_SB(b, h) + boff + n * 2048 + k * 1024); } while (0)
; #define PG8_MMA(ai, bj, At, Bt) do { __builtin_amdgcn_s_setprio(1); _Pragma("unroll") for (int m = 0; m < 4; ++m) _Pragma("unroll") for (int n = 0; n < 2; ++n) _Pragma("unroll") for (int k = 0; k < 2; ++k) \
;         acc[ai][bj][m][n] = __builtin_amdgcn_mfma_f32_16x16x32_bf16(Bt[n][k], At[m][k], acc[ai][bj][m][n], 0, 0, 0); __builtin_amdgcn_s_setprio(0); } while (0)
; #define PG8_WAIT_V(n) asm volatile("s_waitcnt vmcnt(" #n ")" ::: "memory")
; #define PG8_WAIT_L(n) asm volatile("s_waitcnt lgkmcnt(" #n ")" ::: "memory")
; #define PG8_BAR __builtin_amdgcn_s_barrier()
; #define PG8_SCHED __builtin_amdgcn_sched_barrier(0)
; template <class Epi, bool ALIGN_EPI>
; __device__ __forceinline__ void gemm_phase(LAS unsigned char* lds, const Gemm g, const StaticOrder& S, const Epi& E) {
;     ...
;             PG8_WAIT_V(8); PG8_WAIT_L(0); PG8_BAR; PG8_MMA(1, 0, At, B0); PG8_MMA(1, 1, At, B1); PG8_BAR; PG8_SCHED;
;             PG8_LDB(B0, 1, 0); PG8_LDB(B1, 1, 1); PG8_SCHED; PG8_LDA(At, 1, 0); PG8_STAGE(PG8_SA(0, 1), a2 + hstepA, voffA);
;             PG8_WAIT_V(8); PG8_WAIT_L(0); PG8_BAR; PG8_MMA(0, 0, At, B0); PG8_MMA(0, 1, At, B1); PG8_BAR; PG8_SCHED;
	s_waitcnt lgkmcnt(0)
	v_mfma_f32_16x16x32_bf16 v[62:65], v[140:143], v[200:203], v[62:65]
	v_mfma_f32_16x16x32_bf16 v[54:57], v[156:159], v[200:203], v[54:57]
	v_mfma_f32_16x16x32_bf16 v[46:49], v[140:143], v[208:211], v[46:49]
	v_mfma_f32_16x16x32_bf16 v[38:41], v[156:159], v[208:211], v[38:41]
	v_mfma_f32_16x16x32_bf16 v[30:33], v[140:143], v[216:219], v[30:33]
	v_mfma_f32_16x16x32_bf16 v[22:25], v[156:159], v[216:219], v[22:25]
	v_mfma_f32_16x16x32_bf16 v[14:17], v[140:143], v[224:227], v[14:17]
	v_mfma_f32_16x16x32_bf16 v[6:9], v[156:159], v[224:227], v[6:9]
	v_mfma_f32_16x16x32_bf16 v[62:65], v[148:151], v[204:207], v[62:65]
	v_mfma_f32_16x16x32_bf16 v[54:57], v[180:183], v[204:207], v[54:57]
	v_mfma_f32_16x16x32_bf16 v[46:49], v[148:151], v[212:215], v[46:49]
	v_mfma_f32_16x16x32_bf16 v[38:41], v[180:183], v[212:215], v[38:41]
	v_mfma_f32_16x16x32_bf16 v[30:33], v[148:151], v[220:223], v[30:33]
	v_mfma_f32_16x16x32_bf16 v[22:25], v[180:183], v[220:223], v[22:25]
	v_mfma_f32_16x16x32_bf16 v[14:17], v[148:151], v[228:231], v[14:17]
	v_mfma_f32_16x16x32_bf16 v[6:9], v[180:183], v[228:231], v[6:9]
	v_mfma_f32_16x16x32_bf16 v[58:61], v[184:187], v[200:203], v[58:61]
	v_mfma_f32_16x16x32_bf16 v[50:53], v[192:195], v[200:203], v[50:53]
	v_mfma_f32_16x16x32_bf16 v[42:45], v[184:187], v[208:211], v[42:45]
	v_mfma_f32_16x16x32_bf16 v[34:37], v[192:195], v[208:211], v[34:37]
	v_mfma_f32_16x16x32_bf16 v[26:29], v[184:187], v[216:219], v[26:29]
	v_mfma_f32_16x16x32_bf16 v[18:21], v[192:195], v[216:219], v[18:21]
	v_mfma_f32_16x16x32_bf16 v[10:13], v[184:187], v[224:227], v[10:13]
	v_mfma_f32_16x16x32_bf16 v[2:5], v[192:195], v[224:227], v[2:5]
	v_mfma_f32_16x16x32_bf16 v[58:61], v[188:191], v[204:207], v[58:61]
	v_mfma_f32_16x16x32_bf16 v[50:53], v[196:199], v[204:207], v[50:53]
	v_mfma_f32_16x16x32_bf16 v[42:45], v[188:191], v[212:215], v[42:45]
	v_mfma_f32_16x16x32_bf16 v[34:37], v[196:199], v[212:215], v[34:37]
	v_mfma_f32_16x16x32_bf16 v[26:29], v[188:191], v[220:223], v[26:29]
	v_mfma_f32_16x16x32_bf16 v[18:21], v[196:199], v[220:223], v[18:21]
	v_mfma_f32_16x16x32_bf16 v[10:13], v[188:191], v[228:231], v[10:13]
	v_mfma_f32_16x16x32_bf16 v[2:5], v[196:199], v[228:231], v[2:5]
	s_barrier
	s_add_i32 s41, 0, 0x18000
	v_add_u32_e32 v164, s41, v144
	s_add_i32 s42, 0, 0x1c000
	ds_read_b128 v[140:143], v164
	ds_read_b128 v[148:151], v164 offset:1024
	ds_read_b128 v[156:159], v164 offset:2048
	ds_read_b128 v[180:183], v164 offset:3072
	v_add_u32_e32 v164, s42, v144
	ds_read_b128 v[184:187], v164
	ds_read_b128 v[188:191], v164 offset:1024
	ds_read_b128 v[192:195], v164 offset:2048
	ds_read_b128 v[196:199], v164 offset:3072
	s_add_u32 s20, s20, 0x40000
	s_addc_u32 s21, s21, 0
	s_mov_b32 m0, s27
	v_lshl_add_u64 v[172:173], s[20:21], 0, v[134:135]
	ds_read_b128 v[200:203], v146 offset:32768
	ds_read_b128 v[204:207], v146 offset:33792
	ds_read_b128 v[208:211], v146 offset:34816
	ds_read_b128 v[212:215], v146 offset:35840
	ds_read_b128 v[216:219], v146 offset:36864
	ds_read_b128 v[220:223], v146 offset:37888
	ds_read_b128 v[224:227], v146 offset:38912
	ds_read_b128 v[228:231], v146 offset:39936
	global_load_lds_dwordx4 v[172:173], off
	v_lshl_add_u64 v[172:173], s[20:21], 0, v[132:133]
	s_mov_b32 m0, s28
	s_nop 0
	global_load_lds_dwordx4 v[172:173], off
	s_waitcnt vmcnt(8)
	s_waitcnt lgkmcnt(0)
	s_barrier
	s_waitcnt lgkmcnt(0)
	v_mfma_f32_16x16x32_bf16 v[126:129], v[140:143], v[200:203], v[126:129]
	v_mfma_f32_16x16x32_bf16 v[118:121], v[156:159], v[200:203], v[118:121]
	v_mfma_f32_16x16x32_bf16 v[110:113], v[140:143], v[208:211], v[110:113]
	v_mfma_f32_16x16x32_bf16 v[102:105], v[156:159], v[208:211], v[102:105]
	v_mfma_f32_16x16x32_bf16 v[94:97], v[140:143], v[216:219], v[94:97]
	v_mfma_f32_16x16x32_bf16 v[86:89], v[156:159], v[216:219], v[86:89]
	v_mfma_f32_16x16x32_bf16 v[78:81], v[140:143], v[224:227], v[78:81]
	v_mfma_f32_16x16x32_bf16 v[70:73], v[156:159], v[224:227], v[70:73]
	v_mfma_f32_16x16x32_bf16 v[126:129], v[148:151], v[204:207], v[126:129]
	v_mfma_f32_16x16x32_bf16 v[118:121], v[180:183], v[204:207], v[118:121]
	v_mfma_f32_16x16x32_bf16 v[110:113], v[148:151], v[212:215], v[110:113]
	v_mfma_f32_16x16x32_bf16 v[102:105], v[180:183], v[212:215], v[102:105]
	v_mfma_f32_16x16x32_bf16 v[94:97], v[148:151], v[220:223], v[94:97]
	v_mfma_f32_16x16x32_bf16 v[86:89], v[180:183], v[220:223], v[86:89]
	v_mfma_f32_16x16x32_bf16 v[78:81], v[148:151], v[228:231], v[78:81]
	v_mfma_f32_16x16x32_bf16 v[70:73], v[180:183], v[228:231], v[70:73]
	v_mfma_f32_16x16x32_bf16 v[122:125], v[184:187], v[200:203], v[122:125]
	v_mfma_f32_16x16x32_bf16 v[114:117], v[192:195], v[200:203], v[114:117]
	v_mfma_f32_16x16x32_bf16 v[106:109], v[184:187], v[208:211], v[106:109]
	v_mfma_f32_16x16x32_bf16 v[98:101], v[192:195], v[208:211], v[98:101]
	v_mfma_f32_16x16x32_bf16 v[90:93], v[184:187], v[216:219], v[90:93]
	v_mfma_f32_16x16x32_bf16 v[82:85], v[192:195], v[216:219], v[82:85]
	v_mfma_f32_16x16x32_bf16 v[74:77], v[184:187], v[224:227], v[74:77]
	v_mfma_f32_16x16x32_bf16 v[66:69], v[192:195], v[224:227], v[66:69]
	v_mfma_f32_16x16x32_bf16 v[122:125], v[188:191], v[204:207], v[122:125]
	v_mfma_f32_16x16x32_bf16 v[114:117], v[196:199], v[204:207], v[114:117]
	v_mfma_f32_16x16x32_bf16 v[106:109], v[188:191], v[212:215], v[106:109]
	v_mfma_f32_16x16x32_bf16 v[98:101], v[196:199], v[212:215], v[98:101]
	v_mfma_f32_16x16x32_bf16 v[90:93], v[188:191], v[220:223], v[90:93]
	v_mfma_f32_16x16x32_bf16 v[82:85], v[196:199], v[220:223], v[82:85]
	v_mfma_f32_16x16x32_bf16 v[74:77], v[188:191], v[228:231], v[74:77]
	v_mfma_f32_16x16x32_bf16 v[66:69], v[196:199], v[228:231], v[66:69]
	s_barrier
; #define PG8_STAGE(bufoff, gbase, voff) do { _Pragma("unroll") for (int _i = 0; _i < 2; ++_i) \
;         __builtin_amdgcn_global_load_lds((const unsigned*)((const char*)(gbase) + (voff)[_i]), (LAS unsigned*)(lds + (bufoff) + ldsw + _i * 8192), 16, 0, 0); } while (0)
; #define PG8_LDA(dst, b, h) do { _Pragma("unroll") for (int m = 0; m < 4; ++m) _Pragma("unroll") for (int k = 0; k < 2; ++k) dst[m][k] = *(const LAS bf16x8*)(lds + PG8_SA(b, h) + aoff + m * 2048 + k * 1024); } while (0)
; #define PG8_MMA(ai, bj, At, Bt) do { __builtin_amdgcn_s_setprio(1); _Pragma("unroll") for (int m = 0; m < 4; ++m) _Pragma("unroll") for (int n = 0; n < 2; ++n) _Pragma("unroll") for (int k = 0; k < 2; ++k) \
;         acc[ai][bj][m][n] = __builtin_amdgcn_mfma_f32_16x16x32_bf16(Bt[n][k], At[m][k], acc[ai][bj][m][n], 0, 0, 0); __builtin_amdgcn_s_setprio(0); } while (0)
; #define PG8_WAIT_V(n) asm volatile("s_waitcnt vmcnt(" #n ")" ::: "memory")
; #define PG8_WAIT_L(n) asm volatile("s_waitcnt lgkmcnt(" #n ")" ::: "memory")
; #define PG8_BAR __builtin_amdgcn_s_barrier()
; #define PG8_SCHED __builtin_amdgcn_sched_barrier(0)
; template <class Epi, bool ALIGN_EPI>
; __device__ __forceinline__ void gemm_phase(LAS unsigned char* lds, const Gemm g, const StaticOrder& S, const Epi& E) {
;     ...
;             PG8_LDA(At, 1, 1); PG8_STAGE(PG8_SB(1, 0), b3, voffB); PG8_STAGE(PG8_SB(1, 1), b3 + hstepB, voffB); PG8_STAGE(PG8_SA(1, 0), a3, voffA);
;             PG8_WAIT_V(8); PG8_WAIT_L(0); PG8_BAR; PG8_MMA(1, 0, At, B0); PG8_MMA(1, 1, At, B1); PG8_BAR; PG8_SCHED;
;         }
;         if constexpr (ALIGN_EPI) { if (wr == 0) PG8_BAR; }
	s_add_i32 s20, s41, s24
	v_lshl_add_u64 v[152:153], v[152:153], 0, s[94:95]
	s_mov_b32 m0, s20
	ds_read_b128 v[200:203], v146 offset:49152
	ds_read_b128 v[204:207], v146 offset:50176
	ds_read_b128 v[208:211], v146 offset:51200
	ds_read_b128 v[212:215], v146 offset:52224
	ds_read_b128 v[216:219], v146 offset:53248
	ds_read_b128 v[220:223], v146 offset:54272
	ds_read_b128 v[224:227], v146 offset:55296
	ds_read_b128 v[228:231], v146 offset:56320
	global_load_lds_dwordx4 v[152:153], off
	s_add_i32 m0, s20, 0x2000
	s_add_u32 s18, s18, 0x40080
	v_lshl_add_u64 v[152:153], v[160:161], 0, s[94:95]
	s_addc_u32 s19, s19, 0
	s_add_i32 s20, s42, s24
	global_load_lds_dwordx4 v[152:153], off
	v_lshl_add_u64 v[152:153], s[18:19], 0, v[0:1]
	s_mov_b32 m0, s20
	s_nop 0
	global_load_lds_dwordx4 v[152:153], off
	v_lshl_add_u64 v[152:153], s[18:19], 0, v[130:131]
	s_add_i32 m0, s20, 0x2000
	s_nop 0
	global_load_lds_dwordx4 v[152:153], off
	v_lshl_add_u64 v[152:153], v[162:163], 0, s[94:95]
	s_mov_b32 m0, s4
	s_nop 0
	global_load_lds_dwordx4 v[152:153], off
	v_lshl_add_u64 v[152:153], v[170:171], 0, s[94:95]
	s_mov_b32 m0, s29
	s_nop 0
	global_load_lds_dwordx4 v[152:153], off
	s_waitcnt vmcnt(8)
	s_waitcnt lgkmcnt(0)
	s_barrier
	s_waitcnt lgkmcnt(0)
	v_mfma_f32_16x16x32_bf16 v[62:65], v[140:143], v[200:203], v[62:65]
	v_mfma_f32_16x16x32_bf16 v[54:57], v[156:159], v[200:203], v[54:57]
	v_mfma_f32_16x16x32_bf16 v[46:49], v[140:143], v[208:211], v[46:49]
	v_mfma_f32_16x16x32_bf16 v[38:41], v[156:159], v[208:211], v[38:41]
	v_mfma_f32_16x16x32_bf16 v[30:33], v[140:143], v[216:219], v[30:33]
	v_mfma_f32_16x16x32_bf16 v[22:25], v[156:159], v[216:219], v[22:25]
	v_mfma_f32_16x16x32_bf16 v[14:17], v[140:143], v[224:227], v[14:17]
	v_mfma_f32_16x16x32_bf16 v[6:9], v[156:159], v[224:227], v[6:9]
	v_mfma_f32_16x16x32_bf16 v[62:65], v[148:151], v[204:207], v[62:65]
	v_mfma_f32_16x16x32_bf16 v[54:57], v[180:183], v[204:207], v[54:57]
	v_mfma_f32_16x16x32_bf16 v[46:49], v[148:151], v[212:215], v[46:49]
	v_mfma_f32_16x16x32_bf16 v[38:41], v[180:183], v[212:215], v[38:41]
	v_mfma_f32_16x16x32_bf16 v[30:33], v[148:151], v[220:223], v[30:33]
	v_mfma_f32_16x16x32_bf16 v[22:25], v[180:183], v[220:223], v[22:25]
	v_mfma_f32_16x16x32_bf16 v[14:17], v[148:151], v[228:231], v[14:17]
	v_mfma_f32_16x16x32_bf16 v[6:9], v[180:183], v[228:231], v[6:9]
	v_mfma_f32_16x16x32_bf16 v[58:61], v[184:187], v[200:203], v[58:61]
	v_mfma_f32_16x16x32_bf16 v[50:53], v[192:195], v[200:203], v[50:53]
	v_mfma_f32_16x16x32_bf16 v[42:45], v[184:187], v[208:211], v[42:45]
	v_mfma_f32_16x16x32_bf16 v[34:37], v[192:195], v[208:211], v[34:37]
	v_mfma_f32_16x16x32_bf16 v[26:29], v[184:187], v[216:219], v[26:29]
	v_mfma_f32_16x16x32_bf16 v[18:21], v[192:195], v[216:219], v[18:21]
	v_mfma_f32_16x16x32_bf16 v[10:13], v[184:187], v[224:227], v[10:13]
	v_mfma_f32_16x16x32_bf16 v[2:5], v[192:195], v[224:227], v[2:5]
	v_mfma_f32_16x16x32_bf16 v[58:61], v[188:191], v[204:207], v[58:61]
	v_mfma_f32_16x16x32_bf16 v[50:53], v[196:199], v[204:207], v[50:53]
	v_mfma_f32_16x16x32_bf16 v[42:45], v[188:191], v[212:215], v[42:45]
	v_mfma_f32_16x16x32_bf16 v[34:37], v[196:199], v[212:215], v[34:37]
	v_mfma_f32_16x16x32_bf16 v[26:29], v[188:191], v[220:223], v[26:29]
	v_mfma_f32_16x16x32_bf16 v[18:21], v[196:199], v[220:223], v[18:21]
	v_mfma_f32_16x16x32_bf16 v[10:13], v[188:191], v[228:231], v[10:13]
	v_mfma_f32_16x16x32_bf16 v[2:5], v[196:199], v[228:231], v[2:5]
	s_barrier
	s_add_i32 s40, s40, 2
	s_add_u32 s6, s6, 0x100
	s_addc_u32 s7, s7, 0
	s_add_u32 s38, s38, 0x100
	s_addc_u32 s39, s39, 0
	s_cmp_gt_u32 s40, 13
	s_cbranch_scc0 .LBB0_304
	s_and_b64 vcc, exec, s[8:9]
	s_cbranch_vccz .LBB0_307
	s_barrier

; #define PG8_STAGE(bufoff, gbase, voff) do { _Pragma("unroll") for (int _i = 0; _i < 2; ++_i) \
;         __builtin_amdgcn_global_load_lds((const unsigned*)((const char*)(gbase) + (voff)[_i]), (LAS unsigned*)(lds + (bufoff) + ldsw + _i * 8192), 16, 0, 0); } while (0)
; #define PG8_LDA(dst, b, h) do { _Pragma("unroll") for (int m = 0; m < 4; ++m) _Pragma("unroll") for (int k = 0; k < 2; ++k) dst[m][k] = *(const LAS bf16x8*)(lds + PG8_SA(b, h) + aoff + m * 2048 + k * 1024); } while (0)
; #define PG8_LDB(dst, b, h) do { _Pragma("unroll") for (int n = 0; n < 2; ++n) _Pragma("unroll") for (int k = 0; k < 2; ++k) dst[n][k] = *(const LAS bf16x8*)(lds + PG8_SB(b, h) + boff + n * 2048 + k * 1024); } while (0)
; #define PG8_MMA(ai, bj, At, Bt) do { __builtin_amdgcn_s_setprio(1); _Pragma("unroll") for (int m = 0; m < 4; ++m) _Pragma("unroll") for (int n = 0; n < 2; ++n) _Pragma("unroll") for (int k = 0; k < 2; ++k) \
;         acc[ai][bj][m][n] = __builtin_amdgcn_mfma_f32_16x16x32_bf16(Bt[n][k], At[m][k], acc[ai][bj][m][n], 0, 0, 0); __builtin_amdgcn_s_setprio(0); } while (0)
; #define PG8_WAIT_V(n) asm volatile("s_waitcnt vmcnt(" #n ")" ::: "memory")
; #define PG8_WAIT_L(n) asm volatile("s_waitcnt lgkmcnt(" #n ")" ::: "memory")
; #define PG8_BAR __builtin_amdgcn_s_barrier()
; #define PG8_SCHED __builtin_amdgcn_sched_barrier(0)
; template <class Epi, bool ALIGN_EPI>
; __device__ __forceinline__ void gemm_phase(LAS unsigned char* lds, const Gemm g, const StaticOrder& S, const Epi& E) {
;     ...
;             const bool last = (t == nt - 2);
;             const char* a1 = cA + (size_t)(t + 1) * kstep;
;             const char* a2 = last ? nA : cA + (size_t)(t + 2) * kstep; const char* b2 = last ? nB : cB + (size_t)(t + 2) * kstep;
;             const char* a3 = a2 + kstep; const char* b3 = b2 + kstep;
;             PG8_LDB(B0, 0, 0); PG8_LDB(B1, 0, 1); PG8_SCHED; PG8_LDA(At, 0, 0); PG8_STAGE(PG8_SA(1, 1), a1 + hstepA, voffA);
;             PG8_WAIT_V(8); PG8_WAIT_L(0); PG8_BAR; PG8_MMA(0, 0, At, B0); PG8_MMA(0, 1, At, B1); PG8_BAR; PG8_SCHED;
;             PG8_LDA(At, 0, 1); PG8_STAGE(PG8_SB(0, 0), b2, voffB); PG8_STAGE(PG8_SB(0, 1), b2 + hstepB, voffB); PG8_STAGE(PG8_SA(0, 0), a2, voffA);
;             PG8_WAIT_V(8); PG8_WAIT_L(0); PG8_BAR; PG8_MMA(1, 0, At, B0); PG8_MMA(1, 1, At, B1); PG8_BAR; PG8_SCHED;
.LBB0_338:
	s_add_u32 s10, s8, 0x100
	s_addc_u32 s11, s9, 0
	s_add_i32 s42, 0, 0x10000
	s_cmp_eq_u32 s41, 12
	s_cselect_b32 s25, s17, s11
	s_cselect_b32 s24, s16, s10
	v_add_u32_e32 v144, s42, v146
	s_cselect_b32 s23, s15, s40
	s_cselect_b32 s22, s21, s39
	s_add_i32 s43, 0, 0x14000
	ds_read_b128 v[140:143], v144
	ds_read_b128 v[148:151], v144 offset:1024
	ds_read_b128 v[156:159], v144 offset:2048
	ds_read_b128 v[180:183], v144 offset:3072
	v_add_u32_e32 v144, s43, v146
	ds_read_b128 v[184:187], v144
	ds_read_b128 v[188:191], v144 offset:1024
	ds_read_b128 v[192:195], v144 offset:2048
	ds_read_b128 v[196:199], v144 offset:3072
	v_lshl_add_u64 v[144:145], s[8:9], 0, v[136:137]
	s_add_i32 m0, s29, 0xc000
	ds_read_b128 v[200:203], v147
	ds_read_b128 v[204:207], v147 offset:1024
	ds_read_b128 v[208:211], v147 offset:2048
	ds_read_b128 v[212:215], v147 offset:3072
	ds_read_b128 v[216:219], v147 offset:4096
	ds_read_b128 v[220:223], v147 offset:5120
	ds_read_b128 v[224:227], v147 offset:6144
	ds_read_b128 v[228:231], v147 offset:7168
	global_load_lds_dwordx4 v[144:145], off
	v_lshl_add_u64 v[144:145], s[8:9], 0, v[138:139]
	s_add_i32 m0, s29, 0xe000
	s_nop 0
	global_load_lds_dwordx4 v[144:145], off
	s_waitcnt vmcnt(8)
	s_waitcnt lgkmcnt(0)
	s_barrier
	s_waitcnt lgkmcnt(0)
	v_mfma_f32_16x16x32_bf16 v[126:129], v[140:143], v[200:203], v[126:129]
	v_mfma_f32_16x16x32_bf16 v[122:125], v[156:159], v[200:203], v[122:125]
	v_mfma_f32_16x16x32_bf16 v[110:113], v[140:143], v[208:211], v[110:113]
	v_mfma_f32_16x16x32_bf16 v[106:109], v[156:159], v[208:211], v[106:109]
	v_mfma_f32_16x16x32_bf16 v[94:97], v[140:143], v[216:219], v[94:97]
	v_mfma_f32_16x16x32_bf16 v[90:93], v[156:159], v[216:219], v[90:93]
	v_mfma_f32_16x16x32_bf16 v[78:81], v[140:143], v[224:227], v[78:81]
	v_mfma_f32_16x16x32_bf16 v[74:77], v[156:159], v[224:227], v[74:77]
	v_mfma_f32_16x16x32_bf16 v[126:129], v[148:151], v[204:207], v[126:129]
	v_mfma_f32_16x16x32_bf16 v[122:125], v[180:183], v[204:207], v[122:125]
	v_mfma_f32_16x16x32_bf16 v[110:113], v[148:151], v[212:215], v[110:113]
	v_mfma_f32_16x16x32_bf16 v[106:109], v[180:183], v[212:215], v[106:109]
	v_mfma_f32_16x16x32_bf16 v[94:97], v[148:151], v[220:223], v[94:97]
	v_mfma_f32_16x16x32_bf16 v[90:93], v[180:183], v[220:223], v[90:93]
	v_mfma_f32_16x16x32_bf16 v[78:81], v[148:151], v[228:231], v[78:81]
	v_mfma_f32_16x16x32_bf16 v[74:77], v[180:183], v[228:231], v[74:77]
	v_mfma_f32_16x16x32_bf16 v[118:121], v[184:187], v[200:203], v[118:121]
	v_mfma_f32_16x16x32_bf16 v[114:117], v[192:195], v[200:203], v[114:117]
	v_mfma_f32_16x16x32_bf16 v[102:105], v[184:187], v[208:211], v[102:105]
	v_mfma_f32_16x16x32_bf16 v[98:101], v[192:195], v[208:211], v[98:101]
	v_mfma_f32_16x16x32_bf16 v[86:89], v[184:187], v[216:219], v[86:89]
	v_mfma_f32_16x16x32_bf16 v[82:85], v[192:195], v[216:219], v[82:85]
	v_mfma_f32_16x16x32_bf16 v[70:73], v[184:187], v[224:227], v[70:73]
	v_mfma_f32_16x16x32_bf16 v[66:69], v[192:195], v[224:227], v[66:69]
	v_mfma_f32_16x16x32_bf16 v[118:121], v[188:191], v[204:207], v[118:121]
	v_mfma_f32_16x16x32_bf16 v[114:117], v[196:199], v[204:207], v[114:117]
	v_mfma_f32_16x16x32_bf16 v[102:105], v[188:191], v[212:215], v[102:105]
	v_mfma_f32_16x16x32_bf16 v[98:101], v[196:199], v[212:215], v[98:101]
	v_mfma_f32_16x16x32_bf16 v[86:89], v[188:191], v[220:223], v[86:89]
	v_mfma_f32_16x16x32_bf16 v[82:85], v[196:199], v[220:223], v[82:85]
	v_mfma_f32_16x16x32_bf16 v[70:73], v[188:191], v[228:231], v[70:73]
	v_mfma_f32_16x16x32_bf16 v[66:69], v[196:199], v[228:231], v[66:69]
	s_barrier
	s_add_i32 s8, s42, s28
	v_lshl_add_u64 v[144:145], s[22:23], 0, v[0:1]
	s_mov_b32 m0, s8
	ds_read_b128 v[200:203], v147 offset:16384
	ds_read_b128 v[204:207], v147 offset:17408
	ds_read_b128 v[208:211], v147 offset:18432
	ds_read_b128 v[212:215], v147 offset:19456
	ds_read_b128 v[216:219], v147 offset:20480
	ds_read_b128 v[220:223], v147 offset:21504
	ds_read_b128 v[224:227], v147 offset:22528
	ds_read_b128 v[228:231], v147 offset:23552
	global_load_lds_dwordx4 v[144:145], off
	s_add_i32 m0, s8, 0x2000
	s_add_u32 s8, s22, 0x40000
	v_lshl_add_u64 v[152:153], s[22:23], 0, v[134:135]
	s_addc_u32 s9, s23, 0
	s_add_i32 s42, s43, s28
	global_load_lds_dwordx4 v[152:153], off
	v_lshl_add_u64 v[160:161], s[8:9], 0, v[0:1]
	s_mov_b32 m0, s42
	v_lshl_add_u64 v[162:163], s[24:25], 0, v[132:133]
	global_load_lds_dwordx4 v[160:161], off
	v_lshl_add_u64 v[160:161], s[8:9], 0, v[134:135]
	s_add_i32 m0, s42, 0x2000
	s_nop 0
	global_load_lds_dwordx4 v[160:161], off
	v_lshl_add_u64 v[160:161], s[24:25], 0, v[130:131]
	s_mov_b32 m0, s29
	s_nop 0
	global_load_lds_dwordx4 v[160:161], off
	s_mov_b32 m0, s30
	s_nop 0
	global_load_lds_dwordx4 v[162:163], off
	s_waitcnt vmcnt(8)
	s_waitcnt lgkmcnt(0)
	s_barrier
; #define PG8_STAGE(bufoff, gbase, voff) do { _Pragma("unroll") for (int _i = 0; _i < 2; ++_i) \
;         __builtin_amdgcn_global_load_lds((const unsigned*)((const char*)(gbase) + (voff)[_i]), (LAS unsigned*)(lds + (bufoff) + ldsw + _i * 8192), 16, 0, 0); } while (0)
; #define PG8_LDA(dst, b, h) do { _Pragma("unroll") for (int m = 0; m < 4; ++m) _Pragma("unroll") for (int k = 0; k < 2; ++k) dst[m][k] = *(const LAS bf16x8*)(lds + PG8_SA(b, h) + aoff + m * 2048 + k * 1024); } while (0)
; #define PG8_LDB(dst, b, h) do { _Pragma("unroll") for (int n = 0; n < 2; ++n) _Pragma("unroll") for (int k = 0; k < 2; ++k) dst[n][k] = *(const LAS bf16x8*)(lds + PG8_SB(b, h) + boff + n * 2048 + k * 1024); } while (0)
; #define PG8_MMA(ai, bj, At, Bt) do { __builtin_amdgcn_s_setprio(1); _Pragma("unroll") for (int m = 0; m < 4; ++m) _Pragma("unroll") for (int n = 0; n < 2; ++n) _Pragma("unroll") for (int k = 0; k < 2; ++k) \
;         acc[ai][bj][m][n] = __builtin_amdgcn_mfma_f32_16x16x32_bf16(Bt[n][k], At[m][k], acc[ai][bj][m][n], 0, 0, 0); __builtin_amdgcn_s_setprio(0); } while (0)
; #define PG8_WAIT_V(n) asm volatile("s_waitcnt vmcnt(" #n ")" ::: "memory")
; #define PG8_WAIT_L(n) asm volatile("s_waitcnt lgkmcnt(" #n ")" ::: "memory")
; #define PG8_BAR __builtin_amdgcn_s_barrier()
; #define PG8_SCHED __builtin_amdgcn_sched_barrier(0)
; template <class Epi, bool ALIGN_EPI>
; __device__ __forceinline__ void gemm_phase(LAS unsigned char* lds, const Gemm g, const StaticOrder& S, const Epi& E) {
;     ...
;             PG8_WAIT_V(8); PG8_WAIT_L(0); PG8_BAR; PG8_MMA(1, 0, At, B0); PG8_MMA(1, 1, At, B1); PG8_BAR; PG8_SCHED;
;             PG8_LDB(B0, 1, 0); PG8_LDB(B1, 1, 1); PG8_SCHED; PG8_LDA(At, 1, 0); PG8_STAGE(PG8_SA(0, 1), a2 + hstepA, voffA);
;             PG8_WAIT_V(8); PG8_WAIT_L(0); PG8_BAR; PG8_MMA(0, 0, At, B0); PG8_MMA(0, 1, At, B1); PG8_BAR; PG8_SCHED;
	s_waitcnt lgkmcnt(0)
	v_mfma_f32_16x16x32_bf16 v[62:65], v[140:143], v[200:203], v[62:65]
	v_mfma_f32_16x16x32_bf16 v[58:61], v[156:159], v[200:203], v[58:61]
	v_mfma_f32_16x16x32_bf16 v[46:49], v[140:143], v[208:211], v[46:49]
	v_mfma_f32_16x16x32_bf16 v[42:45], v[156:159], v[208:211], v[42:45]
	v_mfma_f32_16x16x32_bf16 v[30:33], v[140:143], v[216:219], v[30:33]
	v_mfma_f32_16x16x32_bf16 v[26:29], v[156:159], v[216:219], v[26:29]
	v_mfma_f32_16x16x32_bf16 v[14:17], v[140:143], v[224:227], v[14:17]
	v_mfma_f32_16x16x32_bf16 v[10:13], v[156:159], v[224:227], v[10:13]
	v_mfma_f32_16x16x32_bf16 v[62:65], v[148:151], v[204:207], v[62:65]
	v_mfma_f32_16x16x32_bf16 v[58:61], v[180:183], v[204:207], v[58:61]
	v_mfma_f32_16x16x32_bf16 v[46:49], v[148:151], v[212:215], v[46:49]
	v_mfma_f32_16x16x32_bf16 v[42:45], v[180:183], v[212:215], v[42:45]
	v_mfma_f32_16x16x32_bf16 v[30:33], v[148:151], v[220:223], v[30:33]
	v_mfma_f32_16x16x32_bf16 v[26:29], v[180:183], v[220:223], v[26:29]
	v_mfma_f32_16x16x32_bf16 v[14:17], v[148:151], v[228:231], v[14:17]
	v_mfma_f32_16x16x32_bf16 v[10:13], v[180:183], v[228:231], v[10:13]
	v_mfma_f32_16x16x32_bf16 v[54:57], v[184:187], v[200:203], v[54:57]
	v_mfma_f32_16x16x32_bf16 v[50:53], v[192:195], v[200:203], v[50:53]
	v_mfma_f32_16x16x32_bf16 v[38:41], v[184:187], v[208:211], v[38:41]
	v_mfma_f32_16x16x32_bf16 v[34:37], v[192:195], v[208:211], v[34:37]
	v_mfma_f32_16x16x32_bf16 v[22:25], v[184:187], v[216:219], v[22:25]
	v_mfma_f32_16x16x32_bf16 v[18:21], v[192:195], v[216:219], v[18:21]
	v_mfma_f32_16x16x32_bf16 v[6:9], v[184:187], v[224:227], v[6:9]
	v_mfma_f32_16x16x32_bf16 v[2:5], v[192:195], v[224:227], v[2:5]
	v_mfma_f32_16x16x32_bf16 v[54:57], v[188:191], v[204:207], v[54:57]
	v_mfma_f32_16x16x32_bf16 v[50:53], v[196:199], v[204:207], v[50:53]
	v_mfma_f32_16x16x32_bf16 v[38:41], v[188:191], v[212:215], v[38:41]
	v_mfma_f32_16x16x32_bf16 v[34:37], v[196:199], v[212:215], v[34:37]
	v_mfma_f32_16x16x32_bf16 v[22:25], v[188:191], v[220:223], v[22:25]
	v_mfma_f32_16x16x32_bf16 v[18:21], v[196:199], v[220:223], v[18:21]
	v_mfma_f32_16x16x32_bf16 v[6:9], v[188:191], v[228:231], v[6:9]
	v_mfma_f32_16x16x32_bf16 v[2:5], v[196:199], v[228:231], v[2:5]
	s_barrier
	s_add_i32 s42, 0, 0x18000
	v_add_u32_e32 v164, s42, v146
	s_add_i32 s43, 0, 0x1c000
	ds_read_b128 v[140:143], v164
	ds_read_b128 v[148:151], v164 offset:1024
	ds_read_b128 v[156:159], v164 offset:2048
	ds_read_b128 v[180:183], v164 offset:3072
	v_add_u32_e32 v164, s43, v146
	ds_read_b128 v[184:187], v164
	ds_read_b128 v[188:191], v164 offset:1024
	ds_read_b128 v[192:195], v164 offset:2048
	ds_read_b128 v[196:199], v164 offset:3072
	s_add_u32 s8, s24, 0x160000
	s_addc_u32 s9, s25, 0
	s_mov_b32 m0, s31
	v_lshl_add_u64 v[170:171], s[8:9], 0, v[130:131]
	ds_read_b128 v[200:203], v147 offset:32768
	ds_read_b128 v[204:207], v147 offset:33792
	ds_read_b128 v[208:211], v147 offset:34816
	ds_read_b128 v[212:215], v147 offset:35840
	ds_read_b128 v[216:219], v147 offset:36864
	ds_read_b128 v[220:223], v147 offset:37888
	ds_read_b128 v[224:227], v147 offset:38912
	ds_read_b128 v[228:231], v147 offset:39936
	global_load_lds_dwordx4 v[170:171], off
	v_lshl_add_u64 v[170:171], s[8:9], 0, v[132:133]
	s_mov_b32 m0, s34
	s_nop 0
	global_load_lds_dwordx4 v[170:171], off
	s_waitcnt vmcnt(8)
	s_waitcnt lgkmcnt(0)
	s_barrier
	s_waitcnt lgkmcnt(0)
	v_mfma_f32_16x16x32_bf16 v[126:129], v[140:143], v[200:203], v[126:129]
	v_mfma_f32_16x16x32_bf16 v[122:125], v[156:159], v[200:203], v[122:125]
	v_mfma_f32_16x16x32_bf16 v[110:113], v[140:143], v[208:211], v[110:113]
	v_mfma_f32_16x16x32_bf16 v[106:109], v[156:159], v[208:211], v[106:109]
	v_mfma_f32_16x16x32_bf16 v[94:97], v[140:143], v[216:219], v[94:97]
	v_mfma_f32_16x16x32_bf16 v[90:93], v[156:159], v[216:219], v[90:93]
	v_mfma_f32_16x16x32_bf16 v[78:81], v[140:143], v[224:227], v[78:81]
	v_mfma_f32_16x16x32_bf16 v[74:77], v[156:159], v[224:227], v[74:77]
	v_mfma_f32_16x16x32_bf16 v[126:129], v[148:151], v[204:207], v[126:129]
	v_mfma_f32_16x16x32_bf16 v[122:125], v[180:183], v[204:207], v[122:125]
	v_mfma_f32_16x16x32_bf16 v[110:113], v[148:151], v[212:215], v[110:113]
	v_mfma_f32_16x16x32_bf16 v[106:109], v[180:183], v[212:215], v[106:109]
	v_mfma_f32_16x16x32_bf16 v[94:97], v[148:151], v[220:223], v[94:97]
	v_mfma_f32_16x16x32_bf16 v[90:93], v[180:183], v[220:223], v[90:93]
	v_mfma_f32_16x16x32_bf16 v[78:81], v[148:151], v[228:231], v[78:81]
	v_mfma_f32_16x16x32_bf16 v[74:77], v[180:183], v[228:231], v[74:77]
	v_mfma_f32_16x16x32_bf16 v[118:121], v[184:187], v[200:203], v[118:121]
	v_mfma_f32_16x16x32_bf16 v[114:117], v[192:195], v[200:203], v[114:117]
	v_mfma_f32_16x16x32_bf16 v[102:105], v[184:187], v[208:211], v[102:105]
	v_mfma_f32_16x16x32_bf16 v[98:101], v[192:195], v[208:211], v[98:101]
	v_mfma_f32_16x16x32_bf16 v[86:89], v[184:187], v[216:219], v[86:89]
	v_mfma_f32_16x16x32_bf16 v[82:85], v[192:195], v[216:219], v[82:85]
	v_mfma_f32_16x16x32_bf16 v[70:73], v[184:187], v[224:227], v[70:73]
	v_mfma_f32_16x16x32_bf16 v[66:69], v[192:195], v[224:227], v[66:69]
	v_mfma_f32_16x16x32_bf16 v[118:121], v[188:191], v[204:207], v[118:121]
	v_mfma_f32_16x16x32_bf16 v[114:117], v[196:199], v[204:207], v[114:117]
	v_mfma_f32_16x16x32_bf16 v[102:105], v[188:191], v[212:215], v[102:105]
	v_mfma_f32_16x16x32_bf16 v[98:101], v[196:199], v[212:215], v[98:101]
	v_mfma_f32_16x16x32_bf16 v[86:89], v[188:191], v[220:223], v[86:89]
	v_mfma_f32_16x16x32_bf16 v[82:85], v[196:199], v[220:223], v[82:85]
	v_mfma_f32_16x16x32_bf16 v[70:73], v[188:191], v[228:231], v[70:73]
	v_mfma_f32_16x16x32_bf16 v[66:69], v[196:199], v[228:231], v[66:69]
	s_barrier
; #define PG8_STAGE(bufoff, gbase, voff) do { _Pragma("unroll") for (int _i = 0; _i < 2; ++_i) \
;         __builtin_amdgcn_global_load_lds((const unsigned*)((const char*)(gbase) + (voff)[_i]), (LAS unsigned*)(lds + (bufoff) + ldsw + _i * 8192), 16, 0, 0); } while (0)
; #define PG8_LDA(dst, b, h) do { _Pragma("unroll") for (int m = 0; m < 4; ++m) _Pragma("unroll") for (int k = 0; k < 2; ++k) dst[m][k] = *(const LAS bf16x8*)(lds + PG8_SA(b, h) + aoff + m * 2048 + k * 1024); } while (0)
; #define PG8_MMA(ai, bj, At, Bt) do { __builtin_amdgcn_s_setprio(1); _Pragma("unroll") for (int m = 0; m < 4; ++m) _Pragma("unroll") for (int n = 0; n < 2; ++n) _Pragma("unroll") for (int k = 0; k < 2; ++k) \
;         acc[ai][bj][m][n] = __builtin_amdgcn_mfma_f32_16x16x32_bf16(Bt[n][k], At[m][k], acc[ai][bj][m][n], 0, 0, 0); __builtin_amdgcn_s_setprio(0); } while (0)
; #define PG8_WAIT_V(n) asm volatile("s_waitcnt vmcnt(" #n ")" ::: "memory")
; #define PG8_WAIT_L(n) asm volatile("s_waitcnt lgkmcnt(" #n ")" ::: "memory")
; #define PG8_BAR __builtin_amdgcn_s_barrier()
; #define PG8_SCHED __builtin_amdgcn_sched_barrier(0)
; template <class Epi, bool ALIGN_EPI>
; __device__ __forceinline__ void gemm_phase(LAS unsigned char* lds, const Gemm g, const StaticOrder& S, const Epi& E) {
;     ...
;             PG8_LDA(At, 1, 1); PG8_STAGE(PG8_SB(1, 0), b3, voffB); PG8_STAGE(PG8_SB(1, 1), b3 + hstepB, voffB); PG8_STAGE(PG8_SA(1, 0), a3, voffA);
;             PG8_WAIT_V(8); PG8_WAIT_L(0); PG8_BAR; PG8_MMA(1, 0, At, B0); PG8_MMA(1, 1, At, B1); PG8_BAR; PG8_SCHED;
;         }
;         if constexpr (ALIGN_EPI) { if (wr == 0) PG8_BAR; }
	s_add_i32 s8, s42, s28
	v_lshl_add_u64 v[144:145], v[144:145], 0, s[94:95]
	s_mov_b32 m0, s8
	ds_read_b128 v[200:203], v147 offset:49152
	ds_read_b128 v[204:207], v147 offset:50176
	ds_read_b128 v[208:211], v147 offset:51200
	ds_read_b128 v[212:215], v147 offset:52224
	ds_read_b128 v[216:219], v147 offset:53248
	ds_read_b128 v[220:223], v147 offset:54272
	ds_read_b128 v[224:227], v147 offset:55296
	ds_read_b128 v[228:231], v147 offset:56320
	global_load_lds_dwordx4 v[144:145], off
	s_add_i32 m0, s8, 0x2000
	s_add_u32 s8, s22, 0x40080
	v_lshl_add_u64 v[144:145], v[152:153], 0, s[94:95]
	s_addc_u32 s9, s23, 0
	s_add_i32 s22, s43, s28
	global_load_lds_dwordx4 v[144:145], off
	v_lshl_add_u64 v[144:145], s[8:9], 0, v[0:1]
	s_mov_b32 m0, s22
	s_nop 0
	global_load_lds_dwordx4 v[144:145], off
	v_lshl_add_u64 v[144:145], s[8:9], 0, v[134:135]
	s_add_i32 m0, s22, 0x2000
	s_nop 0
	global_load_lds_dwordx4 v[144:145], off
	v_lshl_add_u64 v[144:145], v[160:161], 0, s[94:95]
	s_mov_b32 m0, s35
	s_nop 0
	global_load_lds_dwordx4 v[144:145], off
	v_lshl_add_u64 v[144:145], v[162:163], 0, s[94:95]
	s_mov_b32 m0, s36
	s_nop 0
	global_load_lds_dwordx4 v[144:145], off
	s_waitcnt vmcnt(8)
	s_waitcnt lgkmcnt(0)
	s_barrier
	s_waitcnt lgkmcnt(0)
	v_mfma_f32_16x16x32_bf16 v[62:65], v[140:143], v[200:203], v[62:65]
	v_mfma_f32_16x16x32_bf16 v[58:61], v[156:159], v[200:203], v[58:61]
	v_mfma_f32_16x16x32_bf16 v[46:49], v[140:143], v[208:211], v[46:49]
	v_mfma_f32_16x16x32_bf16 v[42:45], v[156:159], v[208:211], v[42:45]
	v_mfma_f32_16x16x32_bf16 v[30:33], v[140:143], v[216:219], v[30:33]
	v_mfma_f32_16x16x32_bf16 v[26:29], v[156:159], v[216:219], v[26:29]
	v_mfma_f32_16x16x32_bf16 v[14:17], v[140:143], v[224:227], v[14:17]
	v_mfma_f32_16x16x32_bf16 v[10:13], v[156:159], v[224:227], v[10:13]
	v_mfma_f32_16x16x32_bf16 v[62:65], v[148:151], v[204:207], v[62:65]
	v_mfma_f32_16x16x32_bf16 v[58:61], v[180:183], v[204:207], v[58:61]
	v_mfma_f32_16x16x32_bf16 v[46:49], v[148:151], v[212:215], v[46:49]
	v_mfma_f32_16x16x32_bf16 v[42:45], v[180:183], v[212:215], v[42:45]
	v_mfma_f32_16x16x32_bf16 v[30:33], v[148:151], v[220:223], v[30:33]
	v_mfma_f32_16x16x32_bf16 v[26:29], v[180:183], v[220:223], v[26:29]
	v_mfma_f32_16x16x32_bf16 v[14:17], v[148:151], v[228:231], v[14:17]
	v_mfma_f32_16x16x32_bf16 v[10:13], v[180:183], v[228:231], v[10:13]
	v_mfma_f32_16x16x32_bf16 v[54:57], v[184:187], v[200:203], v[54:57]
	v_mfma_f32_16x16x32_bf16 v[50:53], v[192:195], v[200:203], v[50:53]
	v_mfma_f32_16x16x32_bf16 v[38:41], v[184:187], v[208:211], v[38:41]
	v_mfma_f32_16x16x32_bf16 v[34:37], v[192:195], v[208:211], v[34:37]
	v_mfma_f32_16x16x32_bf16 v[22:25], v[184:187], v[216:219], v[22:25]
	v_mfma_f32_16x16x32_bf16 v[18:21], v[192:195], v[216:219], v[18:21]
	v_mfma_f32_16x16x32_bf16 v[6:9], v[184:187], v[224:227], v[6:9]
	v_mfma_f32_16x16x32_bf16 v[2:5], v[192:195], v[224:227], v[2:5]
	v_mfma_f32_16x16x32_bf16 v[54:57], v[188:191], v[204:207], v[54:57]
	v_mfma_f32_16x16x32_bf16 v[50:53], v[196:199], v[204:207], v[50:53]
	v_mfma_f32_16x16x32_bf16 v[38:41], v[188:191], v[212:215], v[38:41]
	v_mfma_f32_16x16x32_bf16 v[34:37], v[196:199], v[212:215], v[34:37]
	v_mfma_f32_16x16x32_bf16 v[22:25], v[188:191], v[220:223], v[22:25]
	v_mfma_f32_16x16x32_bf16 v[18:21], v[196:199], v[220:223], v[18:21]
	v_mfma_f32_16x16x32_bf16 v[6:9], v[188:191], v[228:231], v[6:9]
	v_mfma_f32_16x16x32_bf16 v[2:5], v[196:199], v[228:231], v[2:5]
	s_barrier
	s_add_i32 s41, s41, 2
	s_add_u32 s39, s39, 0x100
	s_addc_u32 s40, s40, 0
	s_cmp_gt_u32 s41, 13
	s_mov_b64 s[8:9], s[10:11]
	s_cbranch_scc0 .LBB0_338
	s_and_b64 vcc, exec, s[2:3]
	s_cbranch_vccz .LBB0_341
	s_barrier

; #define PG8_STAGE(bufoff, gbase, voff) do { _Pragma("unroll") for (int _i = 0; _i < 2; ++_i) \
;         __builtin_amdgcn_global_load_lds((const unsigned*)((const char*)(gbase) + (voff)[_i]), (LAS unsigned*)(lds + (bufoff) + ldsw + _i * 8192), 16, 0, 0); } while (0)
; #define PG8_LDA(dst, b, h) do { _Pragma("unroll") for (int m = 0; m < 4; ++m) _Pragma("unroll") for (int k = 0; k < 2; ++k) dst[m][k] = *(const LAS bf16x8*)(lds + PG8_SA(b, h) + aoff + m * 2048 + k * 1024); } while (0)
; #define PG8_LDB(dst, b, h) do { _Pragma("unroll") for (int n = 0; n < 2; ++n) _Pragma("unroll") for (int k = 0; k < 2; ++k) dst[n][k] = *(const LAS bf16x8*)(lds + PG8_SB(b, h) + boff + n * 2048 + k * 1024); } while (0)
; #define PG8_MMA(ai, bj, At, Bt) do { __builtin_amdgcn_s_setprio(1); _Pragma("unroll") for (int m = 0; m < 4; ++m) _Pragma("unroll") for (int n = 0; n < 2; ++n) _Pragma("unroll") for (int k = 0; k < 2; ++k) \
;         acc[ai][bj][m][n] = __builtin_amdgcn_mfma_f32_16x16x32_bf16(Bt[n][k], At[m][k], acc[ai][bj][m][n], 0, 0, 0); __builtin_amdgcn_s_setprio(0); } while (0)
; #define PG8_WAIT_V(n) asm volatile("s_waitcnt vmcnt(" #n ")" ::: "memory")
; #define PG8_WAIT_L(n) asm volatile("s_waitcnt lgkmcnt(" #n ")" ::: "memory")
; #define PG8_BAR __builtin_amdgcn_s_barrier()
; #define PG8_SCHED __builtin_amdgcn_sched_barrier(0)
; template <class Epi, bool ALIGN_EPI>
; __device__ __forceinline__ void gemm_phase(LAS unsigned char* lds, const Gemm g, const StaticOrder& S, const Epi& E) {
;     ...
;             const bool last = (t == nt - 2);
;             const char* a1 = cA + (size_t)(t + 1) * kstep;
;             const char* a2 = last ? nA : cA + (size_t)(t + 2) * kstep; const char* b2 = last ? nB : cB + (size_t)(t + 2) * kstep;
;             const char* a3 = a2 + kstep; const char* b3 = b2 + kstep;
;             PG8_LDB(B0, 0, 0); PG8_LDB(B1, 0, 1); PG8_SCHED; PG8_LDA(At, 0, 0); PG8_STAGE(PG8_SA(1, 1), a1 + hstepA, voffA);
;             PG8_WAIT_V(8); PG8_WAIT_L(0); PG8_BAR; PG8_MMA(0, 0, At, B0); PG8_MMA(0, 1, At, B1); PG8_BAR; PG8_SCHED;
;             PG8_LDA(At, 0, 1); PG8_STAGE(PG8_SB(0, 0), b2, voffB); PG8_STAGE(PG8_SB(0, 1), b2 + hstepB, voffB); PG8_STAGE(PG8_SA(0, 0), a2, voffA);
;             PG8_WAIT_V(8); PG8_WAIT_L(0); PG8_BAR; PG8_MMA(1, 0, At, B0); PG8_MMA(1, 1, At, B1); PG8_BAR; PG8_SCHED;
.LBB0_414:
	s_add_u32 s2, s0, 0x100
	s_addc_u32 s3, s1, 0
	s_add_i32 s44, 0, 0x10000
	s_cmp_eq_u32 s43, 12
	s_cselect_b32 s23, s17, s3
	s_cselect_b32 s22, s16, s2
	v_add_u32_e32 v144, s44, v146
	s_cselect_b32 s21, s15, s42
	s_cselect_b32 s20, s40, s41
	s_add_i32 s45, 0, 0x14000
	ds_read_b128 v[140:143], v144
	ds_read_b128 v[148:151], v144 offset:1024
	ds_read_b128 v[156:159], v144 offset:2048
	ds_read_b128 v[180:183], v144 offset:3072
	v_add_u32_e32 v144, s45, v146
	ds_read_b128 v[184:187], v144
	ds_read_b128 v[188:191], v144 offset:1024
	ds_read_b128 v[192:195], v144 offset:2048
	ds_read_b128 v[196:199], v144 offset:3072
	v_lshl_add_u64 v[144:145], s[0:1], 0, v[136:137]
	s_add_i32 m0, s29, 0xc000
	ds_read_b128 v[200:203], v147
	ds_read_b128 v[204:207], v147 offset:1024
	ds_read_b128 v[208:211], v147 offset:2048
	ds_read_b128 v[212:215], v147 offset:3072
	ds_read_b128 v[216:219], v147 offset:4096
	ds_read_b128 v[220:223], v147 offset:5120
	ds_read_b128 v[224:227], v147 offset:6144
	ds_read_b128 v[228:231], v147 offset:7168
	global_load_lds_dwordx4 v[144:145], off
	v_lshl_add_u64 v[144:145], s[0:1], 0, v[138:139]
	s_add_i32 m0, s29, 0xe000
	s_nop 0
	global_load_lds_dwordx4 v[144:145], off
	s_waitcnt vmcnt(8)
	s_waitcnt lgkmcnt(0)
	s_barrier
	s_waitcnt lgkmcnt(0)
	v_mfma_f32_16x16x32_bf16 v[126:129], v[140:143], v[200:203], v[126:129]
	v_mfma_f32_16x16x32_bf16 v[122:125], v[156:159], v[200:203], v[122:125]
	v_mfma_f32_16x16x32_bf16 v[110:113], v[140:143], v[208:211], v[110:113]
	v_mfma_f32_16x16x32_bf16 v[106:109], v[156:159], v[208:211], v[106:109]
	v_mfma_f32_16x16x32_bf16 v[94:97], v[140:143], v[216:219], v[94:97]
	v_mfma_f32_16x16x32_bf16 v[90:93], v[156:159], v[216:219], v[90:93]
	v_mfma_f32_16x16x32_bf16 v[78:81], v[140:143], v[224:227], v[78:81]
	v_mfma_f32_16x16x32_bf16 v[74:77], v[156:159], v[224:227], v[74:77]
	v_mfma_f32_16x16x32_bf16 v[126:129], v[148:151], v[204:207], v[126:129]
	v_mfma_f32_16x16x32_bf16 v[122:125], v[180:183], v[204:207], v[122:125]
	v_mfma_f32_16x16x32_bf16 v[110:113], v[148:151], v[212:215], v[110:113]
	v_mfma_f32_16x16x32_bf16 v[106:109], v[180:183], v[212:215], v[106:109]
	v_mfma_f32_16x16x32_bf16 v[94:97], v[148:151], v[220:223], v[94:97]
	v_mfma_f32_16x16x32_bf16 v[90:93], v[180:183], v[220:223], v[90:93]
	v_mfma_f32_16x16x32_bf16 v[78:81], v[148:151], v[228:231], v[78:81]
	v_mfma_f32_16x16x32_bf16 v[74:77], v[180:183], v[228:231], v[74:77]
	v_mfma_f32_16x16x32_bf16 v[118:121], v[184:187], v[200:203], v[118:121]
	v_mfma_f32_16x16x32_bf16 v[114:117], v[192:195], v[200:203], v[114:117]
	v_mfma_f32_16x16x32_bf16 v[102:105], v[184:187], v[208:211], v[102:105]
	v_mfma_f32_16x16x32_bf16 v[98:101], v[192:195], v[208:211], v[98:101]
	v_mfma_f32_16x16x32_bf16 v[86:89], v[184:187], v[216:219], v[86:89]
	v_mfma_f32_16x16x32_bf16 v[82:85], v[192:195], v[216:219], v[82:85]
	v_mfma_f32_16x16x32_bf16 v[70:73], v[184:187], v[224:227], v[70:73]
	v_mfma_f32_16x16x32_bf16 v[66:69], v[192:195], v[224:227], v[66:69]
	v_mfma_f32_16x16x32_bf16 v[118:121], v[188:191], v[204:207], v[118:121]
	v_mfma_f32_16x16x32_bf16 v[114:117], v[196:199], v[204:207], v[114:117]
	v_mfma_f32_16x16x32_bf16 v[102:105], v[188:191], v[212:215], v[102:105]
	v_mfma_f32_16x16x32_bf16 v[98:101], v[196:199], v[212:215], v[98:101]
	v_mfma_f32_16x16x32_bf16 v[86:89], v[188:191], v[220:223], v[86:89]
	v_mfma_f32_16x16x32_bf16 v[82:85], v[196:199], v[220:223], v[82:85]
	v_mfma_f32_16x16x32_bf16 v[70:73], v[188:191], v[228:231], v[70:73]
	v_mfma_f32_16x16x32_bf16 v[66:69], v[196:199], v[228:231], v[66:69]
	s_barrier
	s_add_i32 s0, s44, s28
	v_lshl_add_u64 v[144:145], s[20:21], 0, v[0:1]
	s_mov_b32 m0, s0
	ds_read_b128 v[200:203], v147 offset:16384
	ds_read_b128 v[204:207], v147 offset:17408
	ds_read_b128 v[208:211], v147 offset:18432
	ds_read_b128 v[212:215], v147 offset:19456
	ds_read_b128 v[216:219], v147 offset:20480
	ds_read_b128 v[220:223], v147 offset:21504
	ds_read_b128 v[224:227], v147 offset:22528
	ds_read_b128 v[228:231], v147 offset:23552
	global_load_lds_dwordx4 v[144:145], off
	s_add_i32 m0, s0, 0x2000
	s_add_u32 s0, s20, 0x40000
	v_lshl_add_u64 v[152:153], s[20:21], 0, v[134:135]
	s_addc_u32 s1, s21, 0
	s_add_i32 s44, s45, s28
	global_load_lds_dwordx4 v[152:153], off
	v_lshl_add_u64 v[160:161], s[0:1], 0, v[0:1]
	s_mov_b32 m0, s44
	v_lshl_add_u64 v[162:163], s[22:23], 0, v[132:133]
	global_load_lds_dwordx4 v[160:161], off
	v_lshl_add_u64 v[160:161], s[0:1], 0, v[134:135]
	s_add_i32 m0, s44, 0x2000
	s_nop 0
	global_load_lds_dwordx4 v[160:161], off
	v_lshl_add_u64 v[160:161], s[22:23], 0, v[130:131]
	s_mov_b32 m0, s29
	s_nop 0
	global_load_lds_dwordx4 v[160:161], off
	s_mov_b32 m0, s30
	s_nop 0
	global_load_lds_dwordx4 v[162:163], off
	s_waitcnt vmcnt(8)
	s_waitcnt lgkmcnt(0)
	s_barrier
; #define PG8_STAGE(bufoff, gbase, voff) do { _Pragma("unroll") for (int _i = 0; _i < 2; ++_i) \
;         __builtin_amdgcn_global_load_lds((const unsigned*)((const char*)(gbase) + (voff)[_i]), (LAS unsigned*)(lds + (bufoff) + ldsw + _i * 8192), 16, 0, 0); } while (0)
; #define PG8_LDA(dst, b, h) do { _Pragma("unroll") for (int m = 0; m < 4; ++m) _Pragma("unroll") for (int k = 0; k < 2; ++k) dst[m][k] = *(const LAS bf16x8*)(lds + PG8_SA(b, h) + aoff + m * 2048 + k * 1024); } while (0)
; #define PG8_LDB(dst, b, h) do { _Pragma("unroll") for (int n = 0; n < 2; ++n) _Pragma("unroll") for (int k = 0; k < 2; ++k) dst[n][k] = *(const LAS bf16x8*)(lds + PG8_SB(b, h) + boff + n * 2048 + k * 1024); } while (0)
; #define PG8_MMA(ai, bj, At, Bt) do { __builtin_amdgcn_s_setprio(1); _Pragma("unroll") for (int m = 0; m < 4; ++m) _Pragma("unroll") for (int n = 0; n < 2; ++n) _Pragma("unroll") for (int k = 0; k < 2; ++k) \
;         acc[ai][bj][m][n] = __builtin_amdgcn_mfma_f32_16x16x32_bf16(Bt[n][k], At[m][k], acc[ai][bj][m][n], 0, 0, 0); __builtin_amdgcn_s_setprio(0); } while (0)
; #define PG8_WAIT_V(n) asm volatile("s_waitcnt vmcnt(" #n ")" ::: "memory")
; #define PG8_WAIT_L(n) asm volatile("s_waitcnt lgkmcnt(" #n ")" ::: "memory")
; #define PG8_BAR __builtin_amdgcn_s_barrier()
; #define PG8_SCHED __builtin_amdgcn_sched_barrier(0)
; template <class Epi, bool ALIGN_EPI>
; __device__ __forceinline__ void gemm_phase(LAS unsigned char* lds, const Gemm g, const StaticOrder& S, const Epi& E) {
;     ...
;             PG8_WAIT_V(8); PG8_WAIT_L(0); PG8_BAR; PG8_MMA(1, 0, At, B0); PG8_MMA(1, 1, At, B1); PG8_BAR; PG8_SCHED;
;             PG8_LDB(B0, 1, 0); PG8_LDB(B1, 1, 1); PG8_SCHED; PG8_LDA(At, 1, 0); PG8_STAGE(PG8_SA(0, 1), a2 + hstepA, voffA);
;             PG8_WAIT_V(8); PG8_WAIT_L(0); PG8_BAR; PG8_MMA(0, 0, At, B0); PG8_MMA(0, 1, At, B1); PG8_BAR; PG8_SCHED;
	s_waitcnt lgkmcnt(0)
	v_mfma_f32_16x16x32_bf16 v[62:65], v[140:143], v[200:203], v[62:65]
	v_mfma_f32_16x16x32_bf16 v[58:61], v[156:159], v[200:203], v[58:61]
	v_mfma_f32_16x16x32_bf16 v[46:49], v[140:143], v[208:211], v[46:49]
	v_mfma_f32_16x16x32_bf16 v[42:45], v[156:159], v[208:211], v[42:45]
	v_mfma_f32_16x16x32_bf16 v[30:33], v[140:143], v[216:219], v[30:33]
	v_mfma_f32_16x16x32_bf16 v[26:29], v[156:159], v[216:219], v[26:29]
	v_mfma_f32_16x16x32_bf16 v[14:17], v[140:143], v[224:227], v[14:17]
	v_mfma_f32_16x16x32_bf16 v[10:13], v[156:159], v[224:227], v[10:13]
	v_mfma_f32_16x16x32_bf16 v[62:65], v[148:151], v[204:207], v[62:65]
	v_mfma_f32_16x16x32_bf16 v[58:61], v[180:183], v[204:207], v[58:61]
	v_mfma_f32_16x16x32_bf16 v[46:49], v[148:151], v[212:215], v[46:49]
	v_mfma_f32_16x16x32_bf16 v[42:45], v[180:183], v[212:215], v[42:45]
	v_mfma_f32_16x16x32_bf16 v[30:33], v[148:151], v[220:223], v[30:33]
	v_mfma_f32_16x16x32_bf16 v[26:29], v[180:183], v[220:223], v[26:29]
	v_mfma_f32_16x16x32_bf16 v[14:17], v[148:151], v[228:231], v[14:17]
	v_mfma_f32_16x16x32_bf16 v[10:13], v[180:183], v[228:231], v[10:13]
	v_mfma_f32_16x16x32_bf16 v[54:57], v[184:187], v[200:203], v[54:57]
	v_mfma_f32_16x16x32_bf16 v[50:53], v[192:195], v[200:203], v[50:53]
	v_mfma_f32_16x16x32_bf16 v[38:41], v[184:187], v[208:211], v[38:41]
	v_mfma_f32_16x16x32_bf16 v[34:37], v[192:195], v[208:211], v[34:37]
	v_mfma_f32_16x16x32_bf16 v[22:25], v[184:187], v[216:219], v[22:25]
	v_mfma_f32_16x16x32_bf16 v[18:21], v[192:195], v[216:219], v[18:21]
	v_mfma_f32_16x16x32_bf16 v[6:9], v[184:187], v[224:227], v[6:9]
	v_mfma_f32_16x16x32_bf16 v[2:5], v[192:195], v[224:227], v[2:5]
	v_mfma_f32_16x16x32_bf16 v[54:57], v[188:191], v[204:207], v[54:57]
	v_mfma_f32_16x16x32_bf16 v[50:53], v[196:199], v[204:207], v[50:53]
	v_mfma_f32_16x16x32_bf16 v[38:41], v[188:191], v[212:215], v[38:41]
	v_mfma_f32_16x16x32_bf16 v[34:37], v[196:199], v[212:215], v[34:37]
	v_mfma_f32_16x16x32_bf16 v[22:25], v[188:191], v[220:223], v[22:25]
	v_mfma_f32_16x16x32_bf16 v[18:21], v[196:199], v[220:223], v[18:21]
	v_mfma_f32_16x16x32_bf16 v[6:9], v[188:191], v[228:231], v[6:9]
	v_mfma_f32_16x16x32_bf16 v[2:5], v[196:199], v[228:231], v[2:5]
	s_barrier
	s_add_i32 s44, 0, 0x18000
	v_add_u32_e32 v164, s44, v146
	s_add_i32 s45, 0, 0x1c000
	ds_read_b128 v[140:143], v164
	ds_read_b128 v[148:151], v164 offset:1024
	ds_read_b128 v[156:159], v164 offset:2048
	ds_read_b128 v[180:183], v164 offset:3072
	v_add_u32_e32 v164, s45, v146
	ds_read_b128 v[184:187], v164
	ds_read_b128 v[188:191], v164 offset:1024
	ds_read_b128 v[192:195], v164 offset:2048
	ds_read_b128 v[196:199], v164 offset:3072
	s_add_u32 s0, s22, 0x160000
	s_addc_u32 s1, s23, 0
	s_mov_b32 m0, s31
	v_lshl_add_u64 v[170:171], s[0:1], 0, v[130:131]
	ds_read_b128 v[200:203], v147 offset:32768
	ds_read_b128 v[204:207], v147 offset:33792
	ds_read_b128 v[208:211], v147 offset:34816
	ds_read_b128 v[212:215], v147 offset:35840
	ds_read_b128 v[216:219], v147 offset:36864
	ds_read_b128 v[220:223], v147 offset:37888
	ds_read_b128 v[224:227], v147 offset:38912
	ds_read_b128 v[228:231], v147 offset:39936
	global_load_lds_dwordx4 v[170:171], off
	v_lshl_add_u64 v[170:171], s[0:1], 0, v[132:133]
	s_mov_b32 m0, s34
	s_nop 0
	global_load_lds_dwordx4 v[170:171], off
	s_waitcnt vmcnt(8)
	s_waitcnt lgkmcnt(0)
	s_barrier
	s_waitcnt lgkmcnt(0)
	v_mfma_f32_16x16x32_bf16 v[126:129], v[140:143], v[200:203], v[126:129]
	v_mfma_f32_16x16x32_bf16 v[122:125], v[156:159], v[200:203], v[122:125]
	v_mfma_f32_16x16x32_bf16 v[110:113], v[140:143], v[208:211], v[110:113]
	v_mfma_f32_16x16x32_bf16 v[106:109], v[156:159], v[208:211], v[106:109]
	v_mfma_f32_16x16x32_bf16 v[94:97], v[140:143], v[216:219], v[94:97]
	v_mfma_f32_16x16x32_bf16 v[90:93], v[156:159], v[216:219], v[90:93]
	v_mfma_f32_16x16x32_bf16 v[78:81], v[140:143], v[224:227], v[78:81]
	v_mfma_f32_16x16x32_bf16 v[74:77], v[156:159], v[224:227], v[74:77]
	v_mfma_f32_16x16x32_bf16 v[126:129], v[148:151], v[204:207], v[126:129]
	v_mfma_f32_16x16x32_bf16 v[122:125], v[180:183], v[204:207], v[122:125]
	v_mfma_f32_16x16x32_bf16 v[110:113], v[148:151], v[212:215], v[110:113]
	v_mfma_f32_16x16x32_bf16 v[106:109], v[180:183], v[212:215], v[106:109]
	v_mfma_f32_16x16x32_bf16 v[94:97], v[148:151], v[220:223], v[94:97]
	v_mfma_f32_16x16x32_bf16 v[90:93], v[180:183], v[220:223], v[90:93]
	v_mfma_f32_16x16x32_bf16 v[78:81], v[148:151], v[228:231], v[78:81]
	v_mfma_f32_16x16x32_bf16 v[74:77], v[180:183], v[228:231], v[74:77]
	v_mfma_f32_16x16x32_bf16 v[118:121], v[184:187], v[200:203], v[118:121]
	v_mfma_f32_16x16x32_bf16 v[114:117], v[192:195], v[200:203], v[114:117]
	v_mfma_f32_16x16x32_bf16 v[102:105], v[184:187], v[208:211], v[102:105]
	v_mfma_f32_16x16x32_bf16 v[98:101], v[192:195], v[208:211], v[98:101]
	v_mfma_f32_16x16x32_bf16 v[86:89], v[184:187], v[216:219], v[86:89]
	v_mfma_f32_16x16x32_bf16 v[82:85], v[192:195], v[216:219], v[82:85]
	v_mfma_f32_16x16x32_bf16 v[70:73], v[184:187], v[224:227], v[70:73]
	v_mfma_f32_16x16x32_bf16 v[66:69], v[192:195], v[224:227], v[66:69]
	v_mfma_f32_16x16x32_bf16 v[118:121], v[188:191], v[204:207], v[118:121]
	v_mfma_f32_16x16x32_bf16 v[114:117], v[196:199], v[204:207], v[114:117]
	v_mfma_f32_16x16x32_bf16 v[102:105], v[188:191], v[212:215], v[102:105]
	v_mfma_f32_16x16x32_bf16 v[98:101], v[196:199], v[212:215], v[98:101]
	v_mfma_f32_16x16x32_bf16 v[86:89], v[188:191], v[220:223], v[86:89]
	v_mfma_f32_16x16x32_bf16 v[82:85], v[196:199], v[220:223], v[82:85]
	v_mfma_f32_16x16x32_bf16 v[70:73], v[188:191], v[228:231], v[70:73]
	v_mfma_f32_16x16x32_bf16 v[66:69], v[196:199], v[228:231], v[66:69]
	s_barrier
; #define PG8_STAGE(bufoff, gbase, voff) do { _Pragma("unroll") for (int _i = 0; _i < 2; ++_i) \
;         __builtin_amdgcn_global_load_lds((const unsigned*)((const char*)(gbase) + (voff)[_i]), (LAS unsigned*)(lds + (bufoff) + ldsw + _i * 8192), 16, 0, 0); } while (0)
; #define PG8_LDA(dst, b, h) do { _Pragma("unroll") for (int m = 0; m < 4; ++m) _Pragma("unroll") for (int k = 0; k < 2; ++k) dst[m][k] = *(const LAS bf16x8*)(lds + PG8_SA(b, h) + aoff + m * 2048 + k * 1024); } while (0)
; #define PG8_MMA(ai, bj, At, Bt) do { __builtin_amdgcn_s_setprio(1); _Pragma("unroll") for (int m = 0; m < 4; ++m) _Pragma("unroll") for (int n = 0; n < 2; ++n) _Pragma("unroll") for (int k = 0; k < 2; ++k) \
;         acc[ai][bj][m][n] = __builtin_amdgcn_mfma_f32_16x16x32_bf16(Bt[n][k], At[m][k], acc[ai][bj][m][n], 0, 0, 0); __builtin_amdgcn_s_setprio(0); } while (0)
; #define PG8_WAIT_V(n) asm volatile("s_waitcnt vmcnt(" #n ")" ::: "memory")
; #define PG8_WAIT_L(n) asm volatile("s_waitcnt lgkmcnt(" #n ")" ::: "memory")
; #define PG8_BAR __builtin_amdgcn_s_barrier()
; #define PG8_SCHED __builtin_amdgcn_sched_barrier(0)
; template <class Epi, bool ALIGN_EPI>
; __device__ __forceinline__ void gemm_phase(LAS unsigned char* lds, const Gemm g, const StaticOrder& S, const Epi& E) {
;     ...
;             PG8_LDA(At, 1, 1); PG8_STAGE(PG8_SB(1, 0), b3, voffB); PG8_STAGE(PG8_SB(1, 1), b3 + hstepB, voffB); PG8_STAGE(PG8_SA(1, 0), a3, voffA);
;             PG8_WAIT_V(8); PG8_WAIT_L(0); PG8_BAR; PG8_MMA(1, 0, At, B0); PG8_MMA(1, 1, At, B1); PG8_BAR; PG8_SCHED;
;         }
;         if constexpr (ALIGN_EPI) { if (wr == 0) PG8_BAR; }
	s_add_i32 s0, s44, s28
	v_lshl_add_u64 v[144:145], v[144:145], 0, s[94:95]
	s_mov_b32 m0, s0
	ds_read_b128 v[200:203], v147 offset:49152
	ds_read_b128 v[204:207], v147 offset:50176
	ds_read_b128 v[208:211], v147 offset:51200
	ds_read_b128 v[212:215], v147 offset:52224
	ds_read_b128 v[216:219], v147 offset:53248
	ds_read_b128 v[220:223], v147 offset:54272
	ds_read_b128 v[224:227], v147 offset:55296
	ds_read_b128 v[228:231], v147 offset:56320
	global_load_lds_dwordx4 v[144:145], off
	s_add_i32 m0, s0, 0x2000
	s_add_u32 s0, s20, 0x40080
	v_lshl_add_u64 v[144:145], v[152:153], 0, s[94:95]
	s_addc_u32 s1, s21, 0
	s_add_i32 s20, s45, s28
	global_load_lds_dwordx4 v[144:145], off
	v_lshl_add_u64 v[144:145], s[0:1], 0, v[0:1]
	s_mov_b32 m0, s20
	s_nop 0
	global_load_lds_dwordx4 v[144:145], off
	v_lshl_add_u64 v[144:145], s[0:1], 0, v[134:135]
	s_add_i32 m0, s20, 0x2000
	s_nop 0
	global_load_lds_dwordx4 v[144:145], off
	v_lshl_add_u64 v[144:145], v[160:161], 0, s[94:95]
	s_mov_b32 m0, s4
	s_nop 0
	global_load_lds_dwordx4 v[144:145], off
	v_lshl_add_u64 v[144:145], v[162:163], 0, s[94:95]
	s_mov_b32 m0, s35
	s_nop 0
	global_load_lds_dwordx4 v[144:145], off
	s_waitcnt vmcnt(8)
	s_waitcnt lgkmcnt(0)
	s_barrier
	s_waitcnt lgkmcnt(0)
	v_mfma_f32_16x16x32_bf16 v[62:65], v[140:143], v[200:203], v[62:65]
	v_mfma_f32_16x16x32_bf16 v[58:61], v[156:159], v[200:203], v[58:61]
	v_mfma_f32_16x16x32_bf16 v[46:49], v[140:143], v[208:211], v[46:49]
	v_mfma_f32_16x16x32_bf16 v[42:45], v[156:159], v[208:211], v[42:45]
	v_mfma_f32_16x16x32_bf16 v[30:33], v[140:143], v[216:219], v[30:33]
	v_mfma_f32_16x16x32_bf16 v[26:29], v[156:159], v[216:219], v[26:29]
	v_mfma_f32_16x16x32_bf16 v[14:17], v[140:143], v[224:227], v[14:17]
	v_mfma_f32_16x16x32_bf16 v[10:13], v[156:159], v[224:227], v[10:13]
	v_mfma_f32_16x16x32_bf16 v[62:65], v[148:151], v[204:207], v[62:65]
	v_mfma_f32_16x16x32_bf16 v[58:61], v[180:183], v[204:207], v[58:61]
	v_mfma_f32_16x16x32_bf16 v[46:49], v[148:151], v[212:215], v[46:49]
	v_mfma_f32_16x16x32_bf16 v[42:45], v[180:183], v[212:215], v[42:45]
	v_mfma_f32_16x16x32_bf16 v[30:33], v[148:151], v[220:223], v[30:33]
	v_mfma_f32_16x16x32_bf16 v[26:29], v[180:183], v[220:223], v[26:29]
	v_mfma_f32_16x16x32_bf16 v[14:17], v[148:151], v[228:231], v[14:17]
	v_mfma_f32_16x16x32_bf16 v[10:13], v[180:183], v[228:231], v[10:13]
	v_mfma_f32_16x16x32_bf16 v[54:57], v[184:187], v[200:203], v[54:57]
	v_mfma_f32_16x16x32_bf16 v[50:53], v[192:195], v[200:203], v[50:53]
	v_mfma_f32_16x16x32_bf16 v[38:41], v[184:187], v[208:211], v[38:41]
	v_mfma_f32_16x16x32_bf16 v[34:37], v[192:195], v[208:211], v[34:37]
	v_mfma_f32_16x16x32_bf16 v[22:25], v[184:187], v[216:219], v[22:25]
	v_mfma_f32_16x16x32_bf16 v[18:21], v[192:195], v[216:219], v[18:21]
	v_mfma_f32_16x16x32_bf16 v[6:9], v[184:187], v[224:227], v[6:9]
	v_mfma_f32_16x16x32_bf16 v[2:5], v[192:195], v[224:227], v[2:5]
	v_mfma_f32_16x16x32_bf16 v[54:57], v[188:191], v[204:207], v[54:57]
	v_mfma_f32_16x16x32_bf16 v[50:53], v[196:199], v[204:207], v[50:53]
	v_mfma_f32_16x16x32_bf16 v[38:41], v[188:191], v[212:215], v[38:41]
	v_mfma_f32_16x16x32_bf16 v[34:37], v[196:199], v[212:215], v[34:37]
	v_mfma_f32_16x16x32_bf16 v[22:25], v[188:191], v[220:223], v[22:25]
	v_mfma_f32_16x16x32_bf16 v[18:21], v[196:199], v[220:223], v[18:21]
	v_mfma_f32_16x16x32_bf16 v[6:9], v[188:191], v[228:231], v[6:9]
	v_mfma_f32_16x16x32_bf16 v[2:5], v[196:199], v[228:231], v[2:5]
	s_barrier
	s_add_i32 s43, s43, 2
	s_add_u32 s41, s41, 0x100
	s_addc_u32 s42, s42, 0
	s_cmp_gt_u32 s43, 13
	s_mov_b64 s[0:1], s[2:3]
	s_cbranch_scc0 .LBB0_414
	s_and_b64 vcc, exec, s[12:13]
	s_cbranch_vccz .LBB0_417
	s_barrier

; #define PG8_STAGE(bufoff, gbase, voff) do { _Pragma("unroll") for (int _i = 0; _i < 2; ++_i) \
;         __builtin_amdgcn_global_load_lds((const unsigned*)((const char*)(gbase) + (voff)[_i]), (LAS unsigned*)(lds + (bufoff) + ldsw + _i * 8192), 16, 0, 0); } while (0)
; #define PG8_LDA(dst, b, h) do { _Pragma("unroll") for (int m = 0; m < 4; ++m) _Pragma("unroll") for (int k = 0; k < 2; ++k) dst[m][k] = *(const LAS bf16x8*)(lds + PG8_SA(b, h) + aoff + m * 2048 + k * 1024); } while (0)
; #define PG8_LDB(dst, b, h) do { _Pragma("unroll") for (int n = 0; n < 2; ++n) _Pragma("unroll") for (int k = 0; k < 2; ++k) dst[n][k] = *(const LAS bf16x8*)(lds + PG8_SB(b, h) + boff + n * 2048 + k * 1024); } while (0)
; #define PG8_MMA(ai, bj, At, Bt) do { __builtin_amdgcn_s_setprio(1); _Pragma("unroll") for (int m = 0; m < 4; ++m) _Pragma("unroll") for (int n = 0; n < 2; ++n) _Pragma("unroll") for (int k = 0; k < 2; ++k) \
;         acc[ai][bj][m][n] = __builtin_amdgcn_mfma_f32_16x16x32_bf16(Bt[n][k], At[m][k], acc[ai][bj][m][n], 0, 0, 0); __builtin_amdgcn_s_setprio(0); } while (0)
; #define PG8_WAIT_V(n) asm volatile("s_waitcnt vmcnt(" #n ")" ::: "memory")
; #define PG8_WAIT_L(n) asm volatile("s_waitcnt lgkmcnt(" #n ")" ::: "memory")
; #define PG8_BAR __builtin_amdgcn_s_barrier()
; #define PG8_SCHED __builtin_amdgcn_sched_barrier(0)
; template <class Epi, bool ALIGN_EPI>
; __device__ __forceinline__ void gemm_phase(LAS unsigned char* lds, const Gemm g, const StaticOrder& S, const Epi& E) {
;     ...
;             const bool last = (t == nt - 2);
;             const char* a1 = cA + (size_t)(t + 1) * kstep;
;             const char* a2 = last ? nA : cA + (size_t)(t + 2) * kstep; const char* b2 = last ? nB : cB + (size_t)(t + 2) * kstep;
;             const char* a3 = a2 + kstep; const char* b3 = b2 + kstep;
;             PG8_LDB(B0, 0, 0); PG8_LDB(B1, 0, 1); PG8_SCHED; PG8_LDA(At, 0, 0); PG8_STAGE(PG8_SA(1, 1), a1 + hstepA, voffA);
;             PG8_WAIT_V(8); PG8_WAIT_L(0); PG8_BAR; PG8_MMA(0, 0, At, B0); PG8_MMA(0, 1, At, B1); PG8_BAR; PG8_SCHED;
;             PG8_LDA(At, 0, 1); PG8_STAGE(PG8_SB(0, 0), b2, voffB); PG8_STAGE(PG8_SB(0, 1), b2 + hstepB, voffB); PG8_STAGE(PG8_SA(0, 0), a2, voffA);
;             PG8_WAIT_V(8); PG8_WAIT_L(0); PG8_BAR; PG8_MMA(1, 0, At, B0); PG8_MMA(1, 1, At, B1); PG8_BAR; PG8_SCHED;
.LBB0_483:
	s_add_u32 s18, s6, 0xfffc0080
	s_addc_u32 s19, s7, -1
	s_add_i32 s41, 0, 0x10000
	s_cmp_eq_u32 s40, 12
	s_cselect_b32 s21, s1, s19
	s_cselect_b32 s20, s36, s18
	v_add_u32_e32 v152, s41, v140
	s_cselect_b32 s19, s11, s39
	s_cselect_b32 s18, s37, s38
	s_add_i32 s44, 0, 0x14000
	ds_read_b128 v[144:147], v152
	ds_read_b128 v[148:151], v152 offset:1024
	ds_read_b128 v[156:159], v152 offset:2048
	ds_read_b128 v[180:183], v152 offset:3072
	v_add_u32_e32 v152, s44, v140
	ds_read_b128 v[184:187], v152
	ds_read_b128 v[188:191], v152 offset:1024
	ds_read_b128 v[192:195], v152 offset:2048
	ds_read_b128 v[196:199], v152 offset:3072
	v_lshl_add_u64 v[152:153], s[6:7], 0, v[136:137]
	s_add_i32 m0, s25, 0xc000
	ds_read_b128 v[200:203], v142
	ds_read_b128 v[204:207], v142 offset:1024
	ds_read_b128 v[208:211], v142 offset:2048
	ds_read_b128 v[212:215], v142 offset:3072
	ds_read_b128 v[216:219], v142 offset:4096
	ds_read_b128 v[220:223], v142 offset:5120
	ds_read_b128 v[224:227], v142 offset:6144
	ds_read_b128 v[228:231], v142 offset:7168
	global_load_lds_dwordx4 v[152:153], off
	v_lshl_add_u64 v[152:153], s[6:7], 0, v[138:139]
	s_add_i32 m0, s25, 0xe000
	s_nop 0
	global_load_lds_dwordx4 v[152:153], off
	s_waitcnt vmcnt(8)
	s_waitcnt lgkmcnt(0)
	s_barrier
	s_waitcnt lgkmcnt(0)
	v_mfma_f32_16x16x32_bf16 v[126:129], v[144:147], v[200:203], v[126:129]
	v_mfma_f32_16x16x32_bf16 v[122:125], v[156:159], v[200:203], v[122:125]
	v_mfma_f32_16x16x32_bf16 v[110:113], v[144:147], v[208:211], v[110:113]
	v_mfma_f32_16x16x32_bf16 v[106:109], v[156:159], v[208:211], v[106:109]
	v_mfma_f32_16x16x32_bf16 v[94:97], v[144:147], v[216:219], v[94:97]
	v_mfma_f32_16x16x32_bf16 v[90:93], v[156:159], v[216:219], v[90:93]
	v_mfma_f32_16x16x32_bf16 v[78:81], v[144:147], v[224:227], v[78:81]
	v_mfma_f32_16x16x32_bf16 v[74:77], v[156:159], v[224:227], v[74:77]
	v_mfma_f32_16x16x32_bf16 v[126:129], v[148:151], v[204:207], v[126:129]
	v_mfma_f32_16x16x32_bf16 v[122:125], v[180:183], v[204:207], v[122:125]
	v_mfma_f32_16x16x32_bf16 v[110:113], v[148:151], v[212:215], v[110:113]
	v_mfma_f32_16x16x32_bf16 v[106:109], v[180:183], v[212:215], v[106:109]
	v_mfma_f32_16x16x32_bf16 v[94:97], v[148:151], v[220:223], v[94:97]
	v_mfma_f32_16x16x32_bf16 v[90:93], v[180:183], v[220:223], v[90:93]
	v_mfma_f32_16x16x32_bf16 v[78:81], v[148:151], v[228:231], v[78:81]
	v_mfma_f32_16x16x32_bf16 v[74:77], v[180:183], v[228:231], v[74:77]
	v_mfma_f32_16x16x32_bf16 v[118:121], v[184:187], v[200:203], v[118:121]
	v_mfma_f32_16x16x32_bf16 v[114:117], v[192:195], v[200:203], v[114:117]
	v_mfma_f32_16x16x32_bf16 v[102:105], v[184:187], v[208:211], v[102:105]
	v_mfma_f32_16x16x32_bf16 v[98:101], v[192:195], v[208:211], v[98:101]
	v_mfma_f32_16x16x32_bf16 v[86:89], v[184:187], v[216:219], v[86:89]
	v_mfma_f32_16x16x32_bf16 v[82:85], v[192:195], v[216:219], v[82:85]
	v_mfma_f32_16x16x32_bf16 v[70:73], v[184:187], v[224:227], v[70:73]
	v_mfma_f32_16x16x32_bf16 v[66:69], v[192:195], v[224:227], v[66:69]
	v_mfma_f32_16x16x32_bf16 v[118:121], v[188:191], v[204:207], v[118:121]
	v_mfma_f32_16x16x32_bf16 v[114:117], v[196:199], v[204:207], v[114:117]
	v_mfma_f32_16x16x32_bf16 v[102:105], v[188:191], v[212:215], v[102:105]
	v_mfma_f32_16x16x32_bf16 v[98:101], v[196:199], v[212:215], v[98:101]
	v_mfma_f32_16x16x32_bf16 v[86:89], v[188:191], v[220:223], v[86:89]
	v_mfma_f32_16x16x32_bf16 v[82:85], v[196:199], v[220:223], v[82:85]
	v_mfma_f32_16x16x32_bf16 v[70:73], v[188:191], v[228:231], v[70:73]
	v_mfma_f32_16x16x32_bf16 v[66:69], v[196:199], v[228:231], v[66:69]
	s_barrier
	s_add_i32 s41, s41, s24
	v_lshl_add_u64 v[152:153], s[18:19], 0, v[0:1]
	s_mov_b32 m0, s41
	ds_read_b128 v[200:203], v142 offset:16384
	ds_read_b128 v[204:207], v142 offset:17408
	ds_read_b128 v[208:211], v142 offset:18432
	ds_read_b128 v[212:215], v142 offset:19456
	ds_read_b128 v[216:219], v142 offset:20480
	ds_read_b128 v[220:223], v142 offset:21504
	ds_read_b128 v[224:227], v142 offset:22528
	ds_read_b128 v[228:231], v142 offset:23552
	global_load_lds_dwordx4 v[152:153], off
	s_add_i32 m0, s41, 0x2000
	s_add_u32 s42, s18, 0x40000
	v_lshl_add_u64 v[160:161], s[18:19], 0, v[134:135]
	s_addc_u32 s43, s19, 0
	s_add_i32 s41, s44, s24
	global_load_lds_dwordx4 v[160:161], off
	v_lshl_add_u64 v[162:163], s[42:43], 0, v[0:1]
	s_mov_b32 m0, s41
	v_lshl_add_u64 v[170:171], s[20:21], 0, v[132:133]
	global_load_lds_dwordx4 v[162:163], off
	v_lshl_add_u64 v[162:163], s[42:43], 0, v[134:135]
	s_add_i32 m0, s41, 0x2000
	s_nop 0
	global_load_lds_dwordx4 v[162:163], off
	v_lshl_add_u64 v[162:163], s[20:21], 0, v[130:131]
	s_mov_b32 m0, s25
	s_nop 0
	global_load_lds_dwordx4 v[162:163], off
	s_mov_b32 m0, s26
	s_nop 0
	global_load_lds_dwordx4 v[170:171], off
	s_waitcnt vmcnt(8)
	s_waitcnt lgkmcnt(0)
	s_barrier
; #define PG8_STAGE(bufoff, gbase, voff) do { _Pragma("unroll") for (int _i = 0; _i < 2; ++_i) \
;         __builtin_amdgcn_global_load_lds((const unsigned*)((const char*)(gbase) + (voff)[_i]), (LAS unsigned*)(lds + (bufoff) + ldsw + _i * 8192), 16, 0, 0); } while (0)
; #define PG8_LDA(dst, b, h) do { _Pragma("unroll") for (int m = 0; m < 4; ++m) _Pragma("unroll") for (int k = 0; k < 2; ++k) dst[m][k] = *(const LAS bf16x8*)(lds + PG8_SA(b, h) + aoff + m * 2048 + k * 1024); } while (0)
; #define PG8_LDB(dst, b, h) do { _Pragma("unroll") for (int n = 0; n < 2; ++n) _Pragma("unroll") for (int k = 0; k < 2; ++k) dst[n][k] = *(const LAS bf16x8*)(lds + PG8_SB(b, h) + boff + n * 2048 + k * 1024); } while (0)
; #define PG8_MMA(ai, bj, At, Bt) do { __builtin_amdgcn_s_setprio(1); _Pragma("unroll") for (int m = 0; m < 4; ++m) _Pragma("unroll") for (int n = 0; n < 2; ++n) _Pragma("unroll") for (int k = 0; k < 2; ++k) \
;         acc[ai][bj][m][n] = __builtin_amdgcn_mfma_f32_16x16x32_bf16(Bt[n][k], At[m][k], acc[ai][bj][m][n], 0, 0, 0); __builtin_amdgcn_s_setprio(0); } while (0)
; #define PG8_WAIT_V(n) asm volatile("s_waitcnt vmcnt(" #n ")" ::: "memory")
; #define PG8_WAIT_L(n) asm volatile("s_waitcnt lgkmcnt(" #n ")" ::: "memory")
; #define PG8_BAR __builtin_amdgcn_s_barrier()
; #define PG8_SCHED __builtin_amdgcn_sched_barrier(0)
; template <class Epi, bool ALIGN_EPI>
; __device__ __forceinline__ void gemm_phase(LAS unsigned char* lds, const Gemm g, const StaticOrder& S, const Epi& E) {
;     ...
;             PG8_WAIT_V(8); PG8_WAIT_L(0); PG8_BAR; PG8_MMA(1, 0, At, B0); PG8_MMA(1, 1, At, B1); PG8_BAR; PG8_SCHED;
;             PG8_LDB(B0, 1, 0); PG8_LDB(B1, 1, 1); PG8_SCHED; PG8_LDA(At, 1, 0); PG8_STAGE(PG8_SA(0, 1), a2 + hstepA, voffA);
;             PG8_WAIT_V(8); PG8_WAIT_L(0); PG8_BAR; PG8_MMA(0, 0, At, B0); PG8_MMA(0, 1, At, B1); PG8_BAR; PG8_SCHED;
	s_waitcnt lgkmcnt(0)
	v_mfma_f32_16x16x32_bf16 v[62:65], v[144:147], v[200:203], v[62:65]
	v_mfma_f32_16x16x32_bf16 v[58:61], v[156:159], v[200:203], v[58:61]
	v_mfma_f32_16x16x32_bf16 v[46:49], v[144:147], v[208:211], v[46:49]
	v_mfma_f32_16x16x32_bf16 v[42:45], v[156:159], v[208:211], v[42:45]
	v_mfma_f32_16x16x32_bf16 v[30:33], v[144:147], v[216:219], v[30:33]
	v_mfma_f32_16x16x32_bf16 v[26:29], v[156:159], v[216:219], v[26:29]
	v_mfma_f32_16x16x32_bf16 v[14:17], v[144:147], v[224:227], v[14:17]
	v_mfma_f32_16x16x32_bf16 v[10:13], v[156:159], v[224:227], v[10:13]
	v_mfma_f32_16x16x32_bf16 v[62:65], v[148:151], v[204:207], v[62:65]
	v_mfma_f32_16x16x32_bf16 v[58:61], v[180:183], v[204:207], v[58:61]
	v_mfma_f32_16x16x32_bf16 v[46:49], v[148:151], v[212:215], v[46:49]
	v_mfma_f32_16x16x32_bf16 v[42:45], v[180:183], v[212:215], v[42:45]
	v_mfma_f32_16x16x32_bf16 v[30:33], v[148:151], v[220:223], v[30:33]
	v_mfma_f32_16x16x32_bf16 v[26:29], v[180:183], v[220:223], v[26:29]
	v_mfma_f32_16x16x32_bf16 v[14:17], v[148:151], v[228:231], v[14:17]
	v_mfma_f32_16x16x32_bf16 v[10:13], v[180:183], v[228:231], v[10:13]
	v_mfma_f32_16x16x32_bf16 v[54:57], v[184:187], v[200:203], v[54:57]
	v_mfma_f32_16x16x32_bf16 v[50:53], v[192:195], v[200:203], v[50:53]
	v_mfma_f32_16x16x32_bf16 v[38:41], v[184:187], v[208:211], v[38:41]
	v_mfma_f32_16x16x32_bf16 v[34:37], v[192:195], v[208:211], v[34:37]
	v_mfma_f32_16x16x32_bf16 v[22:25], v[184:187], v[216:219], v[22:25]
	v_mfma_f32_16x16x32_bf16 v[18:21], v[192:195], v[216:219], v[18:21]
	v_mfma_f32_16x16x32_bf16 v[6:9], v[184:187], v[224:227], v[6:9]
	v_mfma_f32_16x16x32_bf16 v[2:5], v[192:195], v[224:227], v[2:5]
	v_mfma_f32_16x16x32_bf16 v[54:57], v[188:191], v[204:207], v[54:57]
	v_mfma_f32_16x16x32_bf16 v[50:53], v[196:199], v[204:207], v[50:53]
	v_mfma_f32_16x16x32_bf16 v[38:41], v[188:191], v[212:215], v[38:41]
	v_mfma_f32_16x16x32_bf16 v[34:37], v[196:199], v[212:215], v[34:37]
	v_mfma_f32_16x16x32_bf16 v[22:25], v[188:191], v[220:223], v[22:25]
	v_mfma_f32_16x16x32_bf16 v[18:21], v[196:199], v[220:223], v[18:21]
	v_mfma_f32_16x16x32_bf16 v[6:9], v[188:191], v[228:231], v[6:9]
	v_mfma_f32_16x16x32_bf16 v[2:5], v[196:199], v[228:231], v[2:5]
	s_barrier
	s_add_i32 s41, 0, 0x18000
	v_add_u32_e32 v164, s41, v140
	s_add_i32 s42, 0, 0x1c000
	ds_read_b128 v[144:147], v164
	ds_read_b128 v[148:151], v164 offset:1024
	ds_read_b128 v[156:159], v164 offset:2048
	ds_read_b128 v[180:183], v164 offset:3072
	v_add_u32_e32 v164, s42, v140
	ds_read_b128 v[184:187], v164
	ds_read_b128 v[188:191], v164 offset:1024
	ds_read_b128 v[192:195], v164 offset:2048
	ds_read_b128 v[196:199], v164 offset:3072
	s_add_u32 s20, s20, 0x40000
	s_addc_u32 s21, s21, 0
	s_mov_b32 m0, s27
	v_lshl_add_u64 v[172:173], s[20:21], 0, v[130:131]
	ds_read_b128 v[200:203], v142 offset:32768
	ds_read_b128 v[204:207], v142 offset:33792
	ds_read_b128 v[208:211], v142 offset:34816
	ds_read_b128 v[212:215], v142 offset:35840
	ds_read_b128 v[216:219], v142 offset:36864
	ds_read_b128 v[220:223], v142 offset:37888
	ds_read_b128 v[224:227], v142 offset:38912
	ds_read_b128 v[228:231], v142 offset:39936
	global_load_lds_dwordx4 v[172:173], off
	v_lshl_add_u64 v[172:173], s[20:21], 0, v[132:133]
	s_mov_b32 m0, s28
	s_nop 0
	global_load_lds_dwordx4 v[172:173], off
	s_waitcnt vmcnt(8)
	s_waitcnt lgkmcnt(0)
	s_barrier
	s_waitcnt lgkmcnt(0)
	v_mfma_f32_16x16x32_bf16 v[126:129], v[144:147], v[200:203], v[126:129]
	v_mfma_f32_16x16x32_bf16 v[122:125], v[156:159], v[200:203], v[122:125]
	v_mfma_f32_16x16x32_bf16 v[110:113], v[144:147], v[208:211], v[110:113]
	v_mfma_f32_16x16x32_bf16 v[106:109], v[156:159], v[208:211], v[106:109]
	v_mfma_f32_16x16x32_bf16 v[94:97], v[144:147], v[216:219], v[94:97]
	v_mfma_f32_16x16x32_bf16 v[90:93], v[156:159], v[216:219], v[90:93]
	v_mfma_f32_16x16x32_bf16 v[78:81], v[144:147], v[224:227], v[78:81]
	v_mfma_f32_16x16x32_bf16 v[74:77], v[156:159], v[224:227], v[74:77]
	v_mfma_f32_16x16x32_bf16 v[126:129], v[148:151], v[204:207], v[126:129]
	v_mfma_f32_16x16x32_bf16 v[122:125], v[180:183], v[204:207], v[122:125]
	v_mfma_f32_16x16x32_bf16 v[110:113], v[148:151], v[212:215], v[110:113]
	v_mfma_f32_16x16x32_bf16 v[106:109], v[180:183], v[212:215], v[106:109]
	v_mfma_f32_16x16x32_bf16 v[94:97], v[148:151], v[220:223], v[94:97]
	v_mfma_f32_16x16x32_bf16 v[90:93], v[180:183], v[220:223], v[90:93]
	v_mfma_f32_16x16x32_bf16 v[78:81], v[148:151], v[228:231], v[78:81]
	v_mfma_f32_16x16x32_bf16 v[74:77], v[180:183], v[228:231], v[74:77]
	v_mfma_f32_16x16x32_bf16 v[118:121], v[184:187], v[200:203], v[118:121]
	v_mfma_f32_16x16x32_bf16 v[114:117], v[192:195], v[200:203], v[114:117]
	v_mfma_f32_16x16x32_bf16 v[102:105], v[184:187], v[208:211], v[102:105]
	v_mfma_f32_16x16x32_bf16 v[98:101], v[192:195], v[208:211], v[98:101]
	v_mfma_f32_16x16x32_bf16 v[86:89], v[184:187], v[216:219], v[86:89]
	v_mfma_f32_16x16x32_bf16 v[82:85], v[192:195], v[216:219], v[82:85]
	v_mfma_f32_16x16x32_bf16 v[70:73], v[184:187], v[224:227], v[70:73]
	v_mfma_f32_16x16x32_bf16 v[66:69], v[192:195], v[224:227], v[66:69]
	v_mfma_f32_16x16x32_bf16 v[118:121], v[188:191], v[204:207], v[118:121]
	v_mfma_f32_16x16x32_bf16 v[114:117], v[196:199], v[204:207], v[114:117]
	v_mfma_f32_16x16x32_bf16 v[102:105], v[188:191], v[212:215], v[102:105]
	v_mfma_f32_16x16x32_bf16 v[98:101], v[196:199], v[212:215], v[98:101]
	v_mfma_f32_16x16x32_bf16 v[86:89], v[188:191], v[220:223], v[86:89]
	v_mfma_f32_16x16x32_bf16 v[82:85], v[196:199], v[220:223], v[82:85]
	v_mfma_f32_16x16x32_bf16 v[70:73], v[188:191], v[228:231], v[70:73]
	v_mfma_f32_16x16x32_bf16 v[66:69], v[196:199], v[228:231], v[66:69]
	s_barrier
; #define PG8_STAGE(bufoff, gbase, voff) do { _Pragma("unroll") for (int _i = 0; _i < 2; ++_i) \
;         __builtin_amdgcn_global_load_lds((const unsigned*)((const char*)(gbase) + (voff)[_i]), (LAS unsigned*)(lds + (bufoff) + ldsw + _i * 8192), 16, 0, 0); } while (0)
; #define PG8_LDA(dst, b, h) do { _Pragma("unroll") for (int m = 0; m < 4; ++m) _Pragma("unroll") for (int k = 0; k < 2; ++k) dst[m][k] = *(const LAS bf16x8*)(lds + PG8_SA(b, h) + aoff + m * 2048 + k * 1024); } while (0)
; #define PG8_MMA(ai, bj, At, Bt) do { __builtin_amdgcn_s_setprio(1); _Pragma("unroll") for (int m = 0; m < 4; ++m) _Pragma("unroll") for (int n = 0; n < 2; ++n) _Pragma("unroll") for (int k = 0; k < 2; ++k) \
;         acc[ai][bj][m][n] = __builtin_amdgcn_mfma_f32_16x16x32_bf16(Bt[n][k], At[m][k], acc[ai][bj][m][n], 0, 0, 0); __builtin_amdgcn_s_setprio(0); } while (0)
; #define PG8_WAIT_V(n) asm volatile("s_waitcnt vmcnt(" #n ")" ::: "memory")
; #define PG8_WAIT_L(n) asm volatile("s_waitcnt lgkmcnt(" #n ")" ::: "memory")
; #define PG8_BAR __builtin_amdgcn_s_barrier()
; #define PG8_SCHED __builtin_amdgcn_sched_barrier(0)
; template <class Epi, bool ALIGN_EPI>
; __device__ __forceinline__ void gemm_phase(LAS unsigned char* lds, const Gemm g, const StaticOrder& S, const Epi& E) {
;     ...
;             PG8_LDA(At, 1, 1); PG8_STAGE(PG8_SB(1, 0), b3, voffB); PG8_STAGE(PG8_SB(1, 1), b3 + hstepB, voffB); PG8_STAGE(PG8_SA(1, 0), a3, voffA);
;             PG8_WAIT_V(8); PG8_WAIT_L(0); PG8_BAR; PG8_MMA(1, 0, At, B0); PG8_MMA(1, 1, At, B1); PG8_BAR; PG8_SCHED;
;         }
;         if constexpr (ALIGN_EPI) { if (wr == 0) PG8_BAR; }
	s_add_i32 s20, s41, s24
	v_lshl_add_u64 v[152:153], v[152:153], 0, s[94:95]
	s_mov_b32 m0, s20
	ds_read_b128 v[200:203], v142 offset:49152
	ds_read_b128 v[204:207], v142 offset:50176
	ds_read_b128 v[208:211], v142 offset:51200
	ds_read_b128 v[212:215], v142 offset:52224
	ds_read_b128 v[216:219], v142 offset:53248
	ds_read_b128 v[220:223], v142 offset:54272
	ds_read_b128 v[224:227], v142 offset:55296
	ds_read_b128 v[228:231], v142 offset:56320
	global_load_lds_dwordx4 v[152:153], off
	s_add_i32 m0, s20, 0x2000
	s_add_u32 s18, s18, 0x40080
	v_lshl_add_u64 v[152:153], v[160:161], 0, s[94:95]
	s_addc_u32 s19, s19, 0
	s_add_i32 s20, s42, s24
	global_load_lds_dwordx4 v[152:153], off
	v_lshl_add_u64 v[152:153], s[18:19], 0, v[0:1]
	s_mov_b32 m0, s20
	s_nop 0
	global_load_lds_dwordx4 v[152:153], off
	v_lshl_add_u64 v[152:153], s[18:19], 0, v[134:135]
	s_add_i32 m0, s20, 0x2000
	s_nop 0
	global_load_lds_dwordx4 v[152:153], off
	v_lshl_add_u64 v[152:153], v[162:163], 0, s[94:95]
	s_mov_b32 m0, s4
	s_nop 0
	global_load_lds_dwordx4 v[152:153], off
	v_lshl_add_u64 v[152:153], v[170:171], 0, s[94:95]
	s_mov_b32 m0, s29
	s_nop 0
	global_load_lds_dwordx4 v[152:153], off
	s_waitcnt vmcnt(8)
	s_waitcnt lgkmcnt(0)
	s_barrier
	s_waitcnt lgkmcnt(0)
	v_mfma_f32_16x16x32_bf16 v[62:65], v[144:147], v[200:203], v[62:65]
	v_mfma_f32_16x16x32_bf16 v[58:61], v[156:159], v[200:203], v[58:61]
	v_mfma_f32_16x16x32_bf16 v[46:49], v[144:147], v[208:211], v[46:49]
	v_mfma_f32_16x16x32_bf16 v[42:45], v[156:159], v[208:211], v[42:45]
	v_mfma_f32_16x16x32_bf16 v[30:33], v[144:147], v[216:219], v[30:33]
	v_mfma_f32_16x16x32_bf16 v[26:29], v[156:159], v[216:219], v[26:29]
	v_mfma_f32_16x16x32_bf16 v[14:17], v[144:147], v[224:227], v[14:17]
	v_mfma_f32_16x16x32_bf16 v[10:13], v[156:159], v[224:227], v[10:13]
	v_mfma_f32_16x16x32_bf16 v[62:65], v[148:151], v[204:207], v[62:65]
	v_mfma_f32_16x16x32_bf16 v[58:61], v[180:183], v[204:207], v[58:61]
	v_mfma_f32_16x16x32_bf16 v[46:49], v[148:151], v[212:215], v[46:49]
	v_mfma_f32_16x16x32_bf16 v[42:45], v[180:183], v[212:215], v[42:45]
	v_mfma_f32_16x16x32_bf16 v[30:33], v[148:151], v[220:223], v[30:33]
	v_mfma_f32_16x16x32_bf16 v[26:29], v[180:183], v[220:223], v[26:29]
	v_mfma_f32_16x16x32_bf16 v[14:17], v[148:151], v[228:231], v[14:17]
	v_mfma_f32_16x16x32_bf16 v[10:13], v[180:183], v[228:231], v[10:13]
	v_mfma_f32_16x16x32_bf16 v[54:57], v[184:187], v[200:203], v[54:57]
	v_mfma_f32_16x16x32_bf16 v[50:53], v[192:195], v[200:203], v[50:53]
	v_mfma_f32_16x16x32_bf16 v[38:41], v[184:187], v[208:211], v[38:41]
	v_mfma_f32_16x16x32_bf16 v[34:37], v[192:195], v[208:211], v[34:37]
	v_mfma_f32_16x16x32_bf16 v[22:25], v[184:187], v[216:219], v[22:25]
	v_mfma_f32_16x16x32_bf16 v[18:21], v[192:195], v[216:219], v[18:21]
	v_mfma_f32_16x16x32_bf16 v[6:9], v[184:187], v[224:227], v[6:9]
	v_mfma_f32_16x16x32_bf16 v[2:5], v[192:195], v[224:227], v[2:5]
	v_mfma_f32_16x16x32_bf16 v[54:57], v[188:191], v[204:207], v[54:57]
	v_mfma_f32_16x16x32_bf16 v[50:53], v[196:199], v[204:207], v[50:53]
	v_mfma_f32_16x16x32_bf16 v[38:41], v[188:191], v[212:215], v[38:41]
	v_mfma_f32_16x16x32_bf16 v[34:37], v[196:199], v[212:215], v[34:37]
	v_mfma_f32_16x16x32_bf16 v[22:25], v[188:191], v[220:223], v[22:25]
	v_mfma_f32_16x16x32_bf16 v[18:21], v[196:199], v[220:223], v[18:21]
	v_mfma_f32_16x16x32_bf16 v[6:9], v[188:191], v[228:231], v[6:9]
	v_mfma_f32_16x16x32_bf16 v[2:5], v[196:199], v[228:231], v[2:5]
	s_barrier
	s_add_i32 s40, s40, 2
	s_add_u32 s6, s6, 0x100
	s_addc_u32 s7, s7, 0
	s_add_u32 s38, s38, 0x100
	s_addc_u32 s39, s39, 0
	s_cmp_gt_u32 s40, 13
	s_cbranch_scc0 .LBB0_483
	s_and_b64 vcc, exec, s[8:9]
	s_cbranch_vccz .LBB0_486
	s_barrier

; #define PG8_STAGE(bufoff, gbase, voff) do { _Pragma("unroll") for (int _i = 0; _i < 2; ++_i) \
;         __builtin_amdgcn_global_load_lds((const unsigned*)((const char*)(gbase) + (voff)[_i]), (LAS unsigned*)(lds + (bufoff) + ldsw + _i * 8192), 16, 0, 0); } while (0)
; #define PG8_LDA(dst, b, h) do { _Pragma("unroll") for (int m = 0; m < 4; ++m) _Pragma("unroll") for (int k = 0; k < 2; ++k) dst[m][k] = *(const LAS bf16x8*)(lds + PG8_SA(b, h) + aoff + m * 2048 + k * 1024); } while (0)
; #define PG8_LDB(dst, b, h) do { _Pragma("unroll") for (int n = 0; n < 2; ++n) _Pragma("unroll") for (int k = 0; k < 2; ++k) dst[n][k] = *(const LAS bf16x8*)(lds + PG8_SB(b, h) + boff + n * 2048 + k * 1024); } while (0)
; #define PG8_MMA(ai, bj, At, Bt) do { __builtin_amdgcn_s_setprio(1); _Pragma("unroll") for (int m = 0; m < 4; ++m) _Pragma("unroll") for (int n = 0; n < 2; ++n) _Pragma("unroll") for (int k = 0; k < 2; ++k) \
;         acc[ai][bj][m][n] = __builtin_amdgcn_mfma_f32_16x16x32_bf16(Bt[n][k], At[m][k], acc[ai][bj][m][n], 0, 0, 0); __builtin_amdgcn_s_setprio(0); } while (0)
; #define PG8_WAIT_V(n) asm volatile("s_waitcnt vmcnt(" #n ")" ::: "memory")
; #define PG8_WAIT_L(n) asm volatile("s_waitcnt lgkmcnt(" #n ")" ::: "memory")
; #define PG8_BAR __builtin_amdgcn_s_barrier()
; #define PG8_SCHED __builtin_amdgcn_sched_barrier(0)
; template <class Epi, bool ALIGN_EPI>
; __device__ __forceinline__ void gemm_phase(LAS unsigned char* lds, const Gemm g, const StaticOrder& S, const Epi& E) {
;     ...
;             const bool last = (t == nt - 2);
;             const char* a1 = cA + (size_t)(t + 1) * kstep;
;             const char* a2 = last ? nA : cA + (size_t)(t + 2) * kstep; const char* b2 = last ? nB : cB + (size_t)(t + 2) * kstep;
;             const char* a3 = a2 + kstep; const char* b3 = b2 + kstep;
;             PG8_LDB(B0, 0, 0); PG8_LDB(B1, 0, 1); PG8_SCHED; PG8_LDA(At, 0, 0); PG8_STAGE(PG8_SA(1, 1), a1 + hstepA, voffA);
;             PG8_WAIT_V(8); PG8_WAIT_L(0); PG8_BAR; PG8_MMA(0, 0, At, B0); PG8_MMA(0, 1, At, B1); PG8_BAR; PG8_SCHED;
;             PG8_LDA(At, 0, 1); PG8_STAGE(PG8_SB(0, 0), b2, voffB); PG8_STAGE(PG8_SB(0, 1), b2 + hstepB, voffB); PG8_STAGE(PG8_SA(0, 0), a2, voffA);
;             PG8_WAIT_V(8); PG8_WAIT_L(0); PG8_BAR; PG8_MMA(1, 0, At, B0); PG8_MMA(1, 1, At, B1); PG8_BAR; PG8_SCHED;
.LBB0_603:
	s_add_u32 s24, s6, 0xfffc0080
	s_addc_u32 s25, s7, -1
	s_add_i32 s45, 0, 0x10000
	s_cmp_eq_u32 s44, 12
	s_cselect_b32 s27, s9, s25
	s_cselect_b32 s26, s40, s24
	v_add_u32_e32 v0, s45, v158
	s_cselect_b32 s25, s15, s43
	s_cselect_b32 s24, s41, s42
	s_add_i32 s48, 0, 0x14000
	ds_read_b128 v[142:145], v0
	ds_read_b128 v[146:149], v0 offset:1024
	ds_read_b128 v[150:153], v0 offset:2048
	ds_read_b128 v[180:183], v0 offset:3072
	v_add_u32_e32 v0, s48, v158
	ds_read_b128 v[184:187], v0
	ds_read_b128 v[188:191], v0 offset:1024
	ds_read_b128 v[192:195], v0 offset:2048
	ds_read_b128 v[196:199], v0 offset:3072
	v_lshl_add_u64 v[156:157], s[6:7], 0, v[138:139]
	s_add_i32 m0, s30, 0xc000
	ds_read_b128 v[200:203], v160
	ds_read_b128 v[204:207], v160 offset:1024
	ds_read_b128 v[208:211], v160 offset:2048
	ds_read_b128 v[212:215], v160 offset:3072
	ds_read_b128 v[216:219], v160 offset:4096
	ds_read_b128 v[220:223], v160 offset:5120
	ds_read_b128 v[224:227], v160 offset:6144
	ds_read_b128 v[228:231], v160 offset:7168
	global_load_lds_dwordx4 v[156:157], off
	v_lshl_add_u64 v[156:157], s[6:7], 0, v[140:141]
	s_add_i32 m0, s30, 0xe000
	s_nop 0
	global_load_lds_dwordx4 v[156:157], off
	s_waitcnt vmcnt(8)
	s_waitcnt lgkmcnt(0)
	s_barrier
	s_waitcnt lgkmcnt(0)
	v_mfma_f32_16x16x32_bf16 v[66:69], v[142:145], v[200:203], v[66:69]
	v_mfma_f32_16x16x32_bf16 v[58:61], v[150:153], v[200:203], v[58:61]
	v_mfma_f32_16x16x32_bf16 v[54:57], v[142:145], v[208:211], v[54:57]
	v_mfma_f32_16x16x32_bf16 v[50:53], v[150:153], v[208:211], v[50:53]
	v_mfma_f32_16x16x32_bf16 v[46:49], v[142:145], v[216:219], v[46:49]
	v_mfma_f32_16x16x32_bf16 v[42:45], v[150:153], v[216:219], v[42:45]
	v_mfma_f32_16x16x32_bf16 v[38:41], v[142:145], v[224:227], v[38:41]
	v_mfma_f32_16x16x32_bf16 v[34:37], v[150:153], v[224:227], v[34:37]
	v_mfma_f32_16x16x32_bf16 v[66:69], v[146:149], v[204:207], v[66:69]
	v_mfma_f32_16x16x32_bf16 v[58:61], v[180:183], v[204:207], v[58:61]
	v_mfma_f32_16x16x32_bf16 v[54:57], v[146:149], v[212:215], v[54:57]
	v_mfma_f32_16x16x32_bf16 v[50:53], v[180:183], v[212:215], v[50:53]
	v_mfma_f32_16x16x32_bf16 v[46:49], v[146:149], v[220:223], v[46:49]
	v_mfma_f32_16x16x32_bf16 v[42:45], v[180:183], v[220:223], v[42:45]
	v_mfma_f32_16x16x32_bf16 v[38:41], v[146:149], v[228:231], v[38:41]
	v_mfma_f32_16x16x32_bf16 v[34:37], v[180:183], v[228:231], v[34:37]
	v_mfma_f32_16x16x32_bf16 v[126:129], v[184:187], v[200:203], v[126:129]
	v_mfma_f32_16x16x32_bf16 v[122:125], v[192:195], v[200:203], v[122:125]
	v_mfma_f32_16x16x32_bf16 v[118:121], v[184:187], v[208:211], v[118:121]
	v_mfma_f32_16x16x32_bf16 v[114:117], v[192:195], v[208:211], v[114:117]
	v_mfma_f32_16x16x32_bf16 v[110:113], v[184:187], v[216:219], v[110:113]
	v_mfma_f32_16x16x32_bf16 v[106:109], v[192:195], v[216:219], v[106:109]
	v_mfma_f32_16x16x32_bf16 v[102:105], v[184:187], v[224:227], v[102:105]
	v_mfma_f32_16x16x32_bf16 v[98:101], v[192:195], v[224:227], v[98:101]
	v_mfma_f32_16x16x32_bf16 v[126:129], v[188:191], v[204:207], v[126:129]
	v_mfma_f32_16x16x32_bf16 v[122:125], v[196:199], v[204:207], v[122:125]
	v_mfma_f32_16x16x32_bf16 v[118:121], v[188:191], v[212:215], v[118:121]
	v_mfma_f32_16x16x32_bf16 v[114:117], v[196:199], v[212:215], v[114:117]
	v_mfma_f32_16x16x32_bf16 v[110:113], v[188:191], v[220:223], v[110:113]
	v_mfma_f32_16x16x32_bf16 v[106:109], v[196:199], v[220:223], v[106:109]
	v_mfma_f32_16x16x32_bf16 v[102:105], v[188:191], v[228:231], v[102:105]
	v_mfma_f32_16x16x32_bf16 v[98:101], v[196:199], v[228:231], v[98:101]
	s_barrier
	s_add_i32 s45, s45, s29
	v_lshl_add_u64 v[156:157], s[24:25], 0, v[132:133]
	s_mov_b32 m0, s45
	ds_read_b128 v[200:203], v160 offset:16384
	ds_read_b128 v[204:207], v160 offset:17408
	ds_read_b128 v[208:211], v160 offset:18432
	ds_read_b128 v[212:215], v160 offset:19456
	ds_read_b128 v[216:219], v160 offset:20480
	ds_read_b128 v[220:223], v160 offset:21504
	ds_read_b128 v[224:227], v160 offset:22528
	ds_read_b128 v[228:231], v160 offset:23552
	global_load_lds_dwordx4 v[156:157], off
	s_add_i32 m0, s45, 0x2000
	s_add_u32 s46, s24, 0x40000
	v_lshl_add_u64 v[162:163], s[24:25], 0, v[136:137]
	s_addc_u32 s47, s25, 0
	s_add_i32 s45, s48, s29
	global_load_lds_dwordx4 v[162:163], off
	v_lshl_add_u64 v[170:171], s[46:47], 0, v[132:133]
	s_mov_b32 m0, s45
	v_lshl_add_u64 v[172:173], s[26:27], 0, v[134:135]
	global_load_lds_dwordx4 v[170:171], off
	v_lshl_add_u64 v[170:171], s[46:47], 0, v[136:137]
	s_add_i32 m0, s45, 0x2000
	s_nop 0
	global_load_lds_dwordx4 v[170:171], off
	v_lshl_add_u64 v[170:171], s[26:27], 0, v[130:131]
	s_mov_b32 m0, s30
	s_nop 0
	global_load_lds_dwordx4 v[170:171], off
	s_mov_b32 m0, s31
	s_nop 0
	global_load_lds_dwordx4 v[172:173], off
	s_waitcnt vmcnt(8)
	s_waitcnt lgkmcnt(0)
	s_barrier
; #define PG8_STAGE(bufoff, gbase, voff) do { _Pragma("unroll") for (int _i = 0; _i < 2; ++_i) \
;         __builtin_amdgcn_global_load_lds((const unsigned*)((const char*)(gbase) + (voff)[_i]), (LAS unsigned*)(lds + (bufoff) + ldsw + _i * 8192), 16, 0, 0); } while (0)
; #define PG8_LDA(dst, b, h) do { _Pragma("unroll") for (int m = 0; m < 4; ++m) _Pragma("unroll") for (int k = 0; k < 2; ++k) dst[m][k] = *(const LAS bf16x8*)(lds + PG8_SA(b, h) + aoff + m * 2048 + k * 1024); } while (0)
; #define PG8_LDB(dst, b, h) do { _Pragma("unroll") for (int n = 0; n < 2; ++n) _Pragma("unroll") for (int k = 0; k < 2; ++k) dst[n][k] = *(const LAS bf16x8*)(lds + PG8_SB(b, h) + boff + n * 2048 + k * 1024); } while (0)
; #define PG8_MMA(ai, bj, At, Bt) do { __builtin_amdgcn_s_setprio(1); _Pragma("unroll") for (int m = 0; m < 4; ++m) _Pragma("unroll") for (int n = 0; n < 2; ++n) _Pragma("unroll") for (int k = 0; k < 2; ++k) \
;         acc[ai][bj][m][n] = __builtin_amdgcn_mfma_f32_16x16x32_bf16(Bt[n][k], At[m][k], acc[ai][bj][m][n], 0, 0, 0); __builtin_amdgcn_s_setprio(0); } while (0)
; #define PG8_WAIT_V(n) asm volatile("s_waitcnt vmcnt(" #n ")" ::: "memory")
; #define PG8_WAIT_L(n) asm volatile("s_waitcnt lgkmcnt(" #n ")" ::: "memory")
; #define PG8_BAR __builtin_amdgcn_s_barrier()
; #define PG8_SCHED __builtin_amdgcn_sched_barrier(0)
; template <class Epi, bool ALIGN_EPI>
; __device__ __forceinline__ void gemm_phase(LAS unsigned char* lds, const Gemm g, const StaticOrder& S, const Epi& E) {
;     ...
;             PG8_WAIT_V(8); PG8_WAIT_L(0); PG8_BAR; PG8_MMA(1, 0, At, B0); PG8_MMA(1, 1, At, B1); PG8_BAR; PG8_SCHED;
;             PG8_LDB(B0, 1, 0); PG8_LDB(B1, 1, 1); PG8_SCHED; PG8_LDA(At, 1, 0); PG8_STAGE(PG8_SA(0, 1), a2 + hstepA, voffA);
;             PG8_WAIT_V(8); PG8_WAIT_L(0); PG8_BAR; PG8_MMA(0, 0, At, B0); PG8_MMA(0, 1, At, B1); PG8_BAR; PG8_SCHED;
	s_waitcnt lgkmcnt(0)
	v_mfma_f32_16x16x32_bf16 v[30:33], v[142:145], v[200:203], v[30:33]
	v_mfma_f32_16x16x32_bf16 v[26:29], v[150:153], v[200:203], v[26:29]
	v_mfma_f32_16x16x32_bf16 v[22:25], v[142:145], v[208:211], v[22:25]
	v_mfma_f32_16x16x32_bf16 v[18:21], v[150:153], v[208:211], v[18:21]
	v_mfma_f32_16x16x32_bf16 v[14:17], v[142:145], v[216:219], v[14:17]
	v_mfma_f32_16x16x32_bf16 v[10:13], v[150:153], v[216:219], v[10:13]
	v_mfma_f32_16x16x32_bf16 v[6:9], v[142:145], v[224:227], v[6:9]
	v_mfma_f32_16x16x32_bf16 v[2:5], v[150:153], v[224:227], v[2:5]
	v_mfma_f32_16x16x32_bf16 v[30:33], v[146:149], v[204:207], v[30:33]
	v_mfma_f32_16x16x32_bf16 v[26:29], v[180:183], v[204:207], v[26:29]
	v_mfma_f32_16x16x32_bf16 v[22:25], v[146:149], v[212:215], v[22:25]
	v_mfma_f32_16x16x32_bf16 v[18:21], v[180:183], v[212:215], v[18:21]
	v_mfma_f32_16x16x32_bf16 v[14:17], v[146:149], v[220:223], v[14:17]
	v_mfma_f32_16x16x32_bf16 v[10:13], v[180:183], v[220:223], v[10:13]
	v_mfma_f32_16x16x32_bf16 v[6:9], v[146:149], v[228:231], v[6:9]
	v_mfma_f32_16x16x32_bf16 v[2:5], v[180:183], v[228:231], v[2:5]
	v_mfma_f32_16x16x32_bf16 v[94:97], v[184:187], v[200:203], v[94:97]
	v_mfma_f32_16x16x32_bf16 v[90:93], v[192:195], v[200:203], v[90:93]
	v_mfma_f32_16x16x32_bf16 v[86:89], v[184:187], v[208:211], v[86:89]
	v_mfma_f32_16x16x32_bf16 v[82:85], v[192:195], v[208:211], v[82:85]
	v_mfma_f32_16x16x32_bf16 v[78:81], v[184:187], v[216:219], v[78:81]
	v_mfma_f32_16x16x32_bf16 v[74:77], v[192:195], v[216:219], v[74:77]
	v_mfma_f32_16x16x32_bf16 v[70:73], v[184:187], v[224:227], v[70:73]
	v_mfma_f32_16x16x32_bf16 v[62:65], v[192:195], v[224:227], v[62:65]
	v_mfma_f32_16x16x32_bf16 v[94:97], v[188:191], v[204:207], v[94:97]
	v_mfma_f32_16x16x32_bf16 v[90:93], v[196:199], v[204:207], v[90:93]
	v_mfma_f32_16x16x32_bf16 v[86:89], v[188:191], v[212:215], v[86:89]
	v_mfma_f32_16x16x32_bf16 v[82:85], v[196:199], v[212:215], v[82:85]
	v_mfma_f32_16x16x32_bf16 v[78:81], v[188:191], v[220:223], v[78:81]
	v_mfma_f32_16x16x32_bf16 v[74:77], v[196:199], v[220:223], v[74:77]
	v_mfma_f32_16x16x32_bf16 v[70:73], v[188:191], v[228:231], v[70:73]
	v_mfma_f32_16x16x32_bf16 v[62:65], v[196:199], v[228:231], v[62:65]
	s_barrier
	s_add_i32 s45, 0, 0x18000
	v_add_u32_e32 v0, s45, v158
	s_add_i32 s46, 0, 0x1c000
	ds_read_b128 v[142:145], v0
	ds_read_b128 v[146:149], v0 offset:1024
	ds_read_b128 v[150:153], v0 offset:2048
	ds_read_b128 v[180:183], v0 offset:3072
	v_add_u32_e32 v0, s46, v158
	ds_read_b128 v[184:187], v0
	ds_read_b128 v[188:191], v0 offset:1024
	ds_read_b128 v[192:195], v0 offset:2048
	ds_read_b128 v[196:199], v0 offset:3072
	s_add_u32 s26, s26, 0x40000
	s_addc_u32 s27, s27, 0
	s_mov_b32 m0, s34
	v_lshl_add_u64 v[232:233], s[26:27], 0, v[130:131]
	ds_read_b128 v[200:203], v160 offset:32768
	ds_read_b128 v[204:207], v160 offset:33792
	ds_read_b128 v[208:211], v160 offset:34816
	ds_read_b128 v[212:215], v160 offset:35840
	ds_read_b128 v[216:219], v160 offset:36864
	ds_read_b128 v[220:223], v160 offset:37888
	ds_read_b128 v[224:227], v160 offset:38912
	ds_read_b128 v[228:231], v160 offset:39936
	global_load_lds_dwordx4 v[232:233], off
	v_lshl_add_u64 v[232:233], s[26:27], 0, v[134:135]
	s_mov_b32 m0, s35
	s_nop 0
	global_load_lds_dwordx4 v[232:233], off
	s_waitcnt vmcnt(8)
	s_waitcnt lgkmcnt(0)
	s_barrier
	s_waitcnt lgkmcnt(0)
	v_mfma_f32_16x16x32_bf16 v[66:69], v[142:145], v[200:203], v[66:69]
	v_mfma_f32_16x16x32_bf16 v[58:61], v[150:153], v[200:203], v[58:61]
	v_mfma_f32_16x16x32_bf16 v[54:57], v[142:145], v[208:211], v[54:57]
	v_mfma_f32_16x16x32_bf16 v[50:53], v[150:153], v[208:211], v[50:53]
	v_mfma_f32_16x16x32_bf16 v[46:49], v[142:145], v[216:219], v[46:49]
	v_mfma_f32_16x16x32_bf16 v[42:45], v[150:153], v[216:219], v[42:45]
	v_mfma_f32_16x16x32_bf16 v[38:41], v[142:145], v[224:227], v[38:41]
	v_mfma_f32_16x16x32_bf16 v[34:37], v[150:153], v[224:227], v[34:37]
	v_mfma_f32_16x16x32_bf16 v[66:69], v[146:149], v[204:207], v[66:69]
	v_mfma_f32_16x16x32_bf16 v[58:61], v[180:183], v[204:207], v[58:61]
	v_mfma_f32_16x16x32_bf16 v[54:57], v[146:149], v[212:215], v[54:57]
	v_mfma_f32_16x16x32_bf16 v[50:53], v[180:183], v[212:215], v[50:53]
	v_mfma_f32_16x16x32_bf16 v[46:49], v[146:149], v[220:223], v[46:49]
	v_mfma_f32_16x16x32_bf16 v[42:45], v[180:183], v[220:223], v[42:45]
	v_mfma_f32_16x16x32_bf16 v[38:41], v[146:149], v[228:231], v[38:41]
	v_mfma_f32_16x16x32_bf16 v[34:37], v[180:183], v[228:231], v[34:37]
	v_mfma_f32_16x16x32_bf16 v[126:129], v[184:187], v[200:203], v[126:129]
	v_mfma_f32_16x16x32_bf16 v[122:125], v[192:195], v[200:203], v[122:125]
	v_mfma_f32_16x16x32_bf16 v[118:121], v[184:187], v[208:211], v[118:121]
	v_mfma_f32_16x16x32_bf16 v[114:117], v[192:195], v[208:211], v[114:117]
	v_mfma_f32_16x16x32_bf16 v[110:113], v[184:187], v[216:219], v[110:113]
	v_mfma_f32_16x16x32_bf16 v[106:109], v[192:195], v[216:219], v[106:109]
	v_mfma_f32_16x16x32_bf16 v[102:105], v[184:187], v[224:227], v[102:105]
	v_mfma_f32_16x16x32_bf16 v[98:101], v[192:195], v[224:227], v[98:101]
	v_mfma_f32_16x16x32_bf16 v[126:129], v[188:191], v[204:207], v[126:129]
	v_mfma_f32_16x16x32_bf16 v[122:125], v[196:199], v[204:207], v[122:125]
	v_mfma_f32_16x16x32_bf16 v[118:121], v[188:191], v[212:215], v[118:121]
	v_mfma_f32_16x16x32_bf16 v[114:117], v[196:199], v[212:215], v[114:117]
	v_mfma_f32_16x16x32_bf16 v[110:113], v[188:191], v[220:223], v[110:113]
	v_mfma_f32_16x16x32_bf16 v[106:109], v[196:199], v[220:223], v[106:109]
	v_mfma_f32_16x16x32_bf16 v[102:105], v[188:191], v[228:231], v[102:105]
	v_mfma_f32_16x16x32_bf16 v[98:101], v[196:199], v[228:231], v[98:101]
	s_barrier
; #define PG8_STAGE(bufoff, gbase, voff) do { _Pragma("unroll") for (int _i = 0; _i < 2; ++_i) \
;         __builtin_amdgcn_global_load_lds((const unsigned*)((const char*)(gbase) + (voff)[_i]), (LAS unsigned*)(lds + (bufoff) + ldsw + _i * 8192), 16, 0, 0); } while (0)
; #define PG8_LDA(dst, b, h) do { _Pragma("unroll") for (int m = 0; m < 4; ++m) _Pragma("unroll") for (int k = 0; k < 2; ++k) dst[m][k] = *(const LAS bf16x8*)(lds + PG8_SA(b, h) + aoff + m * 2048 + k * 1024); } while (0)
; #define PG8_MMA(ai, bj, At, Bt) do { __builtin_amdgcn_s_setprio(1); _Pragma("unroll") for (int m = 0; m < 4; ++m) _Pragma("unroll") for (int n = 0; n < 2; ++n) _Pragma("unroll") for (int k = 0; k < 2; ++k) \
;         acc[ai][bj][m][n] = __builtin_amdgcn_mfma_f32_16x16x32_bf16(Bt[n][k], At[m][k], acc[ai][bj][m][n], 0, 0, 0); __builtin_amdgcn_s_setprio(0); } while (0)
; #define PG8_WAIT_V(n) asm volatile("s_waitcnt vmcnt(" #n ")" ::: "memory")
; #define PG8_WAIT_L(n) asm volatile("s_waitcnt lgkmcnt(" #n ")" ::: "memory")
; #define PG8_BAR __builtin_amdgcn_s_barrier()
; #define PG8_SCHED __builtin_amdgcn_sched_barrier(0)
; template <class Epi, bool ALIGN_EPI>
; __device__ __forceinline__ void gemm_phase(LAS unsigned char* lds, const Gemm g, const StaticOrder& S, const Epi& E) {
;     ...
;             PG8_LDA(At, 1, 1); PG8_STAGE(PG8_SB(1, 0), b3, voffB); PG8_STAGE(PG8_SB(1, 1), b3 + hstepB, voffB); PG8_STAGE(PG8_SA(1, 0), a3, voffA);
;             PG8_WAIT_V(8); PG8_WAIT_L(0); PG8_BAR; PG8_MMA(1, 0, At, B0); PG8_MMA(1, 1, At, B1); PG8_BAR; PG8_SCHED;
;         }
;         if constexpr (ALIGN_EPI) { if (wr == 0) PG8_BAR; }
	s_add_i32 s26, s45, s29
	v_lshl_add_u64 v[156:157], v[156:157], 0, s[94:95]
	s_mov_b32 m0, s26
	ds_read_b128 v[200:203], v160 offset:49152
	ds_read_b128 v[204:207], v160 offset:50176
	ds_read_b128 v[208:211], v160 offset:51200
	ds_read_b128 v[212:215], v160 offset:52224
	ds_read_b128 v[216:219], v160 offset:53248
	ds_read_b128 v[220:223], v160 offset:54272
	ds_read_b128 v[224:227], v160 offset:55296
	ds_read_b128 v[228:231], v160 offset:56320
	global_load_lds_dwordx4 v[156:157], off
	s_add_i32 m0, s26, 0x2000
	s_add_u32 s24, s24, 0x40080
	v_lshl_add_u64 v[156:157], v[162:163], 0, s[94:95]
	s_addc_u32 s25, s25, 0
	s_add_i32 s26, s46, s29
	global_load_lds_dwordx4 v[156:157], off
	v_lshl_add_u64 v[156:157], s[24:25], 0, v[132:133]
	s_mov_b32 m0, s26
	s_nop 0
	global_load_lds_dwordx4 v[156:157], off
	v_lshl_add_u64 v[156:157], s[24:25], 0, v[136:137]
	s_add_i32 m0, s26, 0x2000
	s_nop 0
	global_load_lds_dwordx4 v[156:157], off
	v_lshl_add_u64 v[156:157], v[170:171], 0, s[94:95]
	s_mov_b32 m0, s36
	s_nop 0
	global_load_lds_dwordx4 v[156:157], off
	v_lshl_add_u64 v[156:157], v[172:173], 0, s[94:95]
	s_mov_b32 m0, s37
	s_nop 0
	global_load_lds_dwordx4 v[156:157], off
	s_waitcnt vmcnt(8)
	s_waitcnt lgkmcnt(0)
	s_barrier
	s_waitcnt lgkmcnt(0)
	v_mfma_f32_16x16x32_bf16 v[30:33], v[142:145], v[200:203], v[30:33]
	v_mfma_f32_16x16x32_bf16 v[26:29], v[150:153], v[200:203], v[26:29]
	v_mfma_f32_16x16x32_bf16 v[22:25], v[142:145], v[208:211], v[22:25]
	v_mfma_f32_16x16x32_bf16 v[18:21], v[150:153], v[208:211], v[18:21]
	v_mfma_f32_16x16x32_bf16 v[14:17], v[142:145], v[216:219], v[14:17]
	v_mfma_f32_16x16x32_bf16 v[10:13], v[150:153], v[216:219], v[10:13]
	v_mfma_f32_16x16x32_bf16 v[6:9], v[142:145], v[224:227], v[6:9]
	v_mfma_f32_16x16x32_bf16 v[2:5], v[150:153], v[224:227], v[2:5]
	v_mfma_f32_16x16x32_bf16 v[30:33], v[146:149], v[204:207], v[30:33]
	v_mfma_f32_16x16x32_bf16 v[26:29], v[180:183], v[204:207], v[26:29]
	v_mfma_f32_16x16x32_bf16 v[22:25], v[146:149], v[212:215], v[22:25]
	v_mfma_f32_16x16x32_bf16 v[18:21], v[180:183], v[212:215], v[18:21]
	v_mfma_f32_16x16x32_bf16 v[14:17], v[146:149], v[220:223], v[14:17]
	v_mfma_f32_16x16x32_bf16 v[10:13], v[180:183], v[220:223], v[10:13]
	v_mfma_f32_16x16x32_bf16 v[6:9], v[146:149], v[228:231], v[6:9]
	v_mfma_f32_16x16x32_bf16 v[2:5], v[180:183], v[228:231], v[2:5]
	v_mfma_f32_16x16x32_bf16 v[94:97], v[184:187], v[200:203], v[94:97]
	v_mfma_f32_16x16x32_bf16 v[90:93], v[192:195], v[200:203], v[90:93]
	v_mfma_f32_16x16x32_bf16 v[86:89], v[184:187], v[208:211], v[86:89]
	v_mfma_f32_16x16x32_bf16 v[82:85], v[192:195], v[208:211], v[82:85]
	v_mfma_f32_16x16x32_bf16 v[78:81], v[184:187], v[216:219], v[78:81]
	v_mfma_f32_16x16x32_bf16 v[74:77], v[192:195], v[216:219], v[74:77]
	v_mfma_f32_16x16x32_bf16 v[70:73], v[184:187], v[224:227], v[70:73]
	v_mfma_f32_16x16x32_bf16 v[62:65], v[192:195], v[224:227], v[62:65]
	v_mfma_f32_16x16x32_bf16 v[94:97], v[188:191], v[204:207], v[94:97]
	v_mfma_f32_16x16x32_bf16 v[90:93], v[196:199], v[204:207], v[90:93]
	v_mfma_f32_16x16x32_bf16 v[86:89], v[188:191], v[212:215], v[86:89]
	v_mfma_f32_16x16x32_bf16 v[82:85], v[196:199], v[212:215], v[82:85]
	v_mfma_f32_16x16x32_bf16 v[78:81], v[188:191], v[220:223], v[78:81]
	v_mfma_f32_16x16x32_bf16 v[74:77], v[196:199], v[220:223], v[74:77]
	v_mfma_f32_16x16x32_bf16 v[70:73], v[188:191], v[228:231], v[70:73]
	v_mfma_f32_16x16x32_bf16 v[62:65], v[196:199], v[228:231], v[62:65]
	s_barrier
	s_add_i32 s44, s44, 2
	s_add_u32 s6, s6, 0x100
	s_addc_u32 s7, s7, 0
	s_add_u32 s42, s42, 0x100
	s_addc_u32 s43, s43, 0
	s_cmp_gt_u32 s44, 13
	s_cbranch_scc0 .LBB0_603
	s_and_b64 vcc, exec, s[12:13]
	s_cbranch_vccz .LBB0_606
	s_barrier

; #define PG8_STAGE(bufoff, gbase, voff) do { _Pragma("unroll") for (int _i = 0; _i < 2; ++_i) \
;         __builtin_amdgcn_global_load_lds((const unsigned*)((const char*)(gbase) + (voff)[_i]), (LAS unsigned*)(lds + (bufoff) + ldsw + _i * 8192), 16, 0, 0); } while (0)
; #define PG8_LDA(dst, b, h) do { _Pragma("unroll") for (int m = 0; m < 4; ++m) _Pragma("unroll") for (int k = 0; k < 2; ++k) dst[m][k] = *(const LAS bf16x8*)(lds + PG8_SA(b, h) + aoff + m * 2048 + k * 1024); } while (0)
; #define PG8_LDB(dst, b, h) do { _Pragma("unroll") for (int n = 0; n < 2; ++n) _Pragma("unroll") for (int k = 0; k < 2; ++k) dst[n][k] = *(const LAS bf16x8*)(lds + PG8_SB(b, h) + boff + n * 2048 + k * 1024); } while (0)
; #define PG8_MMA(ai, bj, At, Bt) do { __builtin_amdgcn_s_setprio(1); _Pragma("unroll") for (int m = 0; m < 4; ++m) _Pragma("unroll") for (int n = 0; n < 2; ++n) _Pragma("unroll") for (int k = 0; k < 2; ++k) \
;         acc[ai][bj][m][n] = __builtin_amdgcn_mfma_f32_16x16x32_bf16(Bt[n][k], At[m][k], acc[ai][bj][m][n], 0, 0, 0); __builtin_amdgcn_s_setprio(0); } while (0)
; #define PG8_WAIT_V(n) asm volatile("s_waitcnt vmcnt(" #n ")" ::: "memory")
; #define PG8_WAIT_L(n) asm volatile("s_waitcnt lgkmcnt(" #n ")" ::: "memory")
; #define PG8_BAR __builtin_amdgcn_s_barrier()
; #define PG8_SCHED __builtin_amdgcn_sched_barrier(0)
; template <class Epi, bool ALIGN_EPI>
; __device__ __forceinline__ void gemm_phase(LAS unsigned char* lds, const Gemm g, const StaticOrder& S, const Epi& E) {
;     ...
;         for (int t = 0; t < nt; t += 2) {
;             const bool last = (t == nt - 2);
;             const char* a1 = cA + (size_t)(t + 1) * kstep;
;             const char* a2 = last ? nA : cA + (size_t)(t + 2) * kstep; const char* b2 = last ? nB : cB + (size_t)(t + 2) * kstep;
;             const char* a3 = a2 + kstep; const char* b3 = b2 + kstep;
;             PG8_LDB(B0, 0, 0); PG8_LDB(B1, 0, 1); PG8_SCHED; PG8_LDA(At, 0, 0); PG8_STAGE(PG8_SA(1, 1), a1 + hstepA, voffA);
;             PG8_WAIT_V(8); PG8_WAIT_L(0); PG8_BAR; PG8_MMA(0, 0, At, B0); PG8_MMA(0, 1, At, B1); PG8_BAR; PG8_SCHED;
;             PG8_LDA(At, 0, 1); PG8_STAGE(PG8_SB(0, 0), b2, voffB); PG8_STAGE(PG8_SB(0, 1), b2 + hstepB, voffB); PG8_STAGE(PG8_SA(0, 0), a2, voffA);
.LBB0_719:
	s_add_u32 s10, s8, 0x100
	s_addc_u32 s11, s9, 0
	s_add_i32 s46, 0, 0x10000
	s_cmp_eq_u32 s45, 40
	s_cselect_b32 s27, s23, s11
	s_cselect_b32 s26, s22, s10
	v_add_u32_e32 v152, s46, v160
	s_cselect_b32 s13, s25, s44
	s_cselect_b32 s12, s24, s29
	s_add_i32 s47, 0, 0x14000
	ds_read_b128 v[130:133], v152
	ds_read_b128 v[134:137], v152 offset:1024
	ds_read_b128 v[148:151], v152 offset:2048
	ds_read_b128 v[156:159], v152 offset:3072
	v_add_u32_e32 v152, s47, v160
	ds_read_b128 v[180:183], v152
	ds_read_b128 v[184:187], v152 offset:1024
	ds_read_b128 v[188:191], v152 offset:2048
	ds_read_b128 v[192:195], v152 offset:3072
	v_lshl_add_u64 v[152:153], s[8:9], 0, v[144:145]
	s_add_i32 m0, s35, 0xc000
	ds_read_b128 v[196:199], v161
	ds_read_b128 v[200:203], v161 offset:1024
	ds_read_b128 v[204:207], v161 offset:2048
	ds_read_b128 v[208:211], v161 offset:3072
	ds_read_b128 v[212:215], v161 offset:4096
	ds_read_b128 v[216:219], v161 offset:5120
	ds_read_b128 v[220:223], v161 offset:6144
	ds_read_b128 v[224:227], v161 offset:7168
	global_load_lds_dwordx4 v[152:153], off
	v_lshl_add_u64 v[152:153], s[8:9], 0, v[146:147]
	s_add_i32 m0, s35, 0xe000
	s_nop 0
	global_load_lds_dwordx4 v[152:153], off
	s_waitcnt vmcnt(8)
	s_waitcnt lgkmcnt(0)
	s_barrier
	s_waitcnt lgkmcnt(0)
	v_mfma_f32_16x16x32_bf16 v[126:129], v[130:133], v[196:199], v[126:129]
	v_mfma_f32_16x16x32_bf16 v[122:125], v[148:151], v[196:199], v[122:125]
	v_mfma_f32_16x16x32_bf16 v[110:113], v[130:133], v[204:207], v[110:113]
	v_mfma_f32_16x16x32_bf16 v[106:109], v[148:151], v[204:207], v[106:109]
	v_mfma_f32_16x16x32_bf16 v[94:97], v[130:133], v[212:215], v[94:97]
	v_mfma_f32_16x16x32_bf16 v[90:93], v[148:151], v[212:215], v[90:93]
	v_mfma_f32_16x16x32_bf16 v[78:81], v[130:133], v[220:223], v[78:81]
	v_mfma_f32_16x16x32_bf16 v[74:77], v[148:151], v[220:223], v[74:77]
	v_mfma_f32_16x16x32_bf16 v[126:129], v[134:137], v[200:203], v[126:129]
	v_mfma_f32_16x16x32_bf16 v[122:125], v[156:159], v[200:203], v[122:125]
	v_mfma_f32_16x16x32_bf16 v[110:113], v[134:137], v[208:211], v[110:113]
	v_mfma_f32_16x16x32_bf16 v[106:109], v[156:159], v[208:211], v[106:109]
	v_mfma_f32_16x16x32_bf16 v[94:97], v[134:137], v[216:219], v[94:97]
	v_mfma_f32_16x16x32_bf16 v[90:93], v[156:159], v[216:219], v[90:93]
	v_mfma_f32_16x16x32_bf16 v[78:81], v[134:137], v[224:227], v[78:81]
	v_mfma_f32_16x16x32_bf16 v[74:77], v[156:159], v[224:227], v[74:77]
	v_mfma_f32_16x16x32_bf16 v[118:121], v[180:183], v[196:199], v[118:121]
	v_mfma_f32_16x16x32_bf16 v[114:117], v[188:191], v[196:199], v[114:117]
	v_mfma_f32_16x16x32_bf16 v[102:105], v[180:183], v[204:207], v[102:105]
	v_mfma_f32_16x16x32_bf16 v[98:101], v[188:191], v[204:207], v[98:101]
	v_mfma_f32_16x16x32_bf16 v[86:89], v[180:183], v[212:215], v[86:89]
	v_mfma_f32_16x16x32_bf16 v[82:85], v[188:191], v[212:215], v[82:85]
	v_mfma_f32_16x16x32_bf16 v[70:73], v[180:183], v[220:223], v[70:73]
	v_mfma_f32_16x16x32_bf16 v[66:69], v[188:191], v[220:223], v[66:69]
	v_mfma_f32_16x16x32_bf16 v[118:121], v[184:187], v[200:203], v[118:121]
	v_mfma_f32_16x16x32_bf16 v[114:117], v[192:195], v[200:203], v[114:117]
	v_mfma_f32_16x16x32_bf16 v[102:105], v[184:187], v[208:211], v[102:105]
	v_mfma_f32_16x16x32_bf16 v[98:101], v[192:195], v[208:211], v[98:101]
	v_mfma_f32_16x16x32_bf16 v[86:89], v[184:187], v[216:219], v[86:89]
	v_mfma_f32_16x16x32_bf16 v[82:85], v[192:195], v[216:219], v[82:85]
	v_mfma_f32_16x16x32_bf16 v[70:73], v[184:187], v[224:227], v[70:73]
	v_mfma_f32_16x16x32_bf16 v[66:69], v[192:195], v[224:227], v[66:69]
	s_barrier
	s_add_i32 s8, s46, s30
	v_lshl_add_u64 v[152:153], s[12:13], 0, v[0:1]
	s_mov_b32 m0, s8
	ds_read_b128 v[196:199], v161 offset:16384
	ds_read_b128 v[200:203], v161 offset:17408
	ds_read_b128 v[204:207], v161 offset:18432
	ds_read_b128 v[208:211], v161 offset:19456
	ds_read_b128 v[212:215], v161 offset:20480
	ds_read_b128 v[216:219], v161 offset:21504
	ds_read_b128 v[220:223], v161 offset:22528
	ds_read_b128 v[224:227], v161 offset:23552
	global_load_lds_dwordx4 v[152:153], off
	s_add_i32 m0, s8, 0x2000
	s_add_u32 s8, s12, 0xb0000
	v_lshl_add_u64 v[162:163], s[12:13], 0, v[142:143]
	s_addc_u32 s9, s13, 0
	s_add_i32 s46, s47, s30
	global_load_lds_dwordx4 v[162:163], off
	v_lshl_add_u64 v[170:171], s[8:9], 0, v[0:1]
	s_mov_b32 m0, s46
	v_lshl_add_u64 v[172:173], s[26:27], 0, v[140:141]
	global_load_lds_dwordx4 v[170:171], off
	v_lshl_add_u64 v[170:171], s[8:9], 0, v[142:143]
	s_add_i32 m0, s46, 0x2000
	s_nop 0
	global_load_lds_dwordx4 v[170:171], off
	v_lshl_add_u64 v[170:171], s[26:27], 0, v[138:139]
	s_mov_b32 m0, s35
	s_nop 0
	global_load_lds_dwordx4 v[170:171], off
	s_mov_b32 m0, s36
	s_nop 0
	global_load_lds_dwordx4 v[172:173], off
	s_waitcnt vmcnt(8)
	s_waitcnt lgkmcnt(0)
	s_barrier
; #define PG8_STAGE(bufoff, gbase, voff) do { _Pragma("unroll") for (int _i = 0; _i < 2; ++_i) \
;         __builtin_amdgcn_global_load_lds((const unsigned*)((const char*)(gbase) + (voff)[_i]), (LAS unsigned*)(lds + (bufoff) + ldsw + _i * 8192), 16, 0, 0); } while (0)
; #define PG8_LDA(dst, b, h) do { _Pragma("unroll") for (int m = 0; m < 4; ++m) _Pragma("unroll") for (int k = 0; k < 2; ++k) dst[m][k] = *(const LAS bf16x8*)(lds + PG8_SA(b, h) + aoff + m * 2048 + k * 1024); } while (0)
; #define PG8_LDB(dst, b, h) do { _Pragma("unroll") for (int n = 0; n < 2; ++n) _Pragma("unroll") for (int k = 0; k < 2; ++k) dst[n][k] = *(const LAS bf16x8*)(lds + PG8_SB(b, h) + boff + n * 2048 + k * 1024); } while (0)
; #define PG8_MMA(ai, bj, At, Bt) do { __builtin_amdgcn_s_setprio(1); _Pragma("unroll") for (int m = 0; m < 4; ++m) _Pragma("unroll") for (int n = 0; n < 2; ++n) _Pragma("unroll") for (int k = 0; k < 2; ++k) \
;         acc[ai][bj][m][n] = __builtin_amdgcn_mfma_f32_16x16x32_bf16(Bt[n][k], At[m][k], acc[ai][bj][m][n], 0, 0, 0); __builtin_amdgcn_s_setprio(0); } while (0)
; #define PG8_WAIT_V(n) asm volatile("s_waitcnt vmcnt(" #n ")" ::: "memory")
; #define PG8_WAIT_L(n) asm volatile("s_waitcnt lgkmcnt(" #n ")" ::: "memory")
; #define PG8_BAR __builtin_amdgcn_s_barrier()
; #define PG8_SCHED __builtin_amdgcn_sched_barrier(0)
; template <class Epi, bool ALIGN_EPI>
; __device__ __forceinline__ void gemm_phase(LAS unsigned char* lds, const Gemm g, const StaticOrder& S, const Epi& E) {
;     ...
;             PG8_WAIT_V(8); PG8_WAIT_L(0); PG8_BAR; PG8_MMA(1, 0, At, B0); PG8_MMA(1, 1, At, B1); PG8_BAR; PG8_SCHED;
;             PG8_LDB(B0, 1, 0); PG8_LDB(B1, 1, 1); PG8_SCHED; PG8_LDA(At, 1, 0); PG8_STAGE(PG8_SA(0, 1), a2 + hstepA, voffA);
;             PG8_WAIT_V(8); PG8_WAIT_L(0); PG8_BAR; PG8_MMA(0, 0, At, B0); PG8_MMA(0, 1, At, B1); PG8_BAR; PG8_SCHED;
	s_waitcnt lgkmcnt(0)
	v_mfma_f32_16x16x32_bf16 v[62:65], v[130:133], v[196:199], v[62:65]
	v_mfma_f32_16x16x32_bf16 v[58:61], v[148:151], v[196:199], v[58:61]
	v_mfma_f32_16x16x32_bf16 v[46:49], v[130:133], v[204:207], v[46:49]
	v_mfma_f32_16x16x32_bf16 v[42:45], v[148:151], v[204:207], v[42:45]
	v_mfma_f32_16x16x32_bf16 v[30:33], v[130:133], v[212:215], v[30:33]
	v_mfma_f32_16x16x32_bf16 v[26:29], v[148:151], v[212:215], v[26:29]
	v_mfma_f32_16x16x32_bf16 v[14:17], v[130:133], v[220:223], v[14:17]
	v_mfma_f32_16x16x32_bf16 v[10:13], v[148:151], v[220:223], v[10:13]
	v_mfma_f32_16x16x32_bf16 v[62:65], v[134:137], v[200:203], v[62:65]
	v_mfma_f32_16x16x32_bf16 v[58:61], v[156:159], v[200:203], v[58:61]
	v_mfma_f32_16x16x32_bf16 v[46:49], v[134:137], v[208:211], v[46:49]
	v_mfma_f32_16x16x32_bf16 v[42:45], v[156:159], v[208:211], v[42:45]
	v_mfma_f32_16x16x32_bf16 v[30:33], v[134:137], v[216:219], v[30:33]
	v_mfma_f32_16x16x32_bf16 v[26:29], v[156:159], v[216:219], v[26:29]
	v_mfma_f32_16x16x32_bf16 v[14:17], v[134:137], v[224:227], v[14:17]
	v_mfma_f32_16x16x32_bf16 v[10:13], v[156:159], v[224:227], v[10:13]
	v_mfma_f32_16x16x32_bf16 v[54:57], v[180:183], v[196:199], v[54:57]
	v_mfma_f32_16x16x32_bf16 v[50:53], v[188:191], v[196:199], v[50:53]
	v_mfma_f32_16x16x32_bf16 v[38:41], v[180:183], v[204:207], v[38:41]
	v_mfma_f32_16x16x32_bf16 v[34:37], v[188:191], v[204:207], v[34:37]
	v_mfma_f32_16x16x32_bf16 v[22:25], v[180:183], v[212:215], v[22:25]
	v_mfma_f32_16x16x32_bf16 v[18:21], v[188:191], v[212:215], v[18:21]
	v_mfma_f32_16x16x32_bf16 v[6:9], v[180:183], v[220:223], v[6:9]
	v_mfma_f32_16x16x32_bf16 v[2:5], v[188:191], v[220:223], v[2:5]
	v_mfma_f32_16x16x32_bf16 v[54:57], v[184:187], v[200:203], v[54:57]
	v_mfma_f32_16x16x32_bf16 v[50:53], v[192:195], v[200:203], v[50:53]
	v_mfma_f32_16x16x32_bf16 v[38:41], v[184:187], v[208:211], v[38:41]
	v_mfma_f32_16x16x32_bf16 v[34:37], v[192:195], v[208:211], v[34:37]
	v_mfma_f32_16x16x32_bf16 v[22:25], v[184:187], v[216:219], v[22:25]
	v_mfma_f32_16x16x32_bf16 v[18:21], v[192:195], v[216:219], v[18:21]
	v_mfma_f32_16x16x32_bf16 v[6:9], v[184:187], v[224:227], v[6:9]
	v_mfma_f32_16x16x32_bf16 v[2:5], v[192:195], v[224:227], v[2:5]
	s_barrier
	s_add_i32 s46, 0, 0x18000
	s_add_i32 s47, 0, 0x1c000
	v_add_u32_e32 v156, s46, v160
	v_add_u32_e32 v164, s47, v160
	ds_read_b128 v[130:133], v156
	ds_read_b128 v[134:137], v156 offset:1024
	ds_read_b128 v[148:151], v156 offset:2048
	ds_read_b128 v[156:159], v156 offset:3072
	ds_read_b128 v[180:183], v164
	ds_read_b128 v[184:187], v164 offset:1024
	ds_read_b128 v[188:191], v164 offset:2048
	ds_read_b128 v[192:195], v164 offset:3072
	s_add_u32 s8, s26, 0xb0000
	s_addc_u32 s9, s27, 0
	s_mov_b32 m0, s37
	v_lshl_add_u64 v[228:229], s[8:9], 0, v[138:139]
	ds_read_b128 v[196:199], v161 offset:32768
	ds_read_b128 v[200:203], v161 offset:33792
	ds_read_b128 v[204:207], v161 offset:34816
	ds_read_b128 v[208:211], v161 offset:35840
	ds_read_b128 v[212:215], v161 offset:36864
	ds_read_b128 v[216:219], v161 offset:37888
	ds_read_b128 v[220:223], v161 offset:38912
	ds_read_b128 v[224:227], v161 offset:39936
	global_load_lds_dwordx4 v[228:229], off
	v_lshl_add_u64 v[228:229], s[8:9], 0, v[140:141]
	s_mov_b32 m0, s38
	s_nop 0
	global_load_lds_dwordx4 v[228:229], off
	s_waitcnt vmcnt(8)
	s_waitcnt lgkmcnt(0)
	s_barrier
	s_waitcnt lgkmcnt(0)
	v_mfma_f32_16x16x32_bf16 v[126:129], v[130:133], v[196:199], v[126:129]
	v_mfma_f32_16x16x32_bf16 v[122:125], v[148:151], v[196:199], v[122:125]
	v_mfma_f32_16x16x32_bf16 v[110:113], v[130:133], v[204:207], v[110:113]
	v_mfma_f32_16x16x32_bf16 v[106:109], v[148:151], v[204:207], v[106:109]
	v_mfma_f32_16x16x32_bf16 v[94:97], v[130:133], v[212:215], v[94:97]
	v_mfma_f32_16x16x32_bf16 v[90:93], v[148:151], v[212:215], v[90:93]
	v_mfma_f32_16x16x32_bf16 v[78:81], v[130:133], v[220:223], v[78:81]
	v_mfma_f32_16x16x32_bf16 v[74:77], v[148:151], v[220:223], v[74:77]
	v_mfma_f32_16x16x32_bf16 v[126:129], v[134:137], v[200:203], v[126:129]
	v_mfma_f32_16x16x32_bf16 v[122:125], v[156:159], v[200:203], v[122:125]
	v_mfma_f32_16x16x32_bf16 v[110:113], v[134:137], v[208:211], v[110:113]
	v_mfma_f32_16x16x32_bf16 v[106:109], v[156:159], v[208:211], v[106:109]
	v_mfma_f32_16x16x32_bf16 v[94:97], v[134:137], v[216:219], v[94:97]
	v_mfma_f32_16x16x32_bf16 v[90:93], v[156:159], v[216:219], v[90:93]
	v_mfma_f32_16x16x32_bf16 v[78:81], v[134:137], v[224:227], v[78:81]
	v_mfma_f32_16x16x32_bf16 v[74:77], v[156:159], v[224:227], v[74:77]
	v_mfma_f32_16x16x32_bf16 v[118:121], v[180:183], v[196:199], v[118:121]
	v_mfma_f32_16x16x32_bf16 v[114:117], v[188:191], v[196:199], v[114:117]
	v_mfma_f32_16x16x32_bf16 v[102:105], v[180:183], v[204:207], v[102:105]
	v_mfma_f32_16x16x32_bf16 v[98:101], v[188:191], v[204:207], v[98:101]
	v_mfma_f32_16x16x32_bf16 v[86:89], v[180:183], v[212:215], v[86:89]
	v_mfma_f32_16x16x32_bf16 v[82:85], v[188:191], v[212:215], v[82:85]
	v_mfma_f32_16x16x32_bf16 v[70:73], v[180:183], v[220:223], v[70:73]
	v_mfma_f32_16x16x32_bf16 v[66:69], v[188:191], v[220:223], v[66:69]
	v_mfma_f32_16x16x32_bf16 v[118:121], v[184:187], v[200:203], v[118:121]
	v_mfma_f32_16x16x32_bf16 v[114:117], v[192:195], v[200:203], v[114:117]
	v_mfma_f32_16x16x32_bf16 v[102:105], v[184:187], v[208:211], v[102:105]
	v_mfma_f32_16x16x32_bf16 v[98:101], v[192:195], v[208:211], v[98:101]
	v_mfma_f32_16x16x32_bf16 v[86:89], v[184:187], v[216:219], v[86:89]
	v_mfma_f32_16x16x32_bf16 v[82:85], v[192:195], v[216:219], v[82:85]
	v_mfma_f32_16x16x32_bf16 v[70:73], v[184:187], v[224:227], v[70:73]
	v_mfma_f32_16x16x32_bf16 v[66:69], v[192:195], v[224:227], v[66:69]
	s_barrier
; #define PG8_STAGE(bufoff, gbase, voff) do { _Pragma("unroll") for (int _i = 0; _i < 2; ++_i) \
;         __builtin_amdgcn_global_load_lds((const unsigned*)((const char*)(gbase) + (voff)[_i]), (LAS unsigned*)(lds + (bufoff) + ldsw + _i * 8192), 16, 0, 0); } while (0)
; #define PG8_LDA(dst, b, h) do { _Pragma("unroll") for (int m = 0; m < 4; ++m) _Pragma("unroll") for (int k = 0; k < 2; ++k) dst[m][k] = *(const LAS bf16x8*)(lds + PG8_SA(b, h) + aoff + m * 2048 + k * 1024); } while (0)
; #define PG8_MMA(ai, bj, At, Bt) do { __builtin_amdgcn_s_setprio(1); _Pragma("unroll") for (int m = 0; m < 4; ++m) _Pragma("unroll") for (int n = 0; n < 2; ++n) _Pragma("unroll") for (int k = 0; k < 2; ++k) \
;         acc[ai][bj][m][n] = __builtin_amdgcn_mfma_f32_16x16x32_bf16(Bt[n][k], At[m][k], acc[ai][bj][m][n], 0, 0, 0); __builtin_amdgcn_s_setprio(0); } while (0)
; #define PG8_WAIT_V(n) asm volatile("s_waitcnt vmcnt(" #n ")" ::: "memory")
; #define PG8_WAIT_L(n) asm volatile("s_waitcnt lgkmcnt(" #n ")" ::: "memory")
; #define PG8_BAR __builtin_amdgcn_s_barrier()
; #define PG8_SCHED __builtin_amdgcn_sched_barrier(0)
; template <class Epi, bool ALIGN_EPI>
; __device__ __forceinline__ void gemm_phase(LAS unsigned char* lds, const Gemm g, const StaticOrder& S, const Epi& E) {
;     ...
;             PG8_LDA(At, 1, 1); PG8_STAGE(PG8_SB(1, 0), b3, voffB); PG8_STAGE(PG8_SB(1, 1), b3 + hstepB, voffB); PG8_STAGE(PG8_SA(1, 0), a3, voffA);
;             PG8_WAIT_V(8); PG8_WAIT_L(0); PG8_BAR; PG8_MMA(1, 0, At, B0); PG8_MMA(1, 1, At, B1); PG8_BAR; PG8_SCHED;
;         }
;         if constexpr (ALIGN_EPI) { if (wr == 0) PG8_BAR; }
	s_add_i32 s8, s46, s30
	v_lshl_add_u64 v[152:153], v[152:153], 0, s[94:95]
	s_mov_b32 m0, s8
	ds_read_b128 v[196:199], v161 offset:49152
	ds_read_b128 v[200:203], v161 offset:50176
	ds_read_b128 v[204:207], v161 offset:51200
	ds_read_b128 v[208:211], v161 offset:52224
	ds_read_b128 v[212:215], v161 offset:53248
	ds_read_b128 v[216:219], v161 offset:54272
	ds_read_b128 v[220:223], v161 offset:55296
	ds_read_b128 v[224:227], v161 offset:56320
	global_load_lds_dwordx4 v[152:153], off
	s_add_i32 m0, s8, 0x2000
	s_add_u32 s8, s12, 0xb0080
	v_lshl_add_u64 v[152:153], v[162:163], 0, s[94:95]
	s_addc_u32 s9, s13, 0
	s_add_i32 s12, s47, s30
	global_load_lds_dwordx4 v[152:153], off
	v_lshl_add_u64 v[152:153], s[8:9], 0, v[0:1]
	s_mov_b32 m0, s12
	s_nop 0
	global_load_lds_dwordx4 v[152:153], off
	v_lshl_add_u64 v[152:153], s[8:9], 0, v[142:143]
	s_add_i32 m0, s12, 0x2000
	s_nop 0
	global_load_lds_dwordx4 v[152:153], off
	v_lshl_add_u64 v[152:153], v[170:171], 0, s[94:95]
	s_mov_b32 m0, s39
	s_nop 0
	global_load_lds_dwordx4 v[152:153], off
	v_lshl_add_u64 v[152:153], v[172:173], 0, s[94:95]
	s_mov_b32 m0, s40
	s_nop 0
	global_load_lds_dwordx4 v[152:153], off
	s_waitcnt vmcnt(8)
	s_waitcnt lgkmcnt(0)
	s_barrier
	s_waitcnt lgkmcnt(0)
	v_mfma_f32_16x16x32_bf16 v[62:65], v[130:133], v[196:199], v[62:65]
	v_mfma_f32_16x16x32_bf16 v[58:61], v[148:151], v[196:199], v[58:61]
	v_mfma_f32_16x16x32_bf16 v[46:49], v[130:133], v[204:207], v[46:49]
	v_mfma_f32_16x16x32_bf16 v[42:45], v[148:151], v[204:207], v[42:45]
	v_mfma_f32_16x16x32_bf16 v[30:33], v[130:133], v[212:215], v[30:33]
	v_mfma_f32_16x16x32_bf16 v[26:29], v[148:151], v[212:215], v[26:29]
	v_mfma_f32_16x16x32_bf16 v[14:17], v[130:133], v[220:223], v[14:17]
	v_mfma_f32_16x16x32_bf16 v[10:13], v[148:151], v[220:223], v[10:13]
	v_mfma_f32_16x16x32_bf16 v[62:65], v[134:137], v[200:203], v[62:65]
	v_mfma_f32_16x16x32_bf16 v[58:61], v[156:159], v[200:203], v[58:61]
	v_mfma_f32_16x16x32_bf16 v[46:49], v[134:137], v[208:211], v[46:49]
	v_mfma_f32_16x16x32_bf16 v[42:45], v[156:159], v[208:211], v[42:45]
	v_mfma_f32_16x16x32_bf16 v[30:33], v[134:137], v[216:219], v[30:33]
	v_mfma_f32_16x16x32_bf16 v[26:29], v[156:159], v[216:219], v[26:29]
	v_mfma_f32_16x16x32_bf16 v[14:17], v[134:137], v[224:227], v[14:17]
	v_mfma_f32_16x16x32_bf16 v[10:13], v[156:159], v[224:227], v[10:13]
	v_mfma_f32_16x16x32_bf16 v[54:57], v[180:183], v[196:199], v[54:57]
	v_mfma_f32_16x16x32_bf16 v[50:53], v[188:191], v[196:199], v[50:53]
	v_mfma_f32_16x16x32_bf16 v[38:41], v[180:183], v[204:207], v[38:41]
	v_mfma_f32_16x16x32_bf16 v[34:37], v[188:191], v[204:207], v[34:37]
	v_mfma_f32_16x16x32_bf16 v[22:25], v[180:183], v[212:215], v[22:25]
	v_mfma_f32_16x16x32_bf16 v[18:21], v[188:191], v[212:215], v[18:21]
	v_mfma_f32_16x16x32_bf16 v[6:9], v[180:183], v[220:223], v[6:9]
	v_mfma_f32_16x16x32_bf16 v[2:5], v[188:191], v[220:223], v[2:5]
	v_mfma_f32_16x16x32_bf16 v[54:57], v[184:187], v[200:203], v[54:57]
	v_mfma_f32_16x16x32_bf16 v[50:53], v[192:195], v[200:203], v[50:53]
	v_mfma_f32_16x16x32_bf16 v[38:41], v[184:187], v[208:211], v[38:41]
	v_mfma_f32_16x16x32_bf16 v[34:37], v[192:195], v[208:211], v[34:37]
	v_mfma_f32_16x16x32_bf16 v[22:25], v[184:187], v[216:219], v[22:25]
	v_mfma_f32_16x16x32_bf16 v[18:21], v[192:195], v[216:219], v[18:21]
	v_mfma_f32_16x16x32_bf16 v[6:9], v[184:187], v[224:227], v[6:9]
	v_mfma_f32_16x16x32_bf16 v[2:5], v[192:195], v[224:227], v[2:5]
	s_barrier
	s_add_i32 s45, s45, 2
	s_add_u32 s29, s29, 0x100
	s_addc_u32 s44, s44, 0
	s_cmp_gt_u32 s45, 41
	s_mov_b64 s[8:9], s[10:11]
	s_cbranch_scc0 .LBB0_719
	s_and_b64 vcc, exec, s[16:17]
	s_cbranch_vccz .LBB0_722
	s_barrier

; #define PG8_STAGE(bufoff, gbase, voff) do { _Pragma("unroll") for (int _i = 0; _i < 2; ++_i) \
;         __builtin_amdgcn_global_load_lds((const unsigned*)((const char*)(gbase) + (voff)[_i]), (LAS unsigned*)(lds + (bufoff) + ldsw + _i * 8192), 16, 0, 0); } while (0)
; #define PG8_LDA(dst, b, h) do { _Pragma("unroll") for (int m = 0; m < 4; ++m) _Pragma("unroll") for (int k = 0; k < 2; ++k) dst[m][k] = *(const LAS bf16x8*)(lds + PG8_SA(b, h) + aoff + m * 2048 + k * 1024); } while (0)
; #define PG8_LDB(dst, b, h) do { _Pragma("unroll") for (int n = 0; n < 2; ++n) _Pragma("unroll") for (int k = 0; k < 2; ++k) dst[n][k] = *(const LAS bf16x8*)(lds + PG8_SB(b, h) + boff + n * 2048 + k * 1024); } while (0)
; #define PG8_MMA(ai, bj, At, Bt) do { __builtin_amdgcn_s_setprio(1); _Pragma("unroll") for (int m = 0; m < 4; ++m) _Pragma("unroll") for (int n = 0; n < 2; ++n) _Pragma("unroll") for (int k = 0; k < 2; ++k) \
;         acc[ai][bj][m][n] = __builtin_amdgcn_mfma_f32_16x16x32_bf16(Bt[n][k], At[m][k], acc[ai][bj][m][n], 0, 0, 0); __builtin_amdgcn_s_setprio(0); } while (0)
; #define PG8_WAIT_V(n) asm volatile("s_waitcnt vmcnt(" #n ")" ::: "memory")
; #define PG8_WAIT_L(n) asm volatile("s_waitcnt lgkmcnt(" #n ")" ::: "memory")
; #define PG8_BAR __builtin_amdgcn_s_barrier()
; #define PG8_SCHED __builtin_amdgcn_sched_barrier(0)
; template <class Epi, bool ALIGN_EPI>
; __device__ __forceinline__ void gemm_phase(LAS unsigned char* lds, const Gemm g, const StaticOrder& S, const Epi& E) {
;     ...
;         for (int t = 0; t < nt; t += 2) {
;             const bool last = (t == nt - 2);
;             const char* a1 = cA + (size_t)(t + 1) * kstep;
;             const char* a2 = last ? nA : cA + (size_t)(t + 2) * kstep; const char* b2 = last ? nB : cB + (size_t)(t + 2) * kstep;
;             const char* a3 = a2 + kstep; const char* b3 = b2 + kstep;
;             PG8_LDB(B0, 0, 0); PG8_LDB(B1, 0, 1); PG8_SCHED; PG8_LDA(At, 0, 0); PG8_STAGE(PG8_SA(1, 1), a1 + hstepA, voffA);
;             PG8_WAIT_V(8); PG8_WAIT_L(0); PG8_BAR; PG8_MMA(0, 0, At, B0); PG8_MMA(0, 1, At, B1); PG8_BAR; PG8_SCHED;
;             PG8_LDA(At, 0, 1); PG8_STAGE(PG8_SB(0, 0), b2, voffB); PG8_STAGE(PG8_SB(0, 1), b2 + hstepB, voffB); PG8_STAGE(PG8_SA(0, 0), a2, voffA);
.LBB0_849:
	s_add_u32 s18, s6, 0xfffc0080
	s_addc_u32 s19, s7, -1
	s_add_i32 s39, 0, 0x10000
	s_cmp_eq_u32 s38, 12
	s_cselect_b32 s21, s1, s19
	s_cselect_b32 s20, s34, s18
	v_add_u32_e32 v152, s39, v144
	s_cselect_b32 s19, s11, s37
	s_cselect_b32 s18, s35, s36
	s_add_i32 s42, 0, 0x14000
	ds_read_b128 v[140:143], v152
	ds_read_b128 v[148:151], v152 offset:1024
	ds_read_b128 v[156:159], v152 offset:2048
	ds_read_b128 v[180:183], v152 offset:3072
	v_add_u32_e32 v152, s42, v144
	ds_read_b128 v[184:187], v152
	ds_read_b128 v[188:191], v152 offset:1024
	ds_read_b128 v[192:195], v152 offset:2048
	ds_read_b128 v[196:199], v152 offset:3072
	v_lshl_add_u64 v[152:153], s[6:7], 0, v[136:137]
	s_add_i32 m0, s23, 0xc000
	ds_read_b128 v[200:203], v146
	ds_read_b128 v[204:207], v146 offset:1024
	ds_read_b128 v[208:211], v146 offset:2048
	ds_read_b128 v[212:215], v146 offset:3072
	ds_read_b128 v[216:219], v146 offset:4096
	ds_read_b128 v[220:223], v146 offset:5120
	ds_read_b128 v[224:227], v146 offset:6144
	ds_read_b128 v[228:231], v146 offset:7168
	global_load_lds_dwordx4 v[152:153], off
	v_lshl_add_u64 v[152:153], s[6:7], 0, v[138:139]
	s_add_i32 m0, s23, 0xe000
	s_nop 0
	global_load_lds_dwordx4 v[152:153], off
	s_waitcnt vmcnt(8)
	s_waitcnt lgkmcnt(0)
	s_barrier
	s_waitcnt lgkmcnt(0)
	v_mfma_f32_16x16x32_bf16 v[126:129], v[140:143], v[200:203], v[126:129]
	v_mfma_f32_16x16x32_bf16 v[118:121], v[156:159], v[200:203], v[118:121]
	v_mfma_f32_16x16x32_bf16 v[110:113], v[140:143], v[208:211], v[110:113]
	v_mfma_f32_16x16x32_bf16 v[102:105], v[156:159], v[208:211], v[102:105]
	v_mfma_f32_16x16x32_bf16 v[94:97], v[140:143], v[216:219], v[94:97]
	v_mfma_f32_16x16x32_bf16 v[86:89], v[156:159], v[216:219], v[86:89]
	v_mfma_f32_16x16x32_bf16 v[78:81], v[140:143], v[224:227], v[78:81]
	v_mfma_f32_16x16x32_bf16 v[70:73], v[156:159], v[224:227], v[70:73]
	v_mfma_f32_16x16x32_bf16 v[126:129], v[148:151], v[204:207], v[126:129]
	v_mfma_f32_16x16x32_bf16 v[118:121], v[180:183], v[204:207], v[118:121]
	v_mfma_f32_16x16x32_bf16 v[110:113], v[148:151], v[212:215], v[110:113]
	v_mfma_f32_16x16x32_bf16 v[102:105], v[180:183], v[212:215], v[102:105]
	v_mfma_f32_16x16x32_bf16 v[94:97], v[148:151], v[220:223], v[94:97]
	v_mfma_f32_16x16x32_bf16 v[86:89], v[180:183], v[220:223], v[86:89]
	v_mfma_f32_16x16x32_bf16 v[78:81], v[148:151], v[228:231], v[78:81]
	v_mfma_f32_16x16x32_bf16 v[70:73], v[180:183], v[228:231], v[70:73]
	v_mfma_f32_16x16x32_bf16 v[122:125], v[184:187], v[200:203], v[122:125]
	v_mfma_f32_16x16x32_bf16 v[114:117], v[192:195], v[200:203], v[114:117]
	v_mfma_f32_16x16x32_bf16 v[106:109], v[184:187], v[208:211], v[106:109]
	v_mfma_f32_16x16x32_bf16 v[98:101], v[192:195], v[208:211], v[98:101]
	v_mfma_f32_16x16x32_bf16 v[90:93], v[184:187], v[216:219], v[90:93]
	v_mfma_f32_16x16x32_bf16 v[82:85], v[192:195], v[216:219], v[82:85]
	v_mfma_f32_16x16x32_bf16 v[74:77], v[184:187], v[224:227], v[74:77]
	v_mfma_f32_16x16x32_bf16 v[66:69], v[192:195], v[224:227], v[66:69]
	v_mfma_f32_16x16x32_bf16 v[122:125], v[188:191], v[204:207], v[122:125]
	v_mfma_f32_16x16x32_bf16 v[114:117], v[196:199], v[204:207], v[114:117]
	v_mfma_f32_16x16x32_bf16 v[106:109], v[188:191], v[212:215], v[106:109]
	v_mfma_f32_16x16x32_bf16 v[98:101], v[196:199], v[212:215], v[98:101]
	v_mfma_f32_16x16x32_bf16 v[90:93], v[188:191], v[220:223], v[90:93]
	v_mfma_f32_16x16x32_bf16 v[82:85], v[196:199], v[220:223], v[82:85]
	v_mfma_f32_16x16x32_bf16 v[74:77], v[188:191], v[228:231], v[74:77]
	v_mfma_f32_16x16x32_bf16 v[66:69], v[196:199], v[228:231], v[66:69]
	s_barrier
	s_add_i32 s39, s39, s22
	v_lshl_add_u64 v[152:153], s[18:19], 0, v[0:1]
	s_mov_b32 m0, s39
	ds_read_b128 v[200:203], v146 offset:16384
	ds_read_b128 v[204:207], v146 offset:17408
	ds_read_b128 v[208:211], v146 offset:18432
	ds_read_b128 v[212:215], v146 offset:19456
	ds_read_b128 v[216:219], v146 offset:20480
	ds_read_b128 v[220:223], v146 offset:21504
	ds_read_b128 v[224:227], v146 offset:22528
	ds_read_b128 v[228:231], v146 offset:23552
	global_load_lds_dwordx4 v[152:153], off
	s_add_i32 m0, s39, 0x2000
	s_add_u32 s40, s18, 0x40000
	v_lshl_add_u64 v[160:161], s[18:19], 0, v[130:131]
	s_addc_u32 s41, s19, 0
	s_add_i32 s39, s42, s22
	global_load_lds_dwordx4 v[160:161], off
	v_lshl_add_u64 v[162:163], s[40:41], 0, v[0:1]
	s_mov_b32 m0, s39
	v_lshl_add_u64 v[170:171], s[20:21], 0, v[132:133]
	global_load_lds_dwordx4 v[162:163], off
	v_lshl_add_u64 v[162:163], s[40:41], 0, v[130:131]
	s_add_i32 m0, s39, 0x2000
	s_nop 0
	global_load_lds_dwordx4 v[162:163], off
	v_lshl_add_u64 v[162:163], s[20:21], 0, v[134:135]
	s_mov_b32 m0, s23
	s_nop 0
	global_load_lds_dwordx4 v[162:163], off
	s_mov_b32 m0, s24
	s_nop 0
	global_load_lds_dwordx4 v[170:171], off
	s_waitcnt vmcnt(8)
	s_waitcnt lgkmcnt(0)
	s_barrier
; #define PG8_STAGE(bufoff, gbase, voff) do { _Pragma("unroll") for (int _i = 0; _i < 2; ++_i) \
;         __builtin_amdgcn_global_load_lds((const unsigned*)((const char*)(gbase) + (voff)[_i]), (LAS unsigned*)(lds + (bufoff) + ldsw + _i * 8192), 16, 0, 0); } while (0)
; #define PG8_LDA(dst, b, h) do { _Pragma("unroll") for (int m = 0; m < 4; ++m) _Pragma("unroll") for (int k = 0; k < 2; ++k) dst[m][k] = *(const LAS bf16x8*)(lds + PG8_SA(b, h) + aoff + m * 2048 + k * 1024); } while (0)
; #define PG8_LDB(dst, b, h) do { _Pragma("unroll") for (int n = 0; n < 2; ++n) _Pragma("unroll") for (int k = 0; k < 2; ++k) dst[n][k] = *(const LAS bf16x8*)(lds + PG8_SB(b, h) + boff + n * 2048 + k * 1024); } while (0)
; #define PG8_MMA(ai, bj, At, Bt) do { __builtin_amdgcn_s_setprio(1); _Pragma("unroll") for (int m = 0; m < 4; ++m) _Pragma("unroll") for (int n = 0; n < 2; ++n) _Pragma("unroll") for (int k = 0; k < 2; ++k) \
;         acc[ai][bj][m][n] = __builtin_amdgcn_mfma_f32_16x16x32_bf16(Bt[n][k], At[m][k], acc[ai][bj][m][n], 0, 0, 0); __builtin_amdgcn_s_setprio(0); } while (0)
; #define PG8_WAIT_V(n) asm volatile("s_waitcnt vmcnt(" #n ")" ::: "memory")
; #define PG8_WAIT_L(n) asm volatile("s_waitcnt lgkmcnt(" #n ")" ::: "memory")
; #define PG8_BAR __builtin_amdgcn_s_barrier()
; #define PG8_SCHED __builtin_amdgcn_sched_barrier(0)
; template <class Epi, bool ALIGN_EPI>
; __device__ __forceinline__ void gemm_phase(LAS unsigned char* lds, const Gemm g, const StaticOrder& S, const Epi& E) {
;     ...
;             PG8_WAIT_V(8); PG8_WAIT_L(0); PG8_BAR; PG8_MMA(1, 0, At, B0); PG8_MMA(1, 1, At, B1); PG8_BAR; PG8_SCHED;
;             PG8_LDB(B0, 1, 0); PG8_LDB(B1, 1, 1); PG8_SCHED; PG8_LDA(At, 1, 0); PG8_STAGE(PG8_SA(0, 1), a2 + hstepA, voffA);
;             PG8_WAIT_V(8); PG8_WAIT_L(0); PG8_BAR; PG8_MMA(0, 0, At, B0); PG8_MMA(0, 1, At, B1); PG8_BAR; PG8_SCHED;
	s_waitcnt lgkmcnt(0)
	v_mfma_f32_16x16x32_bf16 v[62:65], v[140:143], v[200:203], v[62:65]
	v_mfma_f32_16x16x32_bf16 v[54:57], v[156:159], v[200:203], v[54:57]
	v_mfma_f32_16x16x32_bf16 v[46:49], v[140:143], v[208:211], v[46:49]
	v_mfma_f32_16x16x32_bf16 v[38:41], v[156:159], v[208:211], v[38:41]
	v_mfma_f32_16x16x32_bf16 v[30:33], v[140:143], v[216:219], v[30:33]
	v_mfma_f32_16x16x32_bf16 v[22:25], v[156:159], v[216:219], v[22:25]
	v_mfma_f32_16x16x32_bf16 v[14:17], v[140:143], v[224:227], v[14:17]
	v_mfma_f32_16x16x32_bf16 v[6:9], v[156:159], v[224:227], v[6:9]
	v_mfma_f32_16x16x32_bf16 v[62:65], v[148:151], v[204:207], v[62:65]
	v_mfma_f32_16x16x32_bf16 v[54:57], v[180:183], v[204:207], v[54:57]
	v_mfma_f32_16x16x32_bf16 v[46:49], v[148:151], v[212:215], v[46:49]
	v_mfma_f32_16x16x32_bf16 v[38:41], v[180:183], v[212:215], v[38:41]
	v_mfma_f32_16x16x32_bf16 v[30:33], v[148:151], v[220:223], v[30:33]
	v_mfma_f32_16x16x32_bf16 v[22:25], v[180:183], v[220:223], v[22:25]
	v_mfma_f32_16x16x32_bf16 v[14:17], v[148:151], v[228:231], v[14:17]
	v_mfma_f32_16x16x32_bf16 v[6:9], v[180:183], v[228:231], v[6:9]
	v_mfma_f32_16x16x32_bf16 v[58:61], v[184:187], v[200:203], v[58:61]
	v_mfma_f32_16x16x32_bf16 v[50:53], v[192:195], v[200:203], v[50:53]
	v_mfma_f32_16x16x32_bf16 v[42:45], v[184:187], v[208:211], v[42:45]
	v_mfma_f32_16x16x32_bf16 v[34:37], v[192:195], v[208:211], v[34:37]
	v_mfma_f32_16x16x32_bf16 v[26:29], v[184:187], v[216:219], v[26:29]
	v_mfma_f32_16x16x32_bf16 v[18:21], v[192:195], v[216:219], v[18:21]
	v_mfma_f32_16x16x32_bf16 v[10:13], v[184:187], v[224:227], v[10:13]
	v_mfma_f32_16x16x32_bf16 v[2:5], v[192:195], v[224:227], v[2:5]
	v_mfma_f32_16x16x32_bf16 v[58:61], v[188:191], v[204:207], v[58:61]
	v_mfma_f32_16x16x32_bf16 v[50:53], v[196:199], v[204:207], v[50:53]
	v_mfma_f32_16x16x32_bf16 v[42:45], v[188:191], v[212:215], v[42:45]
	v_mfma_f32_16x16x32_bf16 v[34:37], v[196:199], v[212:215], v[34:37]
	v_mfma_f32_16x16x32_bf16 v[26:29], v[188:191], v[220:223], v[26:29]
	v_mfma_f32_16x16x32_bf16 v[18:21], v[196:199], v[220:223], v[18:21]
	v_mfma_f32_16x16x32_bf16 v[10:13], v[188:191], v[228:231], v[10:13]
	v_mfma_f32_16x16x32_bf16 v[2:5], v[196:199], v[228:231], v[2:5]
	s_barrier
	s_add_i32 s39, 0, 0x18000
	v_add_u32_e32 v164, s39, v144
	s_add_i32 s40, 0, 0x1c000
	ds_read_b128 v[140:143], v164
	ds_read_b128 v[148:151], v164 offset:1024
	ds_read_b128 v[156:159], v164 offset:2048
	ds_read_b128 v[180:183], v164 offset:3072
	v_add_u32_e32 v164, s40, v144
	ds_read_b128 v[184:187], v164
	ds_read_b128 v[188:191], v164 offset:1024
	ds_read_b128 v[192:195], v164 offset:2048
	ds_read_b128 v[196:199], v164 offset:3072
	s_add_u32 s20, s20, 0x40000
	s_addc_u32 s21, s21, 0
	s_mov_b32 m0, s25
	v_lshl_add_u64 v[172:173], s[20:21], 0, v[134:135]
	ds_read_b128 v[200:203], v146 offset:32768
	ds_read_b128 v[204:207], v146 offset:33792
	ds_read_b128 v[208:211], v146 offset:34816
	ds_read_b128 v[212:215], v146 offset:35840
	ds_read_b128 v[216:219], v146 offset:36864
	ds_read_b128 v[220:223], v146 offset:37888
	ds_read_b128 v[224:227], v146 offset:38912
	ds_read_b128 v[228:231], v146 offset:39936
	global_load_lds_dwordx4 v[172:173], off
	v_lshl_add_u64 v[172:173], s[20:21], 0, v[132:133]
	s_mov_b32 m0, s26
	s_nop 0
	global_load_lds_dwordx4 v[172:173], off
	s_waitcnt vmcnt(8)
	s_waitcnt lgkmcnt(0)
	s_barrier
	s_waitcnt lgkmcnt(0)
	v_mfma_f32_16x16x32_bf16 v[126:129], v[140:143], v[200:203], v[126:129]
	v_mfma_f32_16x16x32_bf16 v[118:121], v[156:159], v[200:203], v[118:121]
	v_mfma_f32_16x16x32_bf16 v[110:113], v[140:143], v[208:211], v[110:113]
	v_mfma_f32_16x16x32_bf16 v[102:105], v[156:159], v[208:211], v[102:105]
	v_mfma_f32_16x16x32_bf16 v[94:97], v[140:143], v[216:219], v[94:97]
	v_mfma_f32_16x16x32_bf16 v[86:89], v[156:159], v[216:219], v[86:89]
	v_mfma_f32_16x16x32_bf16 v[78:81], v[140:143], v[224:227], v[78:81]
	v_mfma_f32_16x16x32_bf16 v[70:73], v[156:159], v[224:227], v[70:73]
	v_mfma_f32_16x16x32_bf16 v[126:129], v[148:151], v[204:207], v[126:129]
	v_mfma_f32_16x16x32_bf16 v[118:121], v[180:183], v[204:207], v[118:121]
	v_mfma_f32_16x16x32_bf16 v[110:113], v[148:151], v[212:215], v[110:113]
	v_mfma_f32_16x16x32_bf16 v[102:105], v[180:183], v[212:215], v[102:105]
	v_mfma_f32_16x16x32_bf16 v[94:97], v[148:151], v[220:223], v[94:97]
	v_mfma_f32_16x16x32_bf16 v[86:89], v[180:183], v[220:223], v[86:89]
	v_mfma_f32_16x16x32_bf16 v[78:81], v[148:151], v[228:231], v[78:81]
	v_mfma_f32_16x16x32_bf16 v[70:73], v[180:183], v[228:231], v[70:73]
	v_mfma_f32_16x16x32_bf16 v[122:125], v[184:187], v[200:203], v[122:125]
	v_mfma_f32_16x16x32_bf16 v[114:117], v[192:195], v[200:203], v[114:117]
	v_mfma_f32_16x16x32_bf16 v[106:109], v[184:187], v[208:211], v[106:109]
	v_mfma_f32_16x16x32_bf16 v[98:101], v[192:195], v[208:211], v[98:101]
	v_mfma_f32_16x16x32_bf16 v[90:93], v[184:187], v[216:219], v[90:93]
	v_mfma_f32_16x16x32_bf16 v[82:85], v[192:195], v[216:219], v[82:85]
	v_mfma_f32_16x16x32_bf16 v[74:77], v[184:187], v[224:227], v[74:77]
	v_mfma_f32_16x16x32_bf16 v[66:69], v[192:195], v[224:227], v[66:69]
	v_mfma_f32_16x16x32_bf16 v[122:125], v[188:191], v[204:207], v[122:125]
	v_mfma_f32_16x16x32_bf16 v[114:117], v[196:199], v[204:207], v[114:117]
	v_mfma_f32_16x16x32_bf16 v[106:109], v[188:191], v[212:215], v[106:109]
	v_mfma_f32_16x16x32_bf16 v[98:101], v[196:199], v[212:215], v[98:101]
	v_mfma_f32_16x16x32_bf16 v[90:93], v[188:191], v[220:223], v[90:93]
	v_mfma_f32_16x16x32_bf16 v[82:85], v[196:199], v[220:223], v[82:85]
	v_mfma_f32_16x16x32_bf16 v[74:77], v[188:191], v[228:231], v[74:77]
	v_mfma_f32_16x16x32_bf16 v[66:69], v[196:199], v[228:231], v[66:69]
	s_barrier
; #define PG8_STAGE(bufoff, gbase, voff) do { _Pragma("unroll") for (int _i = 0; _i < 2; ++_i) \
;         __builtin_amdgcn_global_load_lds((const unsigned*)((const char*)(gbase) + (voff)[_i]), (LAS unsigned*)(lds + (bufoff) + ldsw + _i * 8192), 16, 0, 0); } while (0)
; #define PG8_LDA(dst, b, h) do { _Pragma("unroll") for (int m = 0; m < 4; ++m) _Pragma("unroll") for (int k = 0; k < 2; ++k) dst[m][k] = *(const LAS bf16x8*)(lds + PG8_SA(b, h) + aoff + m * 2048 + k * 1024); } while (0)
; #define PG8_MMA(ai, bj, At, Bt) do { __builtin_amdgcn_s_setprio(1); _Pragma("unroll") for (int m = 0; m < 4; ++m) _Pragma("unroll") for (int n = 0; n < 2; ++n) _Pragma("unroll") for (int k = 0; k < 2; ++k) \
;         acc[ai][bj][m][n] = __builtin_amdgcn_mfma_f32_16x16x32_bf16(Bt[n][k], At[m][k], acc[ai][bj][m][n], 0, 0, 0); __builtin_amdgcn_s_setprio(0); } while (0)
; #define PG8_WAIT_V(n) asm volatile("s_waitcnt vmcnt(" #n ")" ::: "memory")
; #define PG8_WAIT_L(n) asm volatile("s_waitcnt lgkmcnt(" #n ")" ::: "memory")
; #define PG8_BAR __builtin_amdgcn_s_barrier()
; #define PG8_SCHED __builtin_amdgcn_sched_barrier(0)
; template <class Epi, bool ALIGN_EPI>
; __device__ __forceinline__ void gemm_phase(LAS unsigned char* lds, const Gemm g, const StaticOrder& S, const Epi& E) {
;     ...
;             PG8_LDA(At, 1, 1); PG8_STAGE(PG8_SB(1, 0), b3, voffB); PG8_STAGE(PG8_SB(1, 1), b3 + hstepB, voffB); PG8_STAGE(PG8_SA(1, 0), a3, voffA);
;             PG8_WAIT_V(8); PG8_WAIT_L(0); PG8_BAR; PG8_MMA(1, 0, At, B0); PG8_MMA(1, 1, At, B1); PG8_BAR; PG8_SCHED;
;         }
;         if constexpr (ALIGN_EPI) { if (wr == 0) PG8_BAR; }
	s_add_i32 s20, s39, s22
	v_lshl_add_u64 v[152:153], v[152:153], 0, s[94:95]
	s_mov_b32 m0, s20
	ds_read_b128 v[200:203], v146 offset:49152
	ds_read_b128 v[204:207], v146 offset:50176
	ds_read_b128 v[208:211], v146 offset:51200
	ds_read_b128 v[212:215], v146 offset:52224
	ds_read_b128 v[216:219], v146 offset:53248
	ds_read_b128 v[220:223], v146 offset:54272
	ds_read_b128 v[224:227], v146 offset:55296
	ds_read_b128 v[228:231], v146 offset:56320
	global_load_lds_dwordx4 v[152:153], off
	s_add_i32 m0, s20, 0x2000
	s_add_u32 s18, s18, 0x40080
	v_lshl_add_u64 v[152:153], v[160:161], 0, s[94:95]
	s_addc_u32 s19, s19, 0
	s_add_i32 s20, s40, s22
	global_load_lds_dwordx4 v[152:153], off
	v_lshl_add_u64 v[152:153], s[18:19], 0, v[0:1]
	s_mov_b32 m0, s20
	s_nop 0
	global_load_lds_dwordx4 v[152:153], off
	v_lshl_add_u64 v[152:153], s[18:19], 0, v[130:131]
	s_add_i32 m0, s20, 0x2000
	s_nop 0
	global_load_lds_dwordx4 v[152:153], off
	v_lshl_add_u64 v[152:153], v[162:163], 0, s[94:95]
	s_mov_b32 m0, s27
	s_nop 0
	global_load_lds_dwordx4 v[152:153], off
	v_lshl_add_u64 v[152:153], v[170:171], 0, s[94:95]
	s_mov_b32 m0, s28
	s_nop 0
	global_load_lds_dwordx4 v[152:153], off
	s_waitcnt vmcnt(8)
	s_waitcnt lgkmcnt(0)
	s_barrier
	s_waitcnt lgkmcnt(0)
	v_mfma_f32_16x16x32_bf16 v[62:65], v[140:143], v[200:203], v[62:65]
	v_mfma_f32_16x16x32_bf16 v[54:57], v[156:159], v[200:203], v[54:57]
	v_mfma_f32_16x16x32_bf16 v[46:49], v[140:143], v[208:211], v[46:49]
	v_mfma_f32_16x16x32_bf16 v[38:41], v[156:159], v[208:211], v[38:41]
	v_mfma_f32_16x16x32_bf16 v[30:33], v[140:143], v[216:219], v[30:33]
	v_mfma_f32_16x16x32_bf16 v[22:25], v[156:159], v[216:219], v[22:25]
	v_mfma_f32_16x16x32_bf16 v[14:17], v[140:143], v[224:227], v[14:17]
	v_mfma_f32_16x16x32_bf16 v[6:9], v[156:159], v[224:227], v[6:9]
	v_mfma_f32_16x16x32_bf16 v[62:65], v[148:151], v[204:207], v[62:65]
	v_mfma_f32_16x16x32_bf16 v[54:57], v[180:183], v[204:207], v[54:57]
	v_mfma_f32_16x16x32_bf16 v[46:49], v[148:151], v[212:215], v[46:49]
	v_mfma_f32_16x16x32_bf16 v[38:41], v[180:183], v[212:215], v[38:41]
	v_mfma_f32_16x16x32_bf16 v[30:33], v[148:151], v[220:223], v[30:33]
	v_mfma_f32_16x16x32_bf16 v[22:25], v[180:183], v[220:223], v[22:25]
	v_mfma_f32_16x16x32_bf16 v[14:17], v[148:151], v[228:231], v[14:17]
	v_mfma_f32_16x16x32_bf16 v[6:9], v[180:183], v[228:231], v[6:9]
	v_mfma_f32_16x16x32_bf16 v[58:61], v[184:187], v[200:203], v[58:61]
	v_mfma_f32_16x16x32_bf16 v[50:53], v[192:195], v[200:203], v[50:53]
	v_mfma_f32_16x16x32_bf16 v[42:45], v[184:187], v[208:211], v[42:45]
	v_mfma_f32_16x16x32_bf16 v[34:37], v[192:195], v[208:211], v[34:37]
	v_mfma_f32_16x16x32_bf16 v[26:29], v[184:187], v[216:219], v[26:29]
	v_mfma_f32_16x16x32_bf16 v[18:21], v[192:195], v[216:219], v[18:21]
	v_mfma_f32_16x16x32_bf16 v[10:13], v[184:187], v[224:227], v[10:13]
	v_mfma_f32_16x16x32_bf16 v[2:5], v[192:195], v[224:227], v[2:5]
	v_mfma_f32_16x16x32_bf16 v[58:61], v[188:191], v[204:207], v[58:61]
	v_mfma_f32_16x16x32_bf16 v[50:53], v[196:199], v[204:207], v[50:53]
	v_mfma_f32_16x16x32_bf16 v[42:45], v[188:191], v[212:215], v[42:45]
	v_mfma_f32_16x16x32_bf16 v[34:37], v[196:199], v[212:215], v[34:37]
	v_mfma_f32_16x16x32_bf16 v[26:29], v[188:191], v[220:223], v[26:29]
	v_mfma_f32_16x16x32_bf16 v[18:21], v[196:199], v[220:223], v[18:21]
	v_mfma_f32_16x16x32_bf16 v[10:13], v[188:191], v[228:231], v[10:13]
	v_mfma_f32_16x16x32_bf16 v[2:5], v[196:199], v[228:231], v[2:5]
	s_barrier
	s_add_i32 s38, s38, 2
	s_add_u32 s6, s6, 0x100
	s_addc_u32 s7, s7, 0
	s_add_u32 s36, s36, 0x100
	s_addc_u32 s37, s37, 0
	s_cmp_gt_u32 s38, 13
	s_cbranch_scc0 .LBB0_849
	s_and_b64 vcc, exec, s[8:9]
	s_cbranch_vccz .LBB0_852
	s_barrier
